# removed the per-phase s_setprio 1/0 flips inside all GEMM K-loops (on top of peeled C=0 first iteration and LDS-staged row statistics in P7)
# speedup vs baseline: 1.0090x; 1.0083x over previous
;     DI bool next(int i, Unit& u) const { if (!s.next(i >> 1, u)) return false; u.sel = i & 1; return true; }
; template <class Epi, class Sched, bool ALIGN_EPI, bool CONVA>
; DI void gemm_phase(LAS unsigned char* lds, const Gemm g, const Sched& S, const Epi& E) {
;     ...
;         const bool has_next = S.next(ui + 1, nxt);
;         const char* nA = has_next ? (const char*)(nxt.sel ? g.A2 : g.A) + (size_t)nxt.pm * tstepA + abias : cA;
;         const char* nB = has_next ? (const char*)(nxt.sel ? g.Bt2 : g.Bt) + (size_t)nxt.pn * tstepB : cB;
.LBB0_161:
	s_ashr_i32 s41, s40, 31
	s_lshl_b64 s[42:43], s[40:41], 19
	s_add_u32 s42, s28, s42
	s_addc_u32 s43, s29, s43
	s_and_b64 s[44:45], s[0:1], exec
	s_cselect_b32 s41, s43, s47
	s_cselect_b32 s70, s42, s46
	s_ashr_i32 s31, s30, 31
	s_lshl_b64 s[44:45], s[30:31], 19
	s_add_u32 s44, s14, s44
	s_addc_u32 s45, s15, s45
	s_and_b64 s[54:55], s[0:1], exec
	s_cselect_b32 s31, s45, s53
	s_cselect_b32 s71, s44, s52
	s_add_u32 s46, s46, 0x40080
	s_addc_u32 s47, s47, 0
	s_add_u32 s77, s52, 0x100
	s_addc_u32 s78, s53, 0
	s_mov_b32 s79, -2
	ds_read_b128 v[154:157], v149
	ds_read_b128 v[158:161], v149 offset:1024
	ds_read_b128 v[162:165], v149 offset:2048
	ds_read_b128 v[166:169], v149 offset:3072
	ds_read_b128 v[170:173], v150
	ds_read_b128 v[178:181], v150 offset:1024
	ds_read_b128 v[182:185], v150 offset:2048
	ds_read_b128 v[186:189], v150 offset:3072
	s_add_u32 s52, s46, 0xfffc0080
	s_addc_u32 s53, s47, -1
	s_cmp_eq_u32 s79, 12
	s_cselect_b32 s55, s41, s53
	s_cselect_b32 s54, s70, s52
	s_cselect_b32 s53, s31, s78
	s_cselect_b32 s52, s71, s77
	v_lshl_add_u64 v[174:175], s[46:47], 0, v[138:139]
	s_add_i32 m0, s35, 0xc000
	ds_read_b128 v[190:193], v151
	ds_read_b128 v[194:197], v151 offset:1024
	ds_read_b128 v[198:201], v151 offset:2048
	ds_read_b128 v[202:205], v151 offset:3072
	ds_read_b128 v[206:209], v151 offset:4096
	ds_read_b128 v[214:217], v151 offset:5120
	ds_read_b128 v[218:221], v151 offset:6144
	ds_read_b128 v[222:225], v151 offset:7168
	global_load_lds_dwordx4 v[174:175], off
	v_lshl_add_u64 v[174:175], s[46:47], 0, v[140:141]
	s_add_i32 m0, s35, 0xe000
	s_nop 0
	global_load_lds_dwordx4 v[174:175], off
	s_waitcnt vmcnt(8)
	s_waitcnt lgkmcnt(0)
	s_barrier
	s_waitcnt lgkmcnt(0)
	v_mfma_f32_16x16x32_bf16 v[124:127], v[154:157], v[190:193], 0
	v_mfma_f32_16x16x32_bf16 v[120:123], v[162:165], v[190:193], 0
	v_mfma_f32_16x16x32_bf16 v[116:119], v[154:157], v[198:201], 0
	v_mfma_f32_16x16x32_bf16 v[112:115], v[162:165], v[198:201], 0
	v_mfma_f32_16x16x32_bf16 v[100:103], v[154:157], v[206:209], 0
	v_mfma_f32_16x16x32_bf16 v[96:99], v[162:165], v[206:209], 0
	v_mfma_f32_16x16x32_bf16 v[84:87], v[154:157], v[218:221], 0
	v_mfma_f32_16x16x32_bf16 v[80:83], v[162:165], v[218:221], 0
	v_mfma_f32_16x16x32_bf16 v[124:127], v[158:161], v[194:197], v[124:127]
	v_mfma_f32_16x16x32_bf16 v[120:123], v[166:169], v[194:197], v[120:123]
	v_mfma_f32_16x16x32_bf16 v[116:119], v[158:161], v[202:205], v[116:119]
	v_mfma_f32_16x16x32_bf16 v[112:115], v[166:169], v[202:205], v[112:115]
	v_mfma_f32_16x16x32_bf16 v[100:103], v[158:161], v[214:217], v[100:103]
	v_mfma_f32_16x16x32_bf16 v[96:99], v[166:169], v[214:217], v[96:99]
	v_mfma_f32_16x16x32_bf16 v[84:87], v[158:161], v[222:225], v[84:87]
	v_mfma_f32_16x16x32_bf16 v[80:83], v[166:169], v[222:225], v[80:83]
	v_mfma_f32_16x16x32_bf16 v[108:111], v[170:173], v[190:193], 0
	v_mfma_f32_16x16x32_bf16 v[104:107], v[182:185], v[190:193], 0
	v_mfma_f32_16x16x32_bf16 v[92:95], v[170:173], v[198:201], 0
	v_mfma_f32_16x16x32_bf16 v[88:91], v[182:185], v[198:201], 0
	v_mfma_f32_16x16x32_bf16 v[76:79], v[170:173], v[206:209], 0
	v_mfma_f32_16x16x32_bf16 v[72:75], v[182:185], v[206:209], 0
	v_mfma_f32_16x16x32_bf16 v[68:71], v[170:173], v[218:221], 0
	v_mfma_f32_16x16x32_bf16 v[64:67], v[182:185], v[218:221], 0
	v_mfma_f32_16x16x32_bf16 v[108:111], v[178:181], v[194:197], v[108:111]
	v_mfma_f32_16x16x32_bf16 v[104:107], v[186:189], v[194:197], v[104:107]
	v_mfma_f32_16x16x32_bf16 v[92:95], v[178:181], v[202:205], v[92:95]
	v_mfma_f32_16x16x32_bf16 v[88:91], v[186:189], v[202:205], v[88:91]
	v_mfma_f32_16x16x32_bf16 v[76:79], v[178:181], v[214:217], v[76:79]
	v_mfma_f32_16x16x32_bf16 v[72:75], v[186:189], v[214:217], v[72:75]
	v_mfma_f32_16x16x32_bf16 v[68:71], v[178:181], v[222:225], v[68:71]
	v_mfma_f32_16x16x32_bf16 v[64:67], v[186:189], v[222:225], v[64:67]
	s_barrier
	s_add_i32 s80, s67, s33
	v_lshl_add_u64 v[174:175], s[52:53], 0, v[132:133]
	s_mov_b32 m0, s80
	ds_read_b128 v[190:193], v151 offset:16384
	ds_read_b128 v[194:197], v151 offset:17408
	ds_read_b128 v[198:201], v151 offset:18432
	ds_read_b128 v[202:205], v151 offset:19456
	ds_read_b128 v[206:209], v151 offset:20480
	ds_read_b128 v[214:217], v151 offset:21504
	ds_read_b128 v[218:221], v151 offset:22528
	ds_read_b128 v[222:225], v151 offset:23552
	global_load_lds_dwordx4 v[174:175], off
	s_add_i32 m0, s80, 0x2000
	s_add_u32 s80, s52, 0x40000
	v_lshl_add_u64 v[210:211], s[52:53], 0, v[128:129]
	s_addc_u32 s81, s53, 0
	s_add_i32 s83, s68, s33
	global_load_lds_dwordx4 v[210:211], off
	v_lshl_add_u64 v[226:227], s[80:81], 0, v[132:133]
	s_mov_b32 m0, s83
	v_lshl_add_u64 v[228:229], s[54:55], 0, v[130:131]
	global_load_lds_dwordx4 v[226:227], off
	v_lshl_add_u64 v[226:227], s[80:81], 0, v[128:129]
	s_add_i32 m0, s83, 0x2000
	s_nop 0
	global_load_lds_dwordx4 v[226:227], off
	v_lshl_add_u64 v[226:227], s[54:55], 0, v[134:135]
	s_mov_b32 m0, s35
	s_nop 0
	global_load_lds_dwordx4 v[226:227], off
	s_mov_b32 m0, s58
	s_nop 0
	global_load_lds_dwordx4 v[228:229], off
	s_waitcnt vmcnt(8)
	s_waitcnt lgkmcnt(0)
	s_barrier
	s_waitcnt lgkmcnt(0)
	v_mfma_f32_16x16x32_bf16 v[60:63], v[154:157], v[190:193], 0
	v_mfma_f32_16x16x32_bf16 v[56:59], v[162:165], v[190:193], 0
	v_mfma_f32_16x16x32_bf16 v[52:55], v[154:157], v[198:201], 0
	v_mfma_f32_16x16x32_bf16 v[48:51], v[162:165], v[198:201], 0
	v_mfma_f32_16x16x32_bf16 v[36:39], v[154:157], v[206:209], 0
	v_mfma_f32_16x16x32_bf16 v[32:35], v[162:165], v[206:209], 0
	v_mfma_f32_16x16x32_bf16 v[20:23], v[154:157], v[218:221], 0
	v_mfma_f32_16x16x32_bf16 v[16:19], v[162:165], v[218:221], 0
	v_mfma_f32_16x16x32_bf16 v[60:63], v[158:161], v[194:197], v[60:63]
	v_mfma_f32_16x16x32_bf16 v[56:59], v[166:169], v[194:197], v[56:59]
	v_mfma_f32_16x16x32_bf16 v[52:55], v[158:161], v[202:205], v[52:55]
	v_mfma_f32_16x16x32_bf16 v[48:51], v[166:169], v[202:205], v[48:51]
	v_mfma_f32_16x16x32_bf16 v[36:39], v[158:161], v[214:217], v[36:39]
	v_mfma_f32_16x16x32_bf16 v[32:35], v[166:169], v[214:217], v[32:35]
	v_mfma_f32_16x16x32_bf16 v[20:23], v[158:161], v[222:225], v[20:23]
	v_mfma_f32_16x16x32_bf16 v[16:19], v[166:169], v[222:225], v[16:19]
	v_mfma_f32_16x16x32_bf16 v[44:47], v[170:173], v[190:193], 0
	v_mfma_f32_16x16x32_bf16 v[40:43], v[182:185], v[190:193], 0
	v_mfma_f32_16x16x32_bf16 v[28:31], v[170:173], v[198:201], 0
	v_mfma_f32_16x16x32_bf16 v[24:27], v[182:185], v[198:201], 0
	v_mfma_f32_16x16x32_bf16 v[12:15], v[170:173], v[206:209], 0
	v_mfma_f32_16x16x32_bf16 v[8:11], v[182:185], v[206:209], 0
	v_mfma_f32_16x16x32_bf16 v[4:7], v[170:173], v[218:221], 0
	v_mfma_f32_16x16x32_bf16 v[0:3], v[182:185], v[218:221], 0
	v_mfma_f32_16x16x32_bf16 v[44:47], v[178:181], v[194:197], v[44:47]
	v_mfma_f32_16x16x32_bf16 v[40:43], v[186:189], v[194:197], v[40:43]
	v_mfma_f32_16x16x32_bf16 v[28:31], v[178:181], v[202:205], v[28:31]
	v_mfma_f32_16x16x32_bf16 v[24:27], v[186:189], v[202:205], v[24:27]
	v_mfma_f32_16x16x32_bf16 v[12:15], v[178:181], v[214:217], v[12:15]
	v_mfma_f32_16x16x32_bf16 v[8:11], v[186:189], v[214:217], v[8:11]
	v_mfma_f32_16x16x32_bf16 v[4:7], v[178:181], v[222:225], v[4:7]
	v_mfma_f32_16x16x32_bf16 v[0:3], v[186:189], v[222:225], v[0:3]
	s_barrier
	s_add_i32 s80, 0, 0x18000
	v_add_u32_e32 v136, s80, v147
	s_add_i32 s81, 0, 0x1c000
	ds_read_b128 v[154:157], v136
	ds_read_b128 v[158:161], v136 offset:1024
	ds_read_b128 v[162:165], v136 offset:2048
	ds_read_b128 v[166:169], v136 offset:3072
	v_add_u32_e32 v136, s81, v147
	ds_read_b128 v[170:173], v136
	ds_read_b128 v[178:181], v136 offset:1024
	ds_read_b128 v[182:185], v136 offset:2048
	ds_read_b128 v[186:189], v136 offset:3072
	s_add_u32 s54, s54, 0x40000
	s_addc_u32 s55, s55, 0
	s_mov_b32 m0, s59
	v_lshl_add_u64 v[230:231], s[54:55], 0, v[134:135]
	ds_read_b128 v[190:193], v151 offset:32768
	ds_read_b128 v[194:197], v151 offset:33792
	ds_read_b128 v[198:201], v151 offset:34816
	ds_read_b128 v[202:205], v151 offset:35840
	ds_read_b128 v[206:209], v151 offset:36864
	ds_read_b128 v[214:217], v151 offset:37888
	ds_read_b128 v[218:221], v151 offset:38912
	ds_read_b128 v[222:225], v151 offset:39936
	global_load_lds_dwordx4 v[230:231], off
	v_lshl_add_u64 v[230:231], s[54:55], 0, v[130:131]
	s_mov_b32 m0, s60
	s_nop 0
	global_load_lds_dwordx4 v[230:231], off
	s_waitcnt vmcnt(8)
	s_waitcnt lgkmcnt(0)
	s_barrier
	s_waitcnt lgkmcnt(0)
	v_mfma_f32_16x16x32_bf16 v[124:127], v[154:157], v[190:193], v[124:127]
	v_mfma_f32_16x16x32_bf16 v[120:123], v[162:165], v[190:193], v[120:123]
	v_mfma_f32_16x16x32_bf16 v[116:119], v[154:157], v[198:201], v[116:119]
	v_mfma_f32_16x16x32_bf16 v[112:115], v[162:165], v[198:201], v[112:115]
	v_mfma_f32_16x16x32_bf16 v[100:103], v[154:157], v[206:209], v[100:103]
	v_mfma_f32_16x16x32_bf16 v[96:99], v[162:165], v[206:209], v[96:99]
	v_mfma_f32_16x16x32_bf16 v[84:87], v[154:157], v[218:221], v[84:87]
	v_mfma_f32_16x16x32_bf16 v[80:83], v[162:165], v[218:221], v[80:83]
	v_mfma_f32_16x16x32_bf16 v[124:127], v[158:161], v[194:197], v[124:127]
	v_mfma_f32_16x16x32_bf16 v[120:123], v[166:169], v[194:197], v[120:123]
	v_mfma_f32_16x16x32_bf16 v[116:119], v[158:161], v[202:205], v[116:119]
	v_mfma_f32_16x16x32_bf16 v[112:115], v[166:169], v[202:205], v[112:115]
	v_mfma_f32_16x16x32_bf16 v[100:103], v[158:161], v[214:217], v[100:103]
	v_mfma_f32_16x16x32_bf16 v[96:99], v[166:169], v[214:217], v[96:99]
	v_mfma_f32_16x16x32_bf16 v[84:87], v[158:161], v[222:225], v[84:87]
	v_mfma_f32_16x16x32_bf16 v[80:83], v[166:169], v[222:225], v[80:83]
	v_mfma_f32_16x16x32_bf16 v[108:111], v[170:173], v[190:193], v[108:111]
	v_mfma_f32_16x16x32_bf16 v[104:107], v[182:185], v[190:193], v[104:107]
	v_mfma_f32_16x16x32_bf16 v[92:95], v[170:173], v[198:201], v[92:95]
	v_mfma_f32_16x16x32_bf16 v[88:91], v[182:185], v[198:201], v[88:91]
	v_mfma_f32_16x16x32_bf16 v[76:79], v[170:173], v[206:209], v[76:79]
	v_mfma_f32_16x16x32_bf16 v[72:75], v[182:185], v[206:209], v[72:75]
	v_mfma_f32_16x16x32_bf16 v[68:71], v[170:173], v[218:221], v[68:71]
	v_mfma_f32_16x16x32_bf16 v[64:67], v[182:185], v[218:221], v[64:67]
	v_mfma_f32_16x16x32_bf16 v[108:111], v[178:181], v[194:197], v[108:111]
	v_mfma_f32_16x16x32_bf16 v[104:107], v[186:189], v[194:197], v[104:107]
	v_mfma_f32_16x16x32_bf16 v[92:95], v[178:181], v[202:205], v[92:95]
	v_mfma_f32_16x16x32_bf16 v[88:91], v[186:189], v[202:205], v[88:91]
	v_mfma_f32_16x16x32_bf16 v[76:79], v[178:181], v[214:217], v[76:79]
	v_mfma_f32_16x16x32_bf16 v[72:75], v[186:189], v[214:217], v[72:75]
	v_mfma_f32_16x16x32_bf16 v[68:71], v[178:181], v[222:225], v[68:71]
	v_mfma_f32_16x16x32_bf16 v[64:67], v[186:189], v[222:225], v[64:67]
	s_barrier
; #define PG8_WAIT_V(n) asm volatile("s_waitcnt vmcnt(" #n ")" ::: "memory")
; template <class Epi, class Sched, bool ALIGN_EPI, bool CONVA>
; DI void gemm_phase(LAS unsigned char* lds, const Gemm g, const Sched& S, const Epi& E) {
;     ...
;         for (int t = 0; t < nt; t += 2) {
;             const bool last = (t == nt - 2);
;             const char* a1 = cA + (size_t)(t + 1) * kstep;
;             const char* a2 = last ? nA : cA + (size_t)(t + 2) * kstep; const char* b2 = last ? nB : cB + (size_t)(t + 2) * kstep;
;             const char* a3 = a2 + kstep; const char* b3 = b2 + kstep;
;             PG8_KBODY(PG8_WAIT_V(8));
	s_add_i32 s54, s80, s33
	v_lshl_add_u64 v[174:175], v[174:175], 0, s[6:7]
	s_mov_b32 m0, s54
	ds_read_b128 v[190:193], v151 offset:49152
	ds_read_b128 v[194:197], v151 offset:50176
	ds_read_b128 v[198:201], v151 offset:51200
	ds_read_b128 v[202:205], v151 offset:52224
	ds_read_b128 v[206:209], v151 offset:53248
	ds_read_b128 v[214:217], v151 offset:54272
	ds_read_b128 v[218:221], v151 offset:55296
	ds_read_b128 v[222:225], v151 offset:56320
	global_load_lds_dwordx4 v[174:175], off
	s_add_i32 m0, s54, 0x2000
	s_add_u32 s52, s52, 0x40080
	v_lshl_add_u64 v[174:175], v[210:211], 0, s[6:7]
	s_addc_u32 s53, s53, 0
	s_add_i32 s54, s81, s33
	global_load_lds_dwordx4 v[174:175], off
	v_lshl_add_u64 v[174:175], s[52:53], 0, v[132:133]
	s_mov_b32 m0, s54
	s_nop 0
	global_load_lds_dwordx4 v[174:175], off
	v_lshl_add_u64 v[174:175], s[52:53], 0, v[128:129]
	s_add_i32 m0, s54, 0x2000
	s_nop 0
	global_load_lds_dwordx4 v[174:175], off
	v_lshl_add_u64 v[174:175], v[226:227], 0, s[6:7]
	s_mov_b32 m0, s62
	s_nop 0
	global_load_lds_dwordx4 v[174:175], off
	v_lshl_add_u64 v[174:175], v[228:229], 0, s[6:7]
	s_mov_b32 m0, s63
	s_nop 0
	global_load_lds_dwordx4 v[174:175], off
	s_waitcnt vmcnt(8)
	s_waitcnt lgkmcnt(0)
	s_barrier
	s_waitcnt lgkmcnt(0)
	v_mfma_f32_16x16x32_bf16 v[60:63], v[154:157], v[190:193], v[60:63]
	v_mfma_f32_16x16x32_bf16 v[56:59], v[162:165], v[190:193], v[56:59]
	v_mfma_f32_16x16x32_bf16 v[52:55], v[154:157], v[198:201], v[52:55]
	v_mfma_f32_16x16x32_bf16 v[48:51], v[162:165], v[198:201], v[48:51]
	v_mfma_f32_16x16x32_bf16 v[36:39], v[154:157], v[206:209], v[36:39]
	v_mfma_f32_16x16x32_bf16 v[32:35], v[162:165], v[206:209], v[32:35]
	v_mfma_f32_16x16x32_bf16 v[20:23], v[154:157], v[218:221], v[20:23]
	v_mfma_f32_16x16x32_bf16 v[16:19], v[162:165], v[218:221], v[16:19]
	v_mfma_f32_16x16x32_bf16 v[60:63], v[158:161], v[194:197], v[60:63]
	v_mfma_f32_16x16x32_bf16 v[56:59], v[166:169], v[194:197], v[56:59]
	v_mfma_f32_16x16x32_bf16 v[52:55], v[158:161], v[202:205], v[52:55]
	v_mfma_f32_16x16x32_bf16 v[48:51], v[166:169], v[202:205], v[48:51]
	v_mfma_f32_16x16x32_bf16 v[36:39], v[158:161], v[214:217], v[36:39]
	v_mfma_f32_16x16x32_bf16 v[32:35], v[166:169], v[214:217], v[32:35]
	v_mfma_f32_16x16x32_bf16 v[20:23], v[158:161], v[222:225], v[20:23]
	v_mfma_f32_16x16x32_bf16 v[16:19], v[166:169], v[222:225], v[16:19]
	v_mfma_f32_16x16x32_bf16 v[44:47], v[170:173], v[190:193], v[44:47]
	v_mfma_f32_16x16x32_bf16 v[40:43], v[182:185], v[190:193], v[40:43]
	v_mfma_f32_16x16x32_bf16 v[28:31], v[170:173], v[198:201], v[28:31]
	v_mfma_f32_16x16x32_bf16 v[24:27], v[182:185], v[198:201], v[24:27]
	v_mfma_f32_16x16x32_bf16 v[12:15], v[170:173], v[206:209], v[12:15]
	v_mfma_f32_16x16x32_bf16 v[8:11], v[182:185], v[206:209], v[8:11]
	v_mfma_f32_16x16x32_bf16 v[4:7], v[170:173], v[218:221], v[4:7]
	v_mfma_f32_16x16x32_bf16 v[0:3], v[182:185], v[218:221], v[0:3]
	v_mfma_f32_16x16x32_bf16 v[44:47], v[178:181], v[194:197], v[44:47]
	v_mfma_f32_16x16x32_bf16 v[40:43], v[186:189], v[194:197], v[40:43]
	v_mfma_f32_16x16x32_bf16 v[28:31], v[178:181], v[202:205], v[28:31]
	v_mfma_f32_16x16x32_bf16 v[24:27], v[186:189], v[202:205], v[24:27]
	v_mfma_f32_16x16x32_bf16 v[12:15], v[178:181], v[214:217], v[12:15]
	v_mfma_f32_16x16x32_bf16 v[8:11], v[186:189], v[214:217], v[8:11]
	v_mfma_f32_16x16x32_bf16 v[4:7], v[178:181], v[222:225], v[4:7]
	v_mfma_f32_16x16x32_bf16 v[0:3], v[186:189], v[222:225], v[0:3]
	s_barrier
	s_add_i32 s79, s79, 2
	s_add_u32 s46, s46, 0x100
	s_addc_u32 s47, s47, 0
	s_add_u32 s77, s77, 0x100
	s_addc_u32 s78, s78, 0
	s_cmp_gt_u32 s79, 13
.LBB0_162:
	ds_read_b128 v[154:157], v149
	ds_read_b128 v[158:161], v149 offset:1024
	ds_read_b128 v[162:165], v149 offset:2048
	ds_read_b128 v[166:169], v149 offset:3072
	ds_read_b128 v[170:173], v150
	ds_read_b128 v[178:181], v150 offset:1024
	ds_read_b128 v[182:185], v150 offset:2048
	ds_read_b128 v[186:189], v150 offset:3072
	s_add_u32 s52, s46, 0xfffc0080
	s_addc_u32 s53, s47, -1
	s_cmp_eq_u32 s79, 12
	s_cselect_b32 s55, s41, s53
	s_cselect_b32 s54, s70, s52
	s_cselect_b32 s53, s31, s78
	s_cselect_b32 s52, s71, s77
	v_lshl_add_u64 v[174:175], s[46:47], 0, v[138:139]
	s_add_i32 m0, s35, 0xc000
	ds_read_b128 v[190:193], v151
	ds_read_b128 v[194:197], v151 offset:1024
	ds_read_b128 v[198:201], v151 offset:2048
	ds_read_b128 v[202:205], v151 offset:3072
	ds_read_b128 v[206:209], v151 offset:4096
	ds_read_b128 v[214:217], v151 offset:5120
	ds_read_b128 v[218:221], v151 offset:6144
	ds_read_b128 v[222:225], v151 offset:7168
	global_load_lds_dwordx4 v[174:175], off
	v_lshl_add_u64 v[174:175], s[46:47], 0, v[140:141]
	s_add_i32 m0, s35, 0xe000
	s_nop 0
	global_load_lds_dwordx4 v[174:175], off
	s_waitcnt vmcnt(8)
	s_waitcnt lgkmcnt(0)
	s_barrier
	s_waitcnt lgkmcnt(0)
	v_mfma_f32_16x16x32_bf16 v[124:127], v[154:157], v[190:193], v[124:127]
	v_mfma_f32_16x16x32_bf16 v[120:123], v[162:165], v[190:193], v[120:123]
	v_mfma_f32_16x16x32_bf16 v[116:119], v[154:157], v[198:201], v[116:119]
	v_mfma_f32_16x16x32_bf16 v[112:115], v[162:165], v[198:201], v[112:115]
	v_mfma_f32_16x16x32_bf16 v[100:103], v[154:157], v[206:209], v[100:103]
	v_mfma_f32_16x16x32_bf16 v[96:99], v[162:165], v[206:209], v[96:99]
	v_mfma_f32_16x16x32_bf16 v[84:87], v[154:157], v[218:221], v[84:87]
	v_mfma_f32_16x16x32_bf16 v[80:83], v[162:165], v[218:221], v[80:83]
	v_mfma_f32_16x16x32_bf16 v[124:127], v[158:161], v[194:197], v[124:127]
	v_mfma_f32_16x16x32_bf16 v[120:123], v[166:169], v[194:197], v[120:123]
	v_mfma_f32_16x16x32_bf16 v[116:119], v[158:161], v[202:205], v[116:119]
	v_mfma_f32_16x16x32_bf16 v[112:115], v[166:169], v[202:205], v[112:115]
	v_mfma_f32_16x16x32_bf16 v[100:103], v[158:161], v[214:217], v[100:103]
	v_mfma_f32_16x16x32_bf16 v[96:99], v[166:169], v[214:217], v[96:99]
	v_mfma_f32_16x16x32_bf16 v[84:87], v[158:161], v[222:225], v[84:87]
	v_mfma_f32_16x16x32_bf16 v[80:83], v[166:169], v[222:225], v[80:83]
	v_mfma_f32_16x16x32_bf16 v[108:111], v[170:173], v[190:193], v[108:111]
	v_mfma_f32_16x16x32_bf16 v[104:107], v[182:185], v[190:193], v[104:107]
	v_mfma_f32_16x16x32_bf16 v[92:95], v[170:173], v[198:201], v[92:95]
	v_mfma_f32_16x16x32_bf16 v[88:91], v[182:185], v[198:201], v[88:91]
	v_mfma_f32_16x16x32_bf16 v[76:79], v[170:173], v[206:209], v[76:79]
	v_mfma_f32_16x16x32_bf16 v[72:75], v[182:185], v[206:209], v[72:75]
	v_mfma_f32_16x16x32_bf16 v[68:71], v[170:173], v[218:221], v[68:71]
	v_mfma_f32_16x16x32_bf16 v[64:67], v[182:185], v[218:221], v[64:67]
	v_mfma_f32_16x16x32_bf16 v[108:111], v[178:181], v[194:197], v[108:111]
	v_mfma_f32_16x16x32_bf16 v[104:107], v[186:189], v[194:197], v[104:107]
	v_mfma_f32_16x16x32_bf16 v[92:95], v[178:181], v[202:205], v[92:95]
	v_mfma_f32_16x16x32_bf16 v[88:91], v[186:189], v[202:205], v[88:91]
	v_mfma_f32_16x16x32_bf16 v[76:79], v[178:181], v[214:217], v[76:79]
	v_mfma_f32_16x16x32_bf16 v[72:75], v[186:189], v[214:217], v[72:75]
	v_mfma_f32_16x16x32_bf16 v[68:71], v[178:181], v[222:225], v[68:71]
	v_mfma_f32_16x16x32_bf16 v[64:67], v[186:189], v[222:225], v[64:67]
	s_barrier
	s_add_i32 s80, s67, s33
	v_lshl_add_u64 v[174:175], s[52:53], 0, v[132:133]
	s_mov_b32 m0, s80
	ds_read_b128 v[190:193], v151 offset:16384
	ds_read_b128 v[194:197], v151 offset:17408
	ds_read_b128 v[198:201], v151 offset:18432
	ds_read_b128 v[202:205], v151 offset:19456
	ds_read_b128 v[206:209], v151 offset:20480
	ds_read_b128 v[214:217], v151 offset:21504
	ds_read_b128 v[218:221], v151 offset:22528
	ds_read_b128 v[222:225], v151 offset:23552
	global_load_lds_dwordx4 v[174:175], off
	s_add_i32 m0, s80, 0x2000
	s_add_u32 s80, s52, 0x40000
	v_lshl_add_u64 v[210:211], s[52:53], 0, v[128:129]
	s_addc_u32 s81, s53, 0
	s_add_i32 s83, s68, s33
	global_load_lds_dwordx4 v[210:211], off
	v_lshl_add_u64 v[226:227], s[80:81], 0, v[132:133]
	s_mov_b32 m0, s83
	v_lshl_add_u64 v[228:229], s[54:55], 0, v[130:131]
	global_load_lds_dwordx4 v[226:227], off
	v_lshl_add_u64 v[226:227], s[80:81], 0, v[128:129]
	s_add_i32 m0, s83, 0x2000
	s_nop 0
	global_load_lds_dwordx4 v[226:227], off
	v_lshl_add_u64 v[226:227], s[54:55], 0, v[134:135]
	s_mov_b32 m0, s35
	s_nop 0
	global_load_lds_dwordx4 v[226:227], off
	s_mov_b32 m0, s58
	s_nop 0
	global_load_lds_dwordx4 v[228:229], off
	s_waitcnt vmcnt(8)
	s_waitcnt lgkmcnt(0)
	s_barrier
	s_waitcnt lgkmcnt(0)
	v_mfma_f32_16x16x32_bf16 v[60:63], v[154:157], v[190:193], v[60:63]
	v_mfma_f32_16x16x32_bf16 v[56:59], v[162:165], v[190:193], v[56:59]
	v_mfma_f32_16x16x32_bf16 v[52:55], v[154:157], v[198:201], v[52:55]
	v_mfma_f32_16x16x32_bf16 v[48:51], v[162:165], v[198:201], v[48:51]
	v_mfma_f32_16x16x32_bf16 v[36:39], v[154:157], v[206:209], v[36:39]
	v_mfma_f32_16x16x32_bf16 v[32:35], v[162:165], v[206:209], v[32:35]
	v_mfma_f32_16x16x32_bf16 v[20:23], v[154:157], v[218:221], v[20:23]
	v_mfma_f32_16x16x32_bf16 v[16:19], v[162:165], v[218:221], v[16:19]
	v_mfma_f32_16x16x32_bf16 v[60:63], v[158:161], v[194:197], v[60:63]
	v_mfma_f32_16x16x32_bf16 v[56:59], v[166:169], v[194:197], v[56:59]
	v_mfma_f32_16x16x32_bf16 v[52:55], v[158:161], v[202:205], v[52:55]
	v_mfma_f32_16x16x32_bf16 v[48:51], v[166:169], v[202:205], v[48:51]
	v_mfma_f32_16x16x32_bf16 v[36:39], v[158:161], v[214:217], v[36:39]
	v_mfma_f32_16x16x32_bf16 v[32:35], v[166:169], v[214:217], v[32:35]
	v_mfma_f32_16x16x32_bf16 v[20:23], v[158:161], v[222:225], v[20:23]
	v_mfma_f32_16x16x32_bf16 v[16:19], v[166:169], v[222:225], v[16:19]
	v_mfma_f32_16x16x32_bf16 v[44:47], v[170:173], v[190:193], v[44:47]
	v_mfma_f32_16x16x32_bf16 v[40:43], v[182:185], v[190:193], v[40:43]
	v_mfma_f32_16x16x32_bf16 v[28:31], v[170:173], v[198:201], v[28:31]
	v_mfma_f32_16x16x32_bf16 v[24:27], v[182:185], v[198:201], v[24:27]
	v_mfma_f32_16x16x32_bf16 v[12:15], v[170:173], v[206:209], v[12:15]
	v_mfma_f32_16x16x32_bf16 v[8:11], v[182:185], v[206:209], v[8:11]
	v_mfma_f32_16x16x32_bf16 v[4:7], v[170:173], v[218:221], v[4:7]
	v_mfma_f32_16x16x32_bf16 v[0:3], v[182:185], v[218:221], v[0:3]
	v_mfma_f32_16x16x32_bf16 v[44:47], v[178:181], v[194:197], v[44:47]
	v_mfma_f32_16x16x32_bf16 v[40:43], v[186:189], v[194:197], v[40:43]
	v_mfma_f32_16x16x32_bf16 v[28:31], v[178:181], v[202:205], v[28:31]
	v_mfma_f32_16x16x32_bf16 v[24:27], v[186:189], v[202:205], v[24:27]
	v_mfma_f32_16x16x32_bf16 v[12:15], v[178:181], v[214:217], v[12:15]
	v_mfma_f32_16x16x32_bf16 v[8:11], v[186:189], v[214:217], v[8:11]
	v_mfma_f32_16x16x32_bf16 v[4:7], v[178:181], v[222:225], v[4:7]
	v_mfma_f32_16x16x32_bf16 v[0:3], v[186:189], v[222:225], v[0:3]
	s_barrier
	s_add_i32 s80, 0, 0x18000
	v_add_u32_e32 v136, s80, v147
	s_add_i32 s81, 0, 0x1c000
	ds_read_b128 v[154:157], v136
	ds_read_b128 v[158:161], v136 offset:1024
	ds_read_b128 v[162:165], v136 offset:2048
	ds_read_b128 v[166:169], v136 offset:3072
	v_add_u32_e32 v136, s81, v147
	ds_read_b128 v[170:173], v136
	ds_read_b128 v[178:181], v136 offset:1024
	ds_read_b128 v[182:185], v136 offset:2048
	ds_read_b128 v[186:189], v136 offset:3072
	s_add_u32 s54, s54, 0x40000
	s_addc_u32 s55, s55, 0
	s_mov_b32 m0, s59
	v_lshl_add_u64 v[230:231], s[54:55], 0, v[134:135]
	ds_read_b128 v[190:193], v151 offset:32768
	ds_read_b128 v[194:197], v151 offset:33792
	ds_read_b128 v[198:201], v151 offset:34816
	ds_read_b128 v[202:205], v151 offset:35840
	ds_read_b128 v[206:209], v151 offset:36864
	ds_read_b128 v[214:217], v151 offset:37888
	ds_read_b128 v[218:221], v151 offset:38912
	ds_read_b128 v[222:225], v151 offset:39936
	global_load_lds_dwordx4 v[230:231], off
	v_lshl_add_u64 v[230:231], s[54:55], 0, v[130:131]
	s_mov_b32 m0, s60
	s_nop 0
	global_load_lds_dwordx4 v[230:231], off
	s_waitcnt vmcnt(8)
	s_waitcnt lgkmcnt(0)
	s_barrier
	s_waitcnt lgkmcnt(0)
	v_mfma_f32_16x16x32_bf16 v[124:127], v[154:157], v[190:193], v[124:127]
	v_mfma_f32_16x16x32_bf16 v[120:123], v[162:165], v[190:193], v[120:123]
	v_mfma_f32_16x16x32_bf16 v[116:119], v[154:157], v[198:201], v[116:119]
	v_mfma_f32_16x16x32_bf16 v[112:115], v[162:165], v[198:201], v[112:115]
	v_mfma_f32_16x16x32_bf16 v[100:103], v[154:157], v[206:209], v[100:103]
	v_mfma_f32_16x16x32_bf16 v[96:99], v[162:165], v[206:209], v[96:99]
	v_mfma_f32_16x16x32_bf16 v[84:87], v[154:157], v[218:221], v[84:87]
	v_mfma_f32_16x16x32_bf16 v[80:83], v[162:165], v[218:221], v[80:83]
	v_mfma_f32_16x16x32_bf16 v[124:127], v[158:161], v[194:197], v[124:127]
	v_mfma_f32_16x16x32_bf16 v[120:123], v[166:169], v[194:197], v[120:123]
	v_mfma_f32_16x16x32_bf16 v[116:119], v[158:161], v[202:205], v[116:119]
	v_mfma_f32_16x16x32_bf16 v[112:115], v[166:169], v[202:205], v[112:115]
	v_mfma_f32_16x16x32_bf16 v[100:103], v[158:161], v[214:217], v[100:103]
	v_mfma_f32_16x16x32_bf16 v[96:99], v[166:169], v[214:217], v[96:99]
	v_mfma_f32_16x16x32_bf16 v[84:87], v[158:161], v[222:225], v[84:87]
	v_mfma_f32_16x16x32_bf16 v[80:83], v[166:169], v[222:225], v[80:83]
	v_mfma_f32_16x16x32_bf16 v[108:111], v[170:173], v[190:193], v[108:111]
	v_mfma_f32_16x16x32_bf16 v[104:107], v[182:185], v[190:193], v[104:107]
	v_mfma_f32_16x16x32_bf16 v[92:95], v[170:173], v[198:201], v[92:95]
	v_mfma_f32_16x16x32_bf16 v[88:91], v[182:185], v[198:201], v[88:91]
	v_mfma_f32_16x16x32_bf16 v[76:79], v[170:173], v[206:209], v[76:79]
	v_mfma_f32_16x16x32_bf16 v[72:75], v[182:185], v[206:209], v[72:75]
	v_mfma_f32_16x16x32_bf16 v[68:71], v[170:173], v[218:221], v[68:71]
	v_mfma_f32_16x16x32_bf16 v[64:67], v[182:185], v[218:221], v[64:67]
	v_mfma_f32_16x16x32_bf16 v[108:111], v[178:181], v[194:197], v[108:111]
	v_mfma_f32_16x16x32_bf16 v[104:107], v[186:189], v[194:197], v[104:107]
	v_mfma_f32_16x16x32_bf16 v[92:95], v[178:181], v[202:205], v[92:95]
	v_mfma_f32_16x16x32_bf16 v[88:91], v[186:189], v[202:205], v[88:91]
	v_mfma_f32_16x16x32_bf16 v[76:79], v[178:181], v[214:217], v[76:79]
	v_mfma_f32_16x16x32_bf16 v[72:75], v[186:189], v[214:217], v[72:75]
	v_mfma_f32_16x16x32_bf16 v[68:71], v[178:181], v[222:225], v[68:71]
	v_mfma_f32_16x16x32_bf16 v[64:67], v[186:189], v[222:225], v[64:67]
	s_barrier
; #define PG8_WAIT_V(n) asm volatile("s_waitcnt vmcnt(" #n ")" ::: "memory")
; #define PG8_BAR __builtin_amdgcn_s_barrier()
; template <class Epi, class Sched, bool ALIGN_EPI, bool CONVA>
; DI void gemm_phase(LAS unsigned char* lds, const Gemm g, const Sched& S, const Epi& E) {
;     ...
;         for (int t = 0; t < nt; t += 2) {
;             const bool last = (t == nt - 2);
;             const char* a1 = cA + (size_t)(t + 1) * kstep;
;             const char* a2 = last ? nA : cA + (size_t)(t + 2) * kstep; const char* b2 = last ? nB : cB + (size_t)(t + 2) * kstep;
;             const char* a3 = a2 + kstep; const char* b3 = b2 + kstep;
;             PG8_KBODY(PG8_WAIT_V(8));
;         }
;     ...
;         if constexpr (ALIGN_EPI) { if (wr == 0) PG8_BAR; }
	s_add_i32 s54, s80, s33
	v_lshl_add_u64 v[174:175], v[174:175], 0, s[6:7]
	s_mov_b32 m0, s54
	ds_read_b128 v[190:193], v151 offset:49152
	ds_read_b128 v[194:197], v151 offset:50176
	ds_read_b128 v[198:201], v151 offset:51200
	ds_read_b128 v[202:205], v151 offset:52224
	ds_read_b128 v[206:209], v151 offset:53248
	ds_read_b128 v[214:217], v151 offset:54272
	ds_read_b128 v[218:221], v151 offset:55296
	ds_read_b128 v[222:225], v151 offset:56320
	global_load_lds_dwordx4 v[174:175], off
	s_add_i32 m0, s54, 0x2000
	s_add_u32 s52, s52, 0x40080
	v_lshl_add_u64 v[174:175], v[210:211], 0, s[6:7]
	s_addc_u32 s53, s53, 0
	s_add_i32 s54, s81, s33
	global_load_lds_dwordx4 v[174:175], off
	v_lshl_add_u64 v[174:175], s[52:53], 0, v[132:133]
	s_mov_b32 m0, s54
	s_nop 0
	global_load_lds_dwordx4 v[174:175], off
	v_lshl_add_u64 v[174:175], s[52:53], 0, v[128:129]
	s_add_i32 m0, s54, 0x2000
	s_nop 0
	global_load_lds_dwordx4 v[174:175], off
	v_lshl_add_u64 v[174:175], v[226:227], 0, s[6:7]
	s_mov_b32 m0, s62
	s_nop 0
	global_load_lds_dwordx4 v[174:175], off
	v_lshl_add_u64 v[174:175], v[228:229], 0, s[6:7]
	s_mov_b32 m0, s63
	s_nop 0
	global_load_lds_dwordx4 v[174:175], off
	s_waitcnt vmcnt(8)
	s_waitcnt lgkmcnt(0)
	s_barrier
	s_waitcnt lgkmcnt(0)
	v_mfma_f32_16x16x32_bf16 v[60:63], v[154:157], v[190:193], v[60:63]
	v_mfma_f32_16x16x32_bf16 v[56:59], v[162:165], v[190:193], v[56:59]
	v_mfma_f32_16x16x32_bf16 v[52:55], v[154:157], v[198:201], v[52:55]
	v_mfma_f32_16x16x32_bf16 v[48:51], v[162:165], v[198:201], v[48:51]
	v_mfma_f32_16x16x32_bf16 v[36:39], v[154:157], v[206:209], v[36:39]
	v_mfma_f32_16x16x32_bf16 v[32:35], v[162:165], v[206:209], v[32:35]
	v_mfma_f32_16x16x32_bf16 v[20:23], v[154:157], v[218:221], v[20:23]
	v_mfma_f32_16x16x32_bf16 v[16:19], v[162:165], v[218:221], v[16:19]
	v_mfma_f32_16x16x32_bf16 v[60:63], v[158:161], v[194:197], v[60:63]
	v_mfma_f32_16x16x32_bf16 v[56:59], v[166:169], v[194:197], v[56:59]
	v_mfma_f32_16x16x32_bf16 v[52:55], v[158:161], v[202:205], v[52:55]
	v_mfma_f32_16x16x32_bf16 v[48:51], v[166:169], v[202:205], v[48:51]
	v_mfma_f32_16x16x32_bf16 v[36:39], v[158:161], v[214:217], v[36:39]
	v_mfma_f32_16x16x32_bf16 v[32:35], v[166:169], v[214:217], v[32:35]
	v_mfma_f32_16x16x32_bf16 v[20:23], v[158:161], v[222:225], v[20:23]
	v_mfma_f32_16x16x32_bf16 v[16:19], v[166:169], v[222:225], v[16:19]
	v_mfma_f32_16x16x32_bf16 v[44:47], v[170:173], v[190:193], v[44:47]
	v_mfma_f32_16x16x32_bf16 v[40:43], v[182:185], v[190:193], v[40:43]
	v_mfma_f32_16x16x32_bf16 v[28:31], v[170:173], v[198:201], v[28:31]
	v_mfma_f32_16x16x32_bf16 v[24:27], v[182:185], v[198:201], v[24:27]
	v_mfma_f32_16x16x32_bf16 v[12:15], v[170:173], v[206:209], v[12:15]
	v_mfma_f32_16x16x32_bf16 v[8:11], v[182:185], v[206:209], v[8:11]
	v_mfma_f32_16x16x32_bf16 v[4:7], v[170:173], v[218:221], v[4:7]
	v_mfma_f32_16x16x32_bf16 v[0:3], v[182:185], v[218:221], v[0:3]
	v_mfma_f32_16x16x32_bf16 v[44:47], v[178:181], v[194:197], v[44:47]
	v_mfma_f32_16x16x32_bf16 v[40:43], v[186:189], v[194:197], v[40:43]
	v_mfma_f32_16x16x32_bf16 v[28:31], v[178:181], v[202:205], v[28:31]
	v_mfma_f32_16x16x32_bf16 v[24:27], v[186:189], v[202:205], v[24:27]
	v_mfma_f32_16x16x32_bf16 v[12:15], v[178:181], v[214:217], v[12:15]
	v_mfma_f32_16x16x32_bf16 v[8:11], v[186:189], v[214:217], v[8:11]
	v_mfma_f32_16x16x32_bf16 v[4:7], v[178:181], v[222:225], v[4:7]
	v_mfma_f32_16x16x32_bf16 v[0:3], v[186:189], v[222:225], v[0:3]
	s_barrier
	s_add_i32 s79, s79, 2
	s_add_u32 s46, s46, 0x100
	s_addc_u32 s47, s47, 0
	s_add_u32 s77, s77, 0x100
	s_addc_u32 s78, s78, 0
	s_cmp_gt_u32 s79, 13
	s_cbranch_scc0 .LBB0_162
	s_and_b64 vcc, exec, s[8:9]
	s_cbranch_vccz .LBB0_165
	s_barrier

;     DI bool next(int i, Unit& u) const { if (!s.next(i >> 1, u)) return false; u.sel = i & 1; return true; }
; template <class Epi, class Sched, bool ALIGN_EPI, bool CONVA>
; DI void gemm_phase(LAS unsigned char* lds, const Gemm g, const Sched& S, const Epi& E) {
;     ...
;         const bool has_next = S.next(ui + 1, nxt);
;         const char* nA = has_next ? (const char*)(nxt.sel ? g.A2 : g.A) + (size_t)nxt.pm * tstepA + abias : cA;
;         const char* nB = has_next ? (const char*)(nxt.sel ? g.Bt2 : g.Bt) + (size_t)nxt.pn * tstepB : cB;
.LBB0_532:
	s_xor_b64 s[48:49], s[42:43], -1
	s_mov_b64 s[50:51], s[30:31]
	s_and_b64 s[30:31], s[42:43], exec
	s_cselect_b32 s44, s18, s18
	s_cselect_b32 s30, s16, s16
	s_ashr_i32 s45, s44, 31
	s_lshl_b64 s[44:45], s[44:45], 19
	s_add_u32 s44, s28, s44
	s_addc_u32 s45, s29, s45
	s_and_b64 s[52:53], s[42:43], exec
	s_cselect_b32 s6, s45, s47
	s_cselect_b32 s71, s44, s46
	s_ashr_i32 s31, s30, 31
	s_lshl_b64 s[30:31], s[30:31], 19
	s_add_u32 s30, s56, s30
	s_addc_u32 s31, s57, s31
	s_and_b64 s[52:53], s[42:43], exec
	s_cselect_b32 s80, s31, s51
	s_cselect_b32 s83, s30, s50
	s_add_u32 s46, s46, 0x40080
	s_addc_u32 s47, s47, 0
	s_add_u32 s84, s50, 0x100
	s_addc_u32 s85, s51, 0
	s_mov_b32 s86, -2
	s_add_u32 s19, s46, 0xfffc0080
	s_addc_u32 s33, s47, -1
	s_add_i32 s17, 0, 0x10000
	s_cmp_eq_u32 s86, 12
	s_cselect_b32 s53, s6, s33
	s_cselect_b32 s52, s71, s19
	v_add_u32_e32 v128, s17, v130
	s_cselect_b32 s51, s80, s85
	s_cselect_b32 s50, s83, s84
	s_add_i32 s19, 0, 0x14000
	ds_read_b128 v[132:135], v128
	ds_read_b128 v[136:139], v128 offset:1024
	ds_read_b128 v[140:143], v128 offset:2048
	ds_read_b128 v[166:169], v128 offset:3072
	v_add_u32_e32 v128, s19, v130
	ds_read_b128 v[170:173], v128
	ds_read_b128 v[178:181], v128 offset:1024
	ds_read_b128 v[190:193], v128 offset:2048
	ds_read_b128 v[194:197], v128 offset:3072
	v_lshl_add_u64 v[128:129], s[46:47], 0, v[158:159]
	s_add_i32 m0, s63, 0xc000
	ds_read_b128 v[198:201], v131
	ds_read_b128 v[202:205], v131 offset:1024
	ds_read_b128 v[206:209], v131 offset:2048
	ds_read_b128 v[214:217], v131 offset:3072
	ds_read_b128 v[218:221], v131 offset:4096
	ds_read_b128 v[222:225], v131 offset:5120
	ds_read_b128 v[226:229], v131 offset:6144
	ds_read_b128 v[230:233], v131 offset:7168
	global_load_lds_dwordx4 v[128:129], off
	v_lshl_add_u64 v[128:129], s[46:47], 0, v[160:161]
	s_add_i32 m0, s63, 0xe000
	s_nop 0
	global_load_lds_dwordx4 v[128:129], off
	s_waitcnt vmcnt(8)
	s_waitcnt lgkmcnt(0)
	s_barrier
	s_waitcnt lgkmcnt(0)
	v_mfma_f32_16x16x32_bf16 v[124:127], v[132:135], v[198:201], 0
	v_mfma_f32_16x16x32_bf16 v[120:123], v[140:143], v[198:201], 0
	v_mfma_f32_16x16x32_bf16 v[116:119], v[132:135], v[206:209], 0
	v_mfma_f32_16x16x32_bf16 v[112:115], v[140:143], v[206:209], 0
	v_mfma_f32_16x16x32_bf16 v[96:99], v[132:135], v[218:221], 0
	v_mfma_f32_16x16x32_bf16 v[92:95], v[140:143], v[218:221], 0
	v_mfma_f32_16x16x32_bf16 v[88:91], v[132:135], v[226:229], 0
	v_mfma_f32_16x16x32_bf16 v[80:83], v[140:143], v[226:229], 0
	v_mfma_f32_16x16x32_bf16 v[124:127], v[136:139], v[202:205], v[124:127]
	v_mfma_f32_16x16x32_bf16 v[120:123], v[166:169], v[202:205], v[120:123]
	v_mfma_f32_16x16x32_bf16 v[116:119], v[136:139], v[214:217], v[116:119]
	v_mfma_f32_16x16x32_bf16 v[112:115], v[166:169], v[214:217], v[112:115]
	v_mfma_f32_16x16x32_bf16 v[96:99], v[136:139], v[222:225], v[96:99]
	v_mfma_f32_16x16x32_bf16 v[92:95], v[166:169], v[222:225], v[92:95]
	v_mfma_f32_16x16x32_bf16 v[88:91], v[136:139], v[230:233], v[88:91]
	v_mfma_f32_16x16x32_bf16 v[80:83], v[166:169], v[230:233], v[80:83]
	v_mfma_f32_16x16x32_bf16 v[108:111], v[170:173], v[198:201], 0
	v_mfma_f32_16x16x32_bf16 v[104:107], v[190:193], v[198:201], 0
	v_mfma_f32_16x16x32_bf16 v[100:103], v[170:173], v[206:209], 0
	v_mfma_f32_16x16x32_bf16 v[84:87], v[190:193], v[206:209], 0
	v_mfma_f32_16x16x32_bf16 v[76:79], v[170:173], v[218:221], 0
	v_mfma_f32_16x16x32_bf16 v[72:75], v[190:193], v[218:221], 0
	v_mfma_f32_16x16x32_bf16 v[68:71], v[170:173], v[226:229], 0
	v_mfma_f32_16x16x32_bf16 v[64:67], v[190:193], v[226:229], 0
	v_mfma_f32_16x16x32_bf16 v[108:111], v[178:181], v[202:205], v[108:111]
	v_mfma_f32_16x16x32_bf16 v[104:107], v[194:197], v[202:205], v[104:107]
	v_mfma_f32_16x16x32_bf16 v[100:103], v[178:181], v[214:217], v[100:103]
	v_mfma_f32_16x16x32_bf16 v[84:87], v[194:197], v[214:217], v[84:87]
	v_mfma_f32_16x16x32_bf16 v[76:79], v[178:181], v[222:225], v[76:79]
	v_mfma_f32_16x16x32_bf16 v[72:75], v[194:197], v[222:225], v[72:75]
	v_mfma_f32_16x16x32_bf16 v[68:71], v[178:181], v[230:233], v[68:71]
	v_mfma_f32_16x16x32_bf16 v[64:67], v[194:197], v[230:233], v[64:67]
	s_barrier
	s_add_i32 s33, s17, s62
	v_lshl_add_u64 v[128:129], s[50:51], 0, v[146:147]
	s_mov_b32 m0, s33
	ds_read_b128 v[198:201], v131 offset:16384
	ds_read_b128 v[202:205], v131 offset:17408
	ds_read_b128 v[206:209], v131 offset:18432
	ds_read_b128 v[214:217], v131 offset:19456
	ds_read_b128 v[218:221], v131 offset:20480
	ds_read_b128 v[222:225], v131 offset:21504
	ds_read_b128 v[226:229], v131 offset:22528
	ds_read_b128 v[230:233], v131 offset:23552
	global_load_lds_dwordx4 v[128:129], off
	s_add_i32 m0, s33, 0x2000
	s_add_u32 s88, s50, 0x40000
	v_lshl_add_u64 v[174:175], s[50:51], 0, v[150:151]
	s_addc_u32 s89, s51, 0
	s_add_i32 s33, s19, s62
	global_load_lds_dwordx4 v[174:175], off
	v_lshl_add_u64 v[182:183], s[88:89], 0, v[146:147]
	s_mov_b32 m0, s33
	v_lshl_add_u64 v[210:211], s[52:53], 0, v[148:149]
	global_load_lds_dwordx4 v[182:183], off
	v_lshl_add_u64 v[182:183], s[88:89], 0, v[150:151]
	s_add_i32 m0, s33, 0x2000
	s_nop 0
	global_load_lds_dwordx4 v[182:183], off
	v_lshl_add_u64 v[182:183], s[52:53], 0, v[144:145]
	s_mov_b32 m0, s63
	s_nop 0
	global_load_lds_dwordx4 v[182:183], off
	s_mov_b32 m0, s64
	s_nop 0
	global_load_lds_dwordx4 v[210:211], off
	s_waitcnt vmcnt(8)
	s_waitcnt lgkmcnt(0)
	s_barrier
	s_waitcnt lgkmcnt(0)
	v_mfma_f32_16x16x32_bf16 v[60:63], v[132:135], v[198:201], 0
	v_mfma_f32_16x16x32_bf16 v[56:59], v[140:143], v[198:201], 0
	v_mfma_f32_16x16x32_bf16 v[44:47], v[132:135], v[206:209], 0
	v_mfma_f32_16x16x32_bf16 v[40:43], v[140:143], v[206:209], 0
	v_mfma_f32_16x16x32_bf16 v[28:31], v[132:135], v[218:221], 0
	v_mfma_f32_16x16x32_bf16 v[24:27], v[140:143], v[218:221], 0
	v_mfma_f32_16x16x32_bf16 v[12:15], v[132:135], v[226:229], 0
	v_mfma_f32_16x16x32_bf16 v[8:11], v[140:143], v[226:229], 0
	v_mfma_f32_16x16x32_bf16 v[60:63], v[136:139], v[202:205], v[60:63]
	v_mfma_f32_16x16x32_bf16 v[56:59], v[166:169], v[202:205], v[56:59]
	v_mfma_f32_16x16x32_bf16 v[44:47], v[136:139], v[214:217], v[44:47]
	v_mfma_f32_16x16x32_bf16 v[40:43], v[166:169], v[214:217], v[40:43]
	v_mfma_f32_16x16x32_bf16 v[28:31], v[136:139], v[222:225], v[28:31]
	v_mfma_f32_16x16x32_bf16 v[24:27], v[166:169], v[222:225], v[24:27]
	v_mfma_f32_16x16x32_bf16 v[12:15], v[136:139], v[230:233], v[12:15]
	v_mfma_f32_16x16x32_bf16 v[8:11], v[166:169], v[230:233], v[8:11]
	v_mfma_f32_16x16x32_bf16 v[52:55], v[170:173], v[198:201], 0
	v_mfma_f32_16x16x32_bf16 v[48:51], v[190:193], v[198:201], 0
	v_mfma_f32_16x16x32_bf16 v[36:39], v[170:173], v[206:209], 0
	v_mfma_f32_16x16x32_bf16 v[32:35], v[190:193], v[206:209], 0
	v_mfma_f32_16x16x32_bf16 v[20:23], v[170:173], v[218:221], 0
	v_mfma_f32_16x16x32_bf16 v[16:19], v[190:193], v[218:221], 0
	v_mfma_f32_16x16x32_bf16 v[4:7], v[170:173], v[226:229], 0
	v_mfma_f32_16x16x32_bf16 v[0:3], v[190:193], v[226:229], 0
	v_mfma_f32_16x16x32_bf16 v[52:55], v[178:181], v[202:205], v[52:55]
	v_mfma_f32_16x16x32_bf16 v[48:51], v[194:197], v[202:205], v[48:51]
	v_mfma_f32_16x16x32_bf16 v[36:39], v[178:181], v[214:217], v[36:39]
	v_mfma_f32_16x16x32_bf16 v[32:35], v[194:197], v[214:217], v[32:35]
	v_mfma_f32_16x16x32_bf16 v[20:23], v[178:181], v[222:225], v[20:23]
	v_mfma_f32_16x16x32_bf16 v[16:19], v[194:197], v[222:225], v[16:19]
	v_mfma_f32_16x16x32_bf16 v[4:7], v[178:181], v[230:233], v[4:7]
	v_mfma_f32_16x16x32_bf16 v[0:3], v[194:197], v[230:233], v[0:3]
	s_barrier
	s_add_i32 s33, 0, 0x18000
	s_add_i32 s81, 0, 0x1c000
	v_add_u32_e32 v166, s33, v130
	v_add_u32_e32 v189, s81, v130
	ds_read_b128 v[132:135], v166
	ds_read_b128 v[136:139], v166 offset:1024
	ds_read_b128 v[140:143], v166 offset:2048
	ds_read_b128 v[166:169], v166 offset:3072
	ds_read_b128 v[170:173], v189
	ds_read_b128 v[178:181], v189 offset:1024
	ds_read_b128 v[190:193], v189 offset:2048
	ds_read_b128 v[194:197], v189 offset:3072
	s_add_u32 s52, s52, 0x40000
	s_addc_u32 s53, s53, 0
	s_mov_b32 m0, s65
	v_lshl_add_u64 v[234:235], s[52:53], 0, v[144:145]
	ds_read_b128 v[198:201], v131 offset:32768
	ds_read_b128 v[202:205], v131 offset:33792
	ds_read_b128 v[206:209], v131 offset:34816
	ds_read_b128 v[214:217], v131 offset:35840
	ds_read_b128 v[218:221], v131 offset:36864
	ds_read_b128 v[222:225], v131 offset:37888
	ds_read_b128 v[226:229], v131 offset:38912
	ds_read_b128 v[230:233], v131 offset:39936
	global_load_lds_dwordx4 v[234:235], off
	v_lshl_add_u64 v[234:235], s[52:53], 0, v[148:149]
	s_mov_b32 m0, s68
	s_nop 0
	global_load_lds_dwordx4 v[234:235], off
	s_waitcnt vmcnt(8)
	s_waitcnt lgkmcnt(0)
	s_barrier
	s_waitcnt lgkmcnt(0)
	v_mfma_f32_16x16x32_bf16 v[124:127], v[132:135], v[198:201], v[124:127]
	v_mfma_f32_16x16x32_bf16 v[120:123], v[140:143], v[198:201], v[120:123]
	v_mfma_f32_16x16x32_bf16 v[116:119], v[132:135], v[206:209], v[116:119]
	v_mfma_f32_16x16x32_bf16 v[112:115], v[140:143], v[206:209], v[112:115]
	v_mfma_f32_16x16x32_bf16 v[96:99], v[132:135], v[218:221], v[96:99]
	v_mfma_f32_16x16x32_bf16 v[92:95], v[140:143], v[218:221], v[92:95]
	v_mfma_f32_16x16x32_bf16 v[88:91], v[132:135], v[226:229], v[88:91]
	v_mfma_f32_16x16x32_bf16 v[80:83], v[140:143], v[226:229], v[80:83]
	v_mfma_f32_16x16x32_bf16 v[124:127], v[136:139], v[202:205], v[124:127]
	v_mfma_f32_16x16x32_bf16 v[120:123], v[166:169], v[202:205], v[120:123]
	v_mfma_f32_16x16x32_bf16 v[116:119], v[136:139], v[214:217], v[116:119]
	v_mfma_f32_16x16x32_bf16 v[112:115], v[166:169], v[214:217], v[112:115]
	v_mfma_f32_16x16x32_bf16 v[96:99], v[136:139], v[222:225], v[96:99]
	v_mfma_f32_16x16x32_bf16 v[92:95], v[166:169], v[222:225], v[92:95]
	v_mfma_f32_16x16x32_bf16 v[88:91], v[136:139], v[230:233], v[88:91]
	v_mfma_f32_16x16x32_bf16 v[80:83], v[166:169], v[230:233], v[80:83]
	v_mfma_f32_16x16x32_bf16 v[108:111], v[170:173], v[198:201], v[108:111]
	v_mfma_f32_16x16x32_bf16 v[104:107], v[190:193], v[198:201], v[104:107]
	v_mfma_f32_16x16x32_bf16 v[100:103], v[170:173], v[206:209], v[100:103]
	v_mfma_f32_16x16x32_bf16 v[84:87], v[190:193], v[206:209], v[84:87]
	v_mfma_f32_16x16x32_bf16 v[76:79], v[170:173], v[218:221], v[76:79]
	v_mfma_f32_16x16x32_bf16 v[72:75], v[190:193], v[218:221], v[72:75]
	v_mfma_f32_16x16x32_bf16 v[68:71], v[170:173], v[226:229], v[68:71]
	v_mfma_f32_16x16x32_bf16 v[64:67], v[190:193], v[226:229], v[64:67]
	v_mfma_f32_16x16x32_bf16 v[108:111], v[178:181], v[202:205], v[108:111]
	v_mfma_f32_16x16x32_bf16 v[104:107], v[194:197], v[202:205], v[104:107]
	v_mfma_f32_16x16x32_bf16 v[100:103], v[178:181], v[214:217], v[100:103]
	v_mfma_f32_16x16x32_bf16 v[84:87], v[194:197], v[214:217], v[84:87]
	v_mfma_f32_16x16x32_bf16 v[76:79], v[178:181], v[222:225], v[76:79]
	v_mfma_f32_16x16x32_bf16 v[72:75], v[194:197], v[222:225], v[72:75]
	v_mfma_f32_16x16x32_bf16 v[68:71], v[178:181], v[230:233], v[68:71]
	v_mfma_f32_16x16x32_bf16 v[64:67], v[194:197], v[230:233], v[64:67]
	s_barrier
; #define PG8_WAIT_V(n) asm volatile("s_waitcnt vmcnt(" #n ")" ::: "memory")
; template <class Epi, class Sched, bool ALIGN_EPI, bool CONVA>
; DI void gemm_phase(LAS unsigned char* lds, const Gemm g, const Sched& S, const Epi& E) {
;     ...
;         for (int t = 0; t < nt; t += 2) {
;             const bool last = (t == nt - 2);
;             const char* a1 = cA + (size_t)(t + 1) * kstep;
;             const char* a2 = last ? nA : cA + (size_t)(t + 2) * kstep; const char* b2 = last ? nB : cB + (size_t)(t + 2) * kstep;
;             const char* a3 = a2 + kstep; const char* b3 = b2 + kstep;
;             PG8_KBODY(PG8_WAIT_V(8));
	s_add_i32 s52, s33, s62
	v_lshl_add_u64 v[128:129], v[128:129], 0, s[12:13]
	s_mov_b32 m0, s52
	ds_read_b128 v[198:201], v131 offset:49152
	ds_read_b128 v[202:205], v131 offset:50176
	ds_read_b128 v[206:209], v131 offset:51200
	ds_read_b128 v[214:217], v131 offset:52224
	ds_read_b128 v[218:221], v131 offset:53248
	ds_read_b128 v[222:225], v131 offset:54272
	ds_read_b128 v[226:229], v131 offset:55296
	ds_read_b128 v[230:233], v131 offset:56320
	global_load_lds_dwordx4 v[128:129], off
	s_add_i32 m0, s52, 0x2000
	s_add_u32 s50, s50, 0x40080
	v_lshl_add_u64 v[128:129], v[174:175], 0, s[12:13]
	s_addc_u32 s51, s51, 0
	s_add_i32 s52, s81, s62
	global_load_lds_dwordx4 v[128:129], off
	v_lshl_add_u64 v[128:129], s[50:51], 0, v[146:147]
	s_mov_b32 m0, s52
	s_nop 0
	global_load_lds_dwordx4 v[128:129], off
	v_lshl_add_u64 v[128:129], s[50:51], 0, v[150:151]
	s_add_i32 m0, s52, 0x2000
	s_nop 0
	global_load_lds_dwordx4 v[128:129], off
	v_lshl_add_u64 v[128:129], v[182:183], 0, s[12:13]
	s_mov_b32 m0, s69
	s_nop 0
	global_load_lds_dwordx4 v[128:129], off
	v_lshl_add_u64 v[128:129], v[210:211], 0, s[12:13]
	s_mov_b32 m0, s70
	s_nop 0
	global_load_lds_dwordx4 v[128:129], off
	s_waitcnt vmcnt(8)
	s_waitcnt lgkmcnt(0)
	s_barrier
	s_waitcnt lgkmcnt(0)
	v_mfma_f32_16x16x32_bf16 v[60:63], v[132:135], v[198:201], v[60:63]
	v_mfma_f32_16x16x32_bf16 v[56:59], v[140:143], v[198:201], v[56:59]
	v_mfma_f32_16x16x32_bf16 v[44:47], v[132:135], v[206:209], v[44:47]
	v_mfma_f32_16x16x32_bf16 v[40:43], v[140:143], v[206:209], v[40:43]
	v_mfma_f32_16x16x32_bf16 v[28:31], v[132:135], v[218:221], v[28:31]
	v_mfma_f32_16x16x32_bf16 v[24:27], v[140:143], v[218:221], v[24:27]
	v_mfma_f32_16x16x32_bf16 v[12:15], v[132:135], v[226:229], v[12:15]
	v_mfma_f32_16x16x32_bf16 v[8:11], v[140:143], v[226:229], v[8:11]
	v_mfma_f32_16x16x32_bf16 v[60:63], v[136:139], v[202:205], v[60:63]
	v_mfma_f32_16x16x32_bf16 v[56:59], v[166:169], v[202:205], v[56:59]
	v_mfma_f32_16x16x32_bf16 v[44:47], v[136:139], v[214:217], v[44:47]
	v_mfma_f32_16x16x32_bf16 v[40:43], v[166:169], v[214:217], v[40:43]
	v_mfma_f32_16x16x32_bf16 v[28:31], v[136:139], v[222:225], v[28:31]
	v_mfma_f32_16x16x32_bf16 v[24:27], v[166:169], v[222:225], v[24:27]
	v_mfma_f32_16x16x32_bf16 v[12:15], v[136:139], v[230:233], v[12:15]
	v_mfma_f32_16x16x32_bf16 v[8:11], v[166:169], v[230:233], v[8:11]
	v_mfma_f32_16x16x32_bf16 v[52:55], v[170:173], v[198:201], v[52:55]
	v_mfma_f32_16x16x32_bf16 v[48:51], v[190:193], v[198:201], v[48:51]
	v_mfma_f32_16x16x32_bf16 v[36:39], v[170:173], v[206:209], v[36:39]
	v_mfma_f32_16x16x32_bf16 v[32:35], v[190:193], v[206:209], v[32:35]
	v_mfma_f32_16x16x32_bf16 v[20:23], v[170:173], v[218:221], v[20:23]
	v_mfma_f32_16x16x32_bf16 v[16:19], v[190:193], v[218:221], v[16:19]
	v_mfma_f32_16x16x32_bf16 v[4:7], v[170:173], v[226:229], v[4:7]
	v_mfma_f32_16x16x32_bf16 v[0:3], v[190:193], v[226:229], v[0:3]
	v_mfma_f32_16x16x32_bf16 v[52:55], v[178:181], v[202:205], v[52:55]
	v_mfma_f32_16x16x32_bf16 v[48:51], v[194:197], v[202:205], v[48:51]
	v_mfma_f32_16x16x32_bf16 v[36:39], v[178:181], v[214:217], v[36:39]
	v_mfma_f32_16x16x32_bf16 v[32:35], v[194:197], v[214:217], v[32:35]
	v_mfma_f32_16x16x32_bf16 v[20:23], v[178:181], v[222:225], v[20:23]
	v_mfma_f32_16x16x32_bf16 v[16:19], v[194:197], v[222:225], v[16:19]
	v_mfma_f32_16x16x32_bf16 v[4:7], v[178:181], v[230:233], v[4:7]
	v_mfma_f32_16x16x32_bf16 v[0:3], v[194:197], v[230:233], v[0:3]
	s_barrier
	s_add_i32 s86, s86, 2
	s_add_u32 s46, s46, 0x100
	s_addc_u32 s47, s47, 0
	s_add_u32 s84, s84, 0x100
	s_addc_u32 s85, s85, 0
	s_cmp_gt_u32 s86, 13
.LBB0_533:
	s_add_u32 s19, s46, 0xfffc0080
	s_addc_u32 s33, s47, -1
	s_add_i32 s17, 0, 0x10000
	s_cmp_eq_u32 s86, 12
	s_cselect_b32 s53, s6, s33
	s_cselect_b32 s52, s71, s19
	v_add_u32_e32 v128, s17, v130
	s_cselect_b32 s51, s80, s85
	s_cselect_b32 s50, s83, s84
	s_add_i32 s19, 0, 0x14000
	ds_read_b128 v[132:135], v128
	ds_read_b128 v[136:139], v128 offset:1024
	ds_read_b128 v[140:143], v128 offset:2048
	ds_read_b128 v[166:169], v128 offset:3072
	v_add_u32_e32 v128, s19, v130
	ds_read_b128 v[170:173], v128
	ds_read_b128 v[178:181], v128 offset:1024
	ds_read_b128 v[190:193], v128 offset:2048
	ds_read_b128 v[194:197], v128 offset:3072
	v_lshl_add_u64 v[128:129], s[46:47], 0, v[158:159]
	s_add_i32 m0, s63, 0xc000
	ds_read_b128 v[198:201], v131
	ds_read_b128 v[202:205], v131 offset:1024
	ds_read_b128 v[206:209], v131 offset:2048
	ds_read_b128 v[214:217], v131 offset:3072
	ds_read_b128 v[218:221], v131 offset:4096
	ds_read_b128 v[222:225], v131 offset:5120
	ds_read_b128 v[226:229], v131 offset:6144
	ds_read_b128 v[230:233], v131 offset:7168
	global_load_lds_dwordx4 v[128:129], off
	v_lshl_add_u64 v[128:129], s[46:47], 0, v[160:161]
	s_add_i32 m0, s63, 0xe000
	s_nop 0
	global_load_lds_dwordx4 v[128:129], off
	s_waitcnt vmcnt(8)
	s_waitcnt lgkmcnt(0)
	s_barrier
	s_waitcnt lgkmcnt(0)
	v_mfma_f32_16x16x32_bf16 v[124:127], v[132:135], v[198:201], v[124:127]
	v_mfma_f32_16x16x32_bf16 v[120:123], v[140:143], v[198:201], v[120:123]
	v_mfma_f32_16x16x32_bf16 v[116:119], v[132:135], v[206:209], v[116:119]
	v_mfma_f32_16x16x32_bf16 v[112:115], v[140:143], v[206:209], v[112:115]
	v_mfma_f32_16x16x32_bf16 v[96:99], v[132:135], v[218:221], v[96:99]
	v_mfma_f32_16x16x32_bf16 v[92:95], v[140:143], v[218:221], v[92:95]
	v_mfma_f32_16x16x32_bf16 v[88:91], v[132:135], v[226:229], v[88:91]
	v_mfma_f32_16x16x32_bf16 v[80:83], v[140:143], v[226:229], v[80:83]
	v_mfma_f32_16x16x32_bf16 v[124:127], v[136:139], v[202:205], v[124:127]
	v_mfma_f32_16x16x32_bf16 v[120:123], v[166:169], v[202:205], v[120:123]
	v_mfma_f32_16x16x32_bf16 v[116:119], v[136:139], v[214:217], v[116:119]
	v_mfma_f32_16x16x32_bf16 v[112:115], v[166:169], v[214:217], v[112:115]
	v_mfma_f32_16x16x32_bf16 v[96:99], v[136:139], v[222:225], v[96:99]
	v_mfma_f32_16x16x32_bf16 v[92:95], v[166:169], v[222:225], v[92:95]
	v_mfma_f32_16x16x32_bf16 v[88:91], v[136:139], v[230:233], v[88:91]
	v_mfma_f32_16x16x32_bf16 v[80:83], v[166:169], v[230:233], v[80:83]
	v_mfma_f32_16x16x32_bf16 v[108:111], v[170:173], v[198:201], v[108:111]
	v_mfma_f32_16x16x32_bf16 v[104:107], v[190:193], v[198:201], v[104:107]
	v_mfma_f32_16x16x32_bf16 v[100:103], v[170:173], v[206:209], v[100:103]
	v_mfma_f32_16x16x32_bf16 v[84:87], v[190:193], v[206:209], v[84:87]
	v_mfma_f32_16x16x32_bf16 v[76:79], v[170:173], v[218:221], v[76:79]
	v_mfma_f32_16x16x32_bf16 v[72:75], v[190:193], v[218:221], v[72:75]
	v_mfma_f32_16x16x32_bf16 v[68:71], v[170:173], v[226:229], v[68:71]
	v_mfma_f32_16x16x32_bf16 v[64:67], v[190:193], v[226:229], v[64:67]
	v_mfma_f32_16x16x32_bf16 v[108:111], v[178:181], v[202:205], v[108:111]
	v_mfma_f32_16x16x32_bf16 v[104:107], v[194:197], v[202:205], v[104:107]
	v_mfma_f32_16x16x32_bf16 v[100:103], v[178:181], v[214:217], v[100:103]
	v_mfma_f32_16x16x32_bf16 v[84:87], v[194:197], v[214:217], v[84:87]
	v_mfma_f32_16x16x32_bf16 v[76:79], v[178:181], v[222:225], v[76:79]
	v_mfma_f32_16x16x32_bf16 v[72:75], v[194:197], v[222:225], v[72:75]
	v_mfma_f32_16x16x32_bf16 v[68:71], v[178:181], v[230:233], v[68:71]
	v_mfma_f32_16x16x32_bf16 v[64:67], v[194:197], v[230:233], v[64:67]
	s_barrier
	s_add_i32 s33, s17, s62
	v_lshl_add_u64 v[128:129], s[50:51], 0, v[146:147]
	s_mov_b32 m0, s33
	ds_read_b128 v[198:201], v131 offset:16384
	ds_read_b128 v[202:205], v131 offset:17408
	ds_read_b128 v[206:209], v131 offset:18432
	ds_read_b128 v[214:217], v131 offset:19456
	ds_read_b128 v[218:221], v131 offset:20480
	ds_read_b128 v[222:225], v131 offset:21504
	ds_read_b128 v[226:229], v131 offset:22528
	ds_read_b128 v[230:233], v131 offset:23552
	global_load_lds_dwordx4 v[128:129], off
	s_add_i32 m0, s33, 0x2000
	s_add_u32 s88, s50, 0x40000
	v_lshl_add_u64 v[174:175], s[50:51], 0, v[150:151]
	s_addc_u32 s89, s51, 0
	s_add_i32 s33, s19, s62
	global_load_lds_dwordx4 v[174:175], off
	v_lshl_add_u64 v[182:183], s[88:89], 0, v[146:147]
	s_mov_b32 m0, s33
	v_lshl_add_u64 v[210:211], s[52:53], 0, v[148:149]
	global_load_lds_dwordx4 v[182:183], off
	v_lshl_add_u64 v[182:183], s[88:89], 0, v[150:151]
	s_add_i32 m0, s33, 0x2000
	s_nop 0
	global_load_lds_dwordx4 v[182:183], off
	v_lshl_add_u64 v[182:183], s[52:53], 0, v[144:145]
	s_mov_b32 m0, s63
	s_nop 0
	global_load_lds_dwordx4 v[182:183], off
	s_mov_b32 m0, s64
	s_nop 0
	global_load_lds_dwordx4 v[210:211], off
	s_waitcnt vmcnt(8)
	s_waitcnt lgkmcnt(0)
	s_barrier
	s_waitcnt lgkmcnt(0)
	v_mfma_f32_16x16x32_bf16 v[60:63], v[132:135], v[198:201], v[60:63]
	v_mfma_f32_16x16x32_bf16 v[56:59], v[140:143], v[198:201], v[56:59]
	v_mfma_f32_16x16x32_bf16 v[44:47], v[132:135], v[206:209], v[44:47]
	v_mfma_f32_16x16x32_bf16 v[40:43], v[140:143], v[206:209], v[40:43]
	v_mfma_f32_16x16x32_bf16 v[28:31], v[132:135], v[218:221], v[28:31]
	v_mfma_f32_16x16x32_bf16 v[24:27], v[140:143], v[218:221], v[24:27]
	v_mfma_f32_16x16x32_bf16 v[12:15], v[132:135], v[226:229], v[12:15]
	v_mfma_f32_16x16x32_bf16 v[8:11], v[140:143], v[226:229], v[8:11]
	v_mfma_f32_16x16x32_bf16 v[60:63], v[136:139], v[202:205], v[60:63]
	v_mfma_f32_16x16x32_bf16 v[56:59], v[166:169], v[202:205], v[56:59]
	v_mfma_f32_16x16x32_bf16 v[44:47], v[136:139], v[214:217], v[44:47]
	v_mfma_f32_16x16x32_bf16 v[40:43], v[166:169], v[214:217], v[40:43]
	v_mfma_f32_16x16x32_bf16 v[28:31], v[136:139], v[222:225], v[28:31]
	v_mfma_f32_16x16x32_bf16 v[24:27], v[166:169], v[222:225], v[24:27]
	v_mfma_f32_16x16x32_bf16 v[12:15], v[136:139], v[230:233], v[12:15]
	v_mfma_f32_16x16x32_bf16 v[8:11], v[166:169], v[230:233], v[8:11]
	v_mfma_f32_16x16x32_bf16 v[52:55], v[170:173], v[198:201], v[52:55]
	v_mfma_f32_16x16x32_bf16 v[48:51], v[190:193], v[198:201], v[48:51]
	v_mfma_f32_16x16x32_bf16 v[36:39], v[170:173], v[206:209], v[36:39]
	v_mfma_f32_16x16x32_bf16 v[32:35], v[190:193], v[206:209], v[32:35]
	v_mfma_f32_16x16x32_bf16 v[20:23], v[170:173], v[218:221], v[20:23]
	v_mfma_f32_16x16x32_bf16 v[16:19], v[190:193], v[218:221], v[16:19]
	v_mfma_f32_16x16x32_bf16 v[4:7], v[170:173], v[226:229], v[4:7]
	v_mfma_f32_16x16x32_bf16 v[0:3], v[190:193], v[226:229], v[0:3]
	v_mfma_f32_16x16x32_bf16 v[52:55], v[178:181], v[202:205], v[52:55]
	v_mfma_f32_16x16x32_bf16 v[48:51], v[194:197], v[202:205], v[48:51]
	v_mfma_f32_16x16x32_bf16 v[36:39], v[178:181], v[214:217], v[36:39]
	v_mfma_f32_16x16x32_bf16 v[32:35], v[194:197], v[214:217], v[32:35]
	v_mfma_f32_16x16x32_bf16 v[20:23], v[178:181], v[222:225], v[20:23]
	v_mfma_f32_16x16x32_bf16 v[16:19], v[194:197], v[222:225], v[16:19]
	v_mfma_f32_16x16x32_bf16 v[4:7], v[178:181], v[230:233], v[4:7]
	v_mfma_f32_16x16x32_bf16 v[0:3], v[194:197], v[230:233], v[0:3]
	s_barrier
	s_add_i32 s33, 0, 0x18000
	s_add_i32 s81, 0, 0x1c000
	v_add_u32_e32 v166, s33, v130
	v_add_u32_e32 v189, s81, v130
	ds_read_b128 v[132:135], v166
	ds_read_b128 v[136:139], v166 offset:1024
	ds_read_b128 v[140:143], v166 offset:2048
	ds_read_b128 v[166:169], v166 offset:3072
	ds_read_b128 v[170:173], v189
	ds_read_b128 v[178:181], v189 offset:1024
	ds_read_b128 v[190:193], v189 offset:2048
	ds_read_b128 v[194:197], v189 offset:3072
	s_add_u32 s52, s52, 0x40000
	s_addc_u32 s53, s53, 0
	s_mov_b32 m0, s65
	v_lshl_add_u64 v[234:235], s[52:53], 0, v[144:145]
	ds_read_b128 v[198:201], v131 offset:32768
	ds_read_b128 v[202:205], v131 offset:33792
	ds_read_b128 v[206:209], v131 offset:34816
	ds_read_b128 v[214:217], v131 offset:35840
	ds_read_b128 v[218:221], v131 offset:36864
	ds_read_b128 v[222:225], v131 offset:37888
	ds_read_b128 v[226:229], v131 offset:38912
	ds_read_b128 v[230:233], v131 offset:39936
	global_load_lds_dwordx4 v[234:235], off
	v_lshl_add_u64 v[234:235], s[52:53], 0, v[148:149]
	s_mov_b32 m0, s68
	s_nop 0
	global_load_lds_dwordx4 v[234:235], off
	s_waitcnt vmcnt(8)
	s_waitcnt lgkmcnt(0)
	s_barrier
	s_waitcnt lgkmcnt(0)
	v_mfma_f32_16x16x32_bf16 v[124:127], v[132:135], v[198:201], v[124:127]
	v_mfma_f32_16x16x32_bf16 v[120:123], v[140:143], v[198:201], v[120:123]
	v_mfma_f32_16x16x32_bf16 v[116:119], v[132:135], v[206:209], v[116:119]
	v_mfma_f32_16x16x32_bf16 v[112:115], v[140:143], v[206:209], v[112:115]
	v_mfma_f32_16x16x32_bf16 v[96:99], v[132:135], v[218:221], v[96:99]
	v_mfma_f32_16x16x32_bf16 v[92:95], v[140:143], v[218:221], v[92:95]
	v_mfma_f32_16x16x32_bf16 v[88:91], v[132:135], v[226:229], v[88:91]
	v_mfma_f32_16x16x32_bf16 v[80:83], v[140:143], v[226:229], v[80:83]
	v_mfma_f32_16x16x32_bf16 v[124:127], v[136:139], v[202:205], v[124:127]
	v_mfma_f32_16x16x32_bf16 v[120:123], v[166:169], v[202:205], v[120:123]
	v_mfma_f32_16x16x32_bf16 v[116:119], v[136:139], v[214:217], v[116:119]
	v_mfma_f32_16x16x32_bf16 v[112:115], v[166:169], v[214:217], v[112:115]
	v_mfma_f32_16x16x32_bf16 v[96:99], v[136:139], v[222:225], v[96:99]
	v_mfma_f32_16x16x32_bf16 v[92:95], v[166:169], v[222:225], v[92:95]
	v_mfma_f32_16x16x32_bf16 v[88:91], v[136:139], v[230:233], v[88:91]
	v_mfma_f32_16x16x32_bf16 v[80:83], v[166:169], v[230:233], v[80:83]
	v_mfma_f32_16x16x32_bf16 v[108:111], v[170:173], v[198:201], v[108:111]
	v_mfma_f32_16x16x32_bf16 v[104:107], v[190:193], v[198:201], v[104:107]
	v_mfma_f32_16x16x32_bf16 v[100:103], v[170:173], v[206:209], v[100:103]
	v_mfma_f32_16x16x32_bf16 v[84:87], v[190:193], v[206:209], v[84:87]
	v_mfma_f32_16x16x32_bf16 v[76:79], v[170:173], v[218:221], v[76:79]
	v_mfma_f32_16x16x32_bf16 v[72:75], v[190:193], v[218:221], v[72:75]
	v_mfma_f32_16x16x32_bf16 v[68:71], v[170:173], v[226:229], v[68:71]
	v_mfma_f32_16x16x32_bf16 v[64:67], v[190:193], v[226:229], v[64:67]
	v_mfma_f32_16x16x32_bf16 v[108:111], v[178:181], v[202:205], v[108:111]
	v_mfma_f32_16x16x32_bf16 v[104:107], v[194:197], v[202:205], v[104:107]
	v_mfma_f32_16x16x32_bf16 v[100:103], v[178:181], v[214:217], v[100:103]
	v_mfma_f32_16x16x32_bf16 v[84:87], v[194:197], v[214:217], v[84:87]
	v_mfma_f32_16x16x32_bf16 v[76:79], v[178:181], v[222:225], v[76:79]
	v_mfma_f32_16x16x32_bf16 v[72:75], v[194:197], v[222:225], v[72:75]
	v_mfma_f32_16x16x32_bf16 v[68:71], v[178:181], v[230:233], v[68:71]
	v_mfma_f32_16x16x32_bf16 v[64:67], v[194:197], v[230:233], v[64:67]
	s_barrier
; #define PG8_WAIT_V(n) asm volatile("s_waitcnt vmcnt(" #n ")" ::: "memory")
; #define PG8_BAR __builtin_amdgcn_s_barrier()
; template <class Epi, class Sched, bool ALIGN_EPI, bool CONVA>
; DI void gemm_phase(LAS unsigned char* lds, const Gemm g, const Sched& S, const Epi& E) {
;     ...
;         for (int t = 0; t < nt; t += 2) {
;             const bool last = (t == nt - 2);
;             const char* a1 = cA + (size_t)(t + 1) * kstep;
;             const char* a2 = last ? nA : cA + (size_t)(t + 2) * kstep; const char* b2 = last ? nB : cB + (size_t)(t + 2) * kstep;
;             const char* a3 = a2 + kstep; const char* b3 = b2 + kstep;
;             PG8_KBODY(PG8_WAIT_V(8));
;         }
;     ...
;         if constexpr (ALIGN_EPI) { if (wr == 0) PG8_BAR; }
	s_add_i32 s52, s33, s62
	v_lshl_add_u64 v[128:129], v[128:129], 0, s[12:13]
	s_mov_b32 m0, s52
	ds_read_b128 v[198:201], v131 offset:49152
	ds_read_b128 v[202:205], v131 offset:50176
	ds_read_b128 v[206:209], v131 offset:51200
	ds_read_b128 v[214:217], v131 offset:52224
	ds_read_b128 v[218:221], v131 offset:53248
	ds_read_b128 v[222:225], v131 offset:54272
	ds_read_b128 v[226:229], v131 offset:55296
	ds_read_b128 v[230:233], v131 offset:56320
	global_load_lds_dwordx4 v[128:129], off
	s_add_i32 m0, s52, 0x2000
	s_add_u32 s50, s50, 0x40080
	v_lshl_add_u64 v[128:129], v[174:175], 0, s[12:13]
	s_addc_u32 s51, s51, 0
	s_add_i32 s52, s81, s62
	global_load_lds_dwordx4 v[128:129], off
	v_lshl_add_u64 v[128:129], s[50:51], 0, v[146:147]
	s_mov_b32 m0, s52
	s_nop 0
	global_load_lds_dwordx4 v[128:129], off
	v_lshl_add_u64 v[128:129], s[50:51], 0, v[150:151]
	s_add_i32 m0, s52, 0x2000
	s_nop 0
	global_load_lds_dwordx4 v[128:129], off
	v_lshl_add_u64 v[128:129], v[182:183], 0, s[12:13]
	s_mov_b32 m0, s69
	s_nop 0
	global_load_lds_dwordx4 v[128:129], off
	v_lshl_add_u64 v[128:129], v[210:211], 0, s[12:13]
	s_mov_b32 m0, s70
	s_nop 0
	global_load_lds_dwordx4 v[128:129], off
	s_waitcnt vmcnt(8)
	s_waitcnt lgkmcnt(0)
	s_barrier
	s_waitcnt lgkmcnt(0)
	v_mfma_f32_16x16x32_bf16 v[60:63], v[132:135], v[198:201], v[60:63]
	v_mfma_f32_16x16x32_bf16 v[56:59], v[140:143], v[198:201], v[56:59]
	v_mfma_f32_16x16x32_bf16 v[44:47], v[132:135], v[206:209], v[44:47]
	v_mfma_f32_16x16x32_bf16 v[40:43], v[140:143], v[206:209], v[40:43]
	v_mfma_f32_16x16x32_bf16 v[28:31], v[132:135], v[218:221], v[28:31]
	v_mfma_f32_16x16x32_bf16 v[24:27], v[140:143], v[218:221], v[24:27]
	v_mfma_f32_16x16x32_bf16 v[12:15], v[132:135], v[226:229], v[12:15]
	v_mfma_f32_16x16x32_bf16 v[8:11], v[140:143], v[226:229], v[8:11]
	v_mfma_f32_16x16x32_bf16 v[60:63], v[136:139], v[202:205], v[60:63]
	v_mfma_f32_16x16x32_bf16 v[56:59], v[166:169], v[202:205], v[56:59]
	v_mfma_f32_16x16x32_bf16 v[44:47], v[136:139], v[214:217], v[44:47]
	v_mfma_f32_16x16x32_bf16 v[40:43], v[166:169], v[214:217], v[40:43]
	v_mfma_f32_16x16x32_bf16 v[28:31], v[136:139], v[222:225], v[28:31]
	v_mfma_f32_16x16x32_bf16 v[24:27], v[166:169], v[222:225], v[24:27]
	v_mfma_f32_16x16x32_bf16 v[12:15], v[136:139], v[230:233], v[12:15]
	v_mfma_f32_16x16x32_bf16 v[8:11], v[166:169], v[230:233], v[8:11]
	v_mfma_f32_16x16x32_bf16 v[52:55], v[170:173], v[198:201], v[52:55]
	v_mfma_f32_16x16x32_bf16 v[48:51], v[190:193], v[198:201], v[48:51]
	v_mfma_f32_16x16x32_bf16 v[36:39], v[170:173], v[206:209], v[36:39]
	v_mfma_f32_16x16x32_bf16 v[32:35], v[190:193], v[206:209], v[32:35]
	v_mfma_f32_16x16x32_bf16 v[20:23], v[170:173], v[218:221], v[20:23]
	v_mfma_f32_16x16x32_bf16 v[16:19], v[190:193], v[218:221], v[16:19]
	v_mfma_f32_16x16x32_bf16 v[4:7], v[170:173], v[226:229], v[4:7]
	v_mfma_f32_16x16x32_bf16 v[0:3], v[190:193], v[226:229], v[0:3]
	v_mfma_f32_16x16x32_bf16 v[52:55], v[178:181], v[202:205], v[52:55]
	v_mfma_f32_16x16x32_bf16 v[48:51], v[194:197], v[202:205], v[48:51]
	v_mfma_f32_16x16x32_bf16 v[36:39], v[178:181], v[214:217], v[36:39]
	v_mfma_f32_16x16x32_bf16 v[32:35], v[194:197], v[214:217], v[32:35]
	v_mfma_f32_16x16x32_bf16 v[20:23], v[178:181], v[222:225], v[20:23]
	v_mfma_f32_16x16x32_bf16 v[16:19], v[194:197], v[222:225], v[16:19]
	v_mfma_f32_16x16x32_bf16 v[4:7], v[178:181], v[230:233], v[4:7]
	v_mfma_f32_16x16x32_bf16 v[0:3], v[194:197], v[230:233], v[0:3]
	s_barrier
	s_add_i32 s86, s86, 2
	s_add_u32 s46, s46, 0x100
	s_addc_u32 s47, s47, 0
	s_add_u32 s84, s84, 0x100
	s_addc_u32 s85, s85, 0
	s_cmp_gt_u32 s86, 13
	s_cbranch_scc0 .LBB0_533
	s_and_b64 vcc, exec, s[40:41]
	s_cbranch_vccz .LBB0_536
	s_barrier

.LBB0_549:
	v_add_u32_e32 v140, s17, v189
	v_add_u32_e32 v191, s19, v189
	ds_read_b128 v[128:131], v140
	ds_read_b128 v[132:135], v140 offset:1024
	ds_read_b128 v[136:139], v140 offset:2048
	ds_read_b128 v[140:143], v140 offset:3072
	ds_read_b128 v[192:195], v191
	ds_read_b128 v[196:199], v191 offset:1024
	ds_read_b128 v[200:203], v191 offset:2048
	ds_read_b128 v[204:207], v191 offset:3072
	s_add_u32 s46, s44, 0xfffc0080
	s_addc_u32 s47, s45, -1
	s_cmp_eq_u32 s80, 4
	s_cselect_b32 s49, s6, s47
	s_cselect_b32 s48, s65, s46
	s_cselect_b32 s47, s68, s71
	s_cselect_b32 s46, s69, s70
	v_lshl_add_u64 v[242:243], s[44:45], 0, v[158:159]
	s_add_i32 m0, s51, 0xc000
	ds_read_b128 v[208:211], v190
	ds_read_b128 v[214:217], v190 offset:1024
	ds_read_b128 v[218:221], v190 offset:2048
	ds_read_b128 v[222:225], v190 offset:3072
	ds_read_b128 v[226:229], v190 offset:4096
	ds_read_b128 v[230:233], v190 offset:5120
	ds_read_b128 v[234:237], v190 offset:6144
	ds_read_b128 v[238:241], v190 offset:7168
	global_load_lds_dwordx4 v[242:243], off
	v_lshl_add_u64 v[242:243], s[44:45], 0, v[160:161]
	s_add_i32 m0, s51, 0xe000
	s_nop 0
	global_load_lds_dwordx4 v[242:243], off
	s_waitcnt vmcnt(8)
	s_waitcnt lgkmcnt(0)
	s_barrier
	s_waitcnt lgkmcnt(0)
	v_mfma_f32_16x16x32_bf16 v[124:127], v[128:131], v[208:211], v[124:127]
	v_mfma_f32_16x16x32_bf16 v[120:123], v[136:139], v[208:211], v[120:123]
	v_mfma_f32_16x16x32_bf16 v[116:119], v[128:131], v[218:221], v[116:119]
	v_mfma_f32_16x16x32_bf16 v[112:115], v[136:139], v[218:221], v[112:115]
	v_mfma_f32_16x16x32_bf16 v[108:111], v[128:131], v[226:229], v[108:111]
	v_mfma_f32_16x16x32_bf16 v[104:107], v[136:139], v[226:229], v[104:107]
	v_mfma_f32_16x16x32_bf16 v[100:103], v[128:131], v[234:237], v[100:103]
	v_mfma_f32_16x16x32_bf16 v[96:99], v[136:139], v[234:237], v[96:99]
	v_mfma_f32_16x16x32_bf16 v[124:127], v[132:135], v[214:217], v[124:127]
	v_mfma_f32_16x16x32_bf16 v[120:123], v[140:143], v[214:217], v[120:123]
	v_mfma_f32_16x16x32_bf16 v[116:119], v[132:135], v[222:225], v[116:119]
	v_mfma_f32_16x16x32_bf16 v[112:115], v[140:143], v[222:225], v[112:115]
	v_mfma_f32_16x16x32_bf16 v[108:111], v[132:135], v[230:233], v[108:111]
	v_mfma_f32_16x16x32_bf16 v[104:107], v[140:143], v[230:233], v[104:107]
	v_mfma_f32_16x16x32_bf16 v[100:103], v[132:135], v[238:241], v[100:103]
	v_mfma_f32_16x16x32_bf16 v[96:99], v[140:143], v[238:241], v[96:99]
	v_mfma_f32_16x16x32_bf16 v[92:95], v[192:195], v[208:211], v[92:95]
	v_mfma_f32_16x16x32_bf16 v[88:91], v[200:203], v[208:211], v[88:91]
	v_mfma_f32_16x16x32_bf16 v[84:87], v[192:195], v[218:221], v[84:87]
	v_mfma_f32_16x16x32_bf16 v[80:83], v[200:203], v[218:221], v[80:83]
	v_mfma_f32_16x16x32_bf16 v[76:79], v[192:195], v[226:229], v[76:79]
	v_mfma_f32_16x16x32_bf16 v[72:75], v[200:203], v[226:229], v[72:75]
	v_mfma_f32_16x16x32_bf16 v[68:71], v[192:195], v[234:237], v[68:71]
	v_mfma_f32_16x16x32_bf16 v[64:67], v[200:203], v[234:237], v[64:67]
	v_mfma_f32_16x16x32_bf16 v[92:95], v[196:199], v[214:217], v[92:95]
	v_mfma_f32_16x16x32_bf16 v[88:91], v[204:207], v[214:217], v[88:91]
	v_mfma_f32_16x16x32_bf16 v[84:87], v[196:199], v[222:225], v[84:87]
	v_mfma_f32_16x16x32_bf16 v[80:83], v[204:207], v[222:225], v[80:83]
	v_mfma_f32_16x16x32_bf16 v[76:79], v[196:199], v[230:233], v[76:79]
	v_mfma_f32_16x16x32_bf16 v[72:75], v[204:207], v[230:233], v[72:75]
	v_mfma_f32_16x16x32_bf16 v[68:71], v[196:199], v[238:241], v[68:71]
	v_mfma_f32_16x16x32_bf16 v[64:67], v[204:207], v[238:241], v[64:67]
	s_barrier
	s_add_i32 s83, s17, s50
	v_lshl_add_u64 v[242:243], s[46:47], 0, v[146:147]
	s_mov_b32 m0, s83
	ds_read_b128 v[208:211], v190 offset:16384
	ds_read_b128 v[214:217], v190 offset:17408
	ds_read_b128 v[218:221], v190 offset:18432
	ds_read_b128 v[222:225], v190 offset:19456
	ds_read_b128 v[226:229], v190 offset:20480
	ds_read_b128 v[230:233], v190 offset:21504
	ds_read_b128 v[234:237], v190 offset:22528
	ds_read_b128 v[238:241], v190 offset:23552
	global_load_lds_dwordx4 v[242:243], off
	s_add_i32 m0, s83, 0x2000
	s_add_u32 s84, s46, 0x40000
	v_lshl_add_u64 v[244:245], s[46:47], 0, v[150:151]
	s_addc_u32 s85, s47, 0
	s_add_i32 s83, s19, s50
	global_load_lds_dwordx4 v[244:245], off
	v_lshl_add_u64 v[246:247], s[84:85], 0, v[146:147]
	s_mov_b32 m0, s83
	v_lshl_add_u64 v[248:249], s[48:49], 0, v[148:149]
	global_load_lds_dwordx4 v[246:247], off
	v_lshl_add_u64 v[246:247], s[84:85], 0, v[150:151]
	s_add_i32 m0, s83, 0x2000
	s_nop 0
	global_load_lds_dwordx4 v[246:247], off
	v_lshl_add_u64 v[246:247], s[48:49], 0, v[144:145]
	s_mov_b32 m0, s51
	s_nop 0
	global_load_lds_dwordx4 v[246:247], off
	s_mov_b32 m0, s52
	s_nop 0
	global_load_lds_dwordx4 v[248:249], off
	s_waitcnt vmcnt(8)
	s_waitcnt lgkmcnt(0)
	s_barrier
	s_waitcnt lgkmcnt(0)
	v_mfma_f32_16x16x32_bf16 v[60:63], v[128:131], v[208:211], v[60:63]
	v_mfma_f32_16x16x32_bf16 v[56:59], v[136:139], v[208:211], v[56:59]
	v_mfma_f32_16x16x32_bf16 v[52:55], v[128:131], v[218:221], v[52:55]
	v_mfma_f32_16x16x32_bf16 v[48:51], v[136:139], v[218:221], v[48:51]
	v_mfma_f32_16x16x32_bf16 v[44:47], v[128:131], v[226:229], v[44:47]
	v_mfma_f32_16x16x32_bf16 v[40:43], v[136:139], v[226:229], v[40:43]
	v_mfma_f32_16x16x32_bf16 v[36:39], v[128:131], v[234:237], v[36:39]
	v_mfma_f32_16x16x32_bf16 v[32:35], v[136:139], v[234:237], v[32:35]
	v_mfma_f32_16x16x32_bf16 v[60:63], v[132:135], v[214:217], v[60:63]
	v_mfma_f32_16x16x32_bf16 v[56:59], v[140:143], v[214:217], v[56:59]
	v_mfma_f32_16x16x32_bf16 v[52:55], v[132:135], v[222:225], v[52:55]
	v_mfma_f32_16x16x32_bf16 v[48:51], v[140:143], v[222:225], v[48:51]
	v_mfma_f32_16x16x32_bf16 v[44:47], v[132:135], v[230:233], v[44:47]
	v_mfma_f32_16x16x32_bf16 v[40:43], v[140:143], v[230:233], v[40:43]
	v_mfma_f32_16x16x32_bf16 v[36:39], v[132:135], v[238:241], v[36:39]
	v_mfma_f32_16x16x32_bf16 v[32:35], v[140:143], v[238:241], v[32:35]
	v_mfma_f32_16x16x32_bf16 v[28:31], v[192:195], v[208:211], v[28:31]
	v_mfma_f32_16x16x32_bf16 v[24:27], v[200:203], v[208:211], v[24:27]
	v_mfma_f32_16x16x32_bf16 v[20:23], v[192:195], v[218:221], v[20:23]
	v_mfma_f32_16x16x32_bf16 v[16:19], v[200:203], v[218:221], v[16:19]
	v_mfma_f32_16x16x32_bf16 v[12:15], v[192:195], v[226:229], v[12:15]
	v_mfma_f32_16x16x32_bf16 v[8:11], v[200:203], v[226:229], v[8:11]
	v_mfma_f32_16x16x32_bf16 v[4:7], v[192:195], v[234:237], v[4:7]
	v_mfma_f32_16x16x32_bf16 v[0:3], v[200:203], v[234:237], v[0:3]
	v_mfma_f32_16x16x32_bf16 v[28:31], v[196:199], v[214:217], v[28:31]
	v_mfma_f32_16x16x32_bf16 v[24:27], v[204:207], v[214:217], v[24:27]
	v_mfma_f32_16x16x32_bf16 v[20:23], v[196:199], v[222:225], v[20:23]
	v_mfma_f32_16x16x32_bf16 v[16:19], v[204:207], v[222:225], v[16:19]
	v_mfma_f32_16x16x32_bf16 v[12:15], v[196:199], v[230:233], v[12:15]
	v_mfma_f32_16x16x32_bf16 v[8:11], v[204:207], v[230:233], v[8:11]
	v_mfma_f32_16x16x32_bf16 v[4:7], v[196:199], v[238:241], v[4:7]
	v_mfma_f32_16x16x32_bf16 v[0:3], v[204:207], v[238:241], v[0:3]
	s_barrier
	v_add_u32_e32 v140, s33, v189
	v_add_u32_e32 v191, s81, v189
	ds_read_b128 v[128:131], v140
	ds_read_b128 v[132:135], v140 offset:1024
	ds_read_b128 v[136:139], v140 offset:2048
	ds_read_b128 v[140:143], v140 offset:3072
	ds_read_b128 v[192:195], v191
	ds_read_b128 v[196:199], v191 offset:1024
	ds_read_b128 v[200:203], v191 offset:2048
	ds_read_b128 v[204:207], v191 offset:3072
	s_add_u32 s48, s48, 0x40000
	s_addc_u32 s49, s49, 0
	s_mov_b32 m0, s53
	v_lshl_add_u64 v[250:251], s[48:49], 0, v[144:145]
	ds_read_b128 v[208:211], v190 offset:32768
	ds_read_b128 v[214:217], v190 offset:33792
	ds_read_b128 v[218:221], v190 offset:34816
	ds_read_b128 v[222:225], v190 offset:35840
	ds_read_b128 v[226:229], v190 offset:36864
	ds_read_b128 v[230:233], v190 offset:37888
	ds_read_b128 v[234:237], v190 offset:38912
	ds_read_b128 v[238:241], v190 offset:39936
	global_load_lds_dwordx4 v[250:251], off
	v_lshl_add_u64 v[250:251], s[48:49], 0, v[148:149]
	s_mov_b32 m0, s62
	s_nop 0
	global_load_lds_dwordx4 v[250:251], off
	s_waitcnt vmcnt(8)
	s_waitcnt lgkmcnt(0)
	s_barrier
	s_waitcnt lgkmcnt(0)
	v_mfma_f32_16x16x32_bf16 v[124:127], v[128:131], v[208:211], v[124:127]
	v_mfma_f32_16x16x32_bf16 v[120:123], v[136:139], v[208:211], v[120:123]
	v_mfma_f32_16x16x32_bf16 v[116:119], v[128:131], v[218:221], v[116:119]
	v_mfma_f32_16x16x32_bf16 v[112:115], v[136:139], v[218:221], v[112:115]
	v_mfma_f32_16x16x32_bf16 v[108:111], v[128:131], v[226:229], v[108:111]
	v_mfma_f32_16x16x32_bf16 v[104:107], v[136:139], v[226:229], v[104:107]
	v_mfma_f32_16x16x32_bf16 v[100:103], v[128:131], v[234:237], v[100:103]
	v_mfma_f32_16x16x32_bf16 v[96:99], v[136:139], v[234:237], v[96:99]
	v_mfma_f32_16x16x32_bf16 v[124:127], v[132:135], v[214:217], v[124:127]
	v_mfma_f32_16x16x32_bf16 v[120:123], v[140:143], v[214:217], v[120:123]
	v_mfma_f32_16x16x32_bf16 v[116:119], v[132:135], v[222:225], v[116:119]
	v_mfma_f32_16x16x32_bf16 v[112:115], v[140:143], v[222:225], v[112:115]
	v_mfma_f32_16x16x32_bf16 v[108:111], v[132:135], v[230:233], v[108:111]
	v_mfma_f32_16x16x32_bf16 v[104:107], v[140:143], v[230:233], v[104:107]
	v_mfma_f32_16x16x32_bf16 v[100:103], v[132:135], v[238:241], v[100:103]
	v_mfma_f32_16x16x32_bf16 v[96:99], v[140:143], v[238:241], v[96:99]
	v_mfma_f32_16x16x32_bf16 v[92:95], v[192:195], v[208:211], v[92:95]
	v_mfma_f32_16x16x32_bf16 v[88:91], v[200:203], v[208:211], v[88:91]
	v_mfma_f32_16x16x32_bf16 v[84:87], v[192:195], v[218:221], v[84:87]
	v_mfma_f32_16x16x32_bf16 v[80:83], v[200:203], v[218:221], v[80:83]
	v_mfma_f32_16x16x32_bf16 v[76:79], v[192:195], v[226:229], v[76:79]
	v_mfma_f32_16x16x32_bf16 v[72:75], v[200:203], v[226:229], v[72:75]
	v_mfma_f32_16x16x32_bf16 v[68:71], v[192:195], v[234:237], v[68:71]
	v_mfma_f32_16x16x32_bf16 v[64:67], v[200:203], v[234:237], v[64:67]
	v_mfma_f32_16x16x32_bf16 v[92:95], v[196:199], v[214:217], v[92:95]
	v_mfma_f32_16x16x32_bf16 v[88:91], v[204:207], v[214:217], v[88:91]
	v_mfma_f32_16x16x32_bf16 v[84:87], v[196:199], v[222:225], v[84:87]
	v_mfma_f32_16x16x32_bf16 v[80:83], v[204:207], v[222:225], v[80:83]
	v_mfma_f32_16x16x32_bf16 v[76:79], v[196:199], v[230:233], v[76:79]
	v_mfma_f32_16x16x32_bf16 v[72:75], v[204:207], v[230:233], v[72:75]
	v_mfma_f32_16x16x32_bf16 v[68:71], v[196:199], v[238:241], v[68:71]
	v_mfma_f32_16x16x32_bf16 v[64:67], v[204:207], v[238:241], v[64:67]
	s_barrier
; #define PG8_WAIT_V(n) asm volatile("s_waitcnt vmcnt(" #n ")" ::: "memory")
; template <class Epi, class Sched, bool ALIGN_EPI, bool CONVA>
; DI void gemm_phase(LAS unsigned char* lds, const Gemm g, const Sched& S, const Epi& E) {
;     ...
;         for (int t = 0; t < nt; t += 2) {
;             const bool last = (t == nt - 2);
;             const char* a1 = cA + (size_t)(t + 1) * kstep;
;             const char* a2 = last ? nA : cA + (size_t)(t + 2) * kstep; const char* b2 = last ? nB : cB + (size_t)(t + 2) * kstep;
;             const char* a3 = a2 + kstep; const char* b3 = b2 + kstep;
;             PG8_KBODY(PG8_WAIT_V(8));
;         }
	s_add_i32 s48, s33, s50
	v_lshl_add_u64 v[242:243], v[242:243], 0, s[12:13]
	s_mov_b32 m0, s48
	ds_read_b128 v[208:211], v190 offset:49152
	ds_read_b128 v[214:217], v190 offset:50176
	ds_read_b128 v[218:221], v190 offset:51200
	ds_read_b128 v[222:225], v190 offset:52224
	ds_read_b128 v[226:229], v190 offset:53248
	ds_read_b128 v[230:233], v190 offset:54272
	ds_read_b128 v[234:237], v190 offset:55296
	ds_read_b128 v[238:241], v190 offset:56320
	global_load_lds_dwordx4 v[242:243], off
	s_add_i32 m0, s48, 0x2000
	s_add_u32 s46, s46, 0x40080
	v_lshl_add_u64 v[242:243], v[244:245], 0, s[12:13]
	s_addc_u32 s47, s47, 0
	s_add_i32 s48, s81, s50
	global_load_lds_dwordx4 v[242:243], off
	v_lshl_add_u64 v[242:243], s[46:47], 0, v[146:147]
	s_mov_b32 m0, s48
	s_nop 0
	global_load_lds_dwordx4 v[242:243], off
	v_lshl_add_u64 v[242:243], s[46:47], 0, v[150:151]
	s_add_i32 m0, s48, 0x2000
	s_nop 0
	global_load_lds_dwordx4 v[242:243], off
	v_lshl_add_u64 v[242:243], v[246:247], 0, s[12:13]
	s_mov_b32 m0, s63
	s_nop 0
	global_load_lds_dwordx4 v[242:243], off
	v_lshl_add_u64 v[242:243], v[248:249], 0, s[12:13]
	s_mov_b32 m0, s64
	s_nop 0
	global_load_lds_dwordx4 v[242:243], off
	s_waitcnt vmcnt(8)
	s_waitcnt lgkmcnt(0)
	s_barrier
	s_waitcnt lgkmcnt(0)
	v_mfma_f32_16x16x32_bf16 v[60:63], v[128:131], v[208:211], v[60:63]
	v_mfma_f32_16x16x32_bf16 v[56:59], v[136:139], v[208:211], v[56:59]
	v_mfma_f32_16x16x32_bf16 v[52:55], v[128:131], v[218:221], v[52:55]
	v_mfma_f32_16x16x32_bf16 v[48:51], v[136:139], v[218:221], v[48:51]
	v_mfma_f32_16x16x32_bf16 v[44:47], v[128:131], v[226:229], v[44:47]
	v_mfma_f32_16x16x32_bf16 v[40:43], v[136:139], v[226:229], v[40:43]
	v_mfma_f32_16x16x32_bf16 v[36:39], v[128:131], v[234:237], v[36:39]
	v_mfma_f32_16x16x32_bf16 v[32:35], v[136:139], v[234:237], v[32:35]
	v_mfma_f32_16x16x32_bf16 v[60:63], v[132:135], v[214:217], v[60:63]
	v_mfma_f32_16x16x32_bf16 v[56:59], v[140:143], v[214:217], v[56:59]
	v_mfma_f32_16x16x32_bf16 v[52:55], v[132:135], v[222:225], v[52:55]
	v_mfma_f32_16x16x32_bf16 v[48:51], v[140:143], v[222:225], v[48:51]
	v_mfma_f32_16x16x32_bf16 v[44:47], v[132:135], v[230:233], v[44:47]
	v_mfma_f32_16x16x32_bf16 v[40:43], v[140:143], v[230:233], v[40:43]
	v_mfma_f32_16x16x32_bf16 v[36:39], v[132:135], v[238:241], v[36:39]
	v_mfma_f32_16x16x32_bf16 v[32:35], v[140:143], v[238:241], v[32:35]
	v_mfma_f32_16x16x32_bf16 v[28:31], v[192:195], v[208:211], v[28:31]
	v_mfma_f32_16x16x32_bf16 v[24:27], v[200:203], v[208:211], v[24:27]
	v_mfma_f32_16x16x32_bf16 v[20:23], v[192:195], v[218:221], v[20:23]
	v_mfma_f32_16x16x32_bf16 v[16:19], v[200:203], v[218:221], v[16:19]
	v_mfma_f32_16x16x32_bf16 v[12:15], v[192:195], v[226:229], v[12:15]
	v_mfma_f32_16x16x32_bf16 v[8:11], v[200:203], v[226:229], v[8:11]
	v_mfma_f32_16x16x32_bf16 v[4:7], v[192:195], v[234:237], v[4:7]
	v_mfma_f32_16x16x32_bf16 v[0:3], v[200:203], v[234:237], v[0:3]
	v_mfma_f32_16x16x32_bf16 v[28:31], v[196:199], v[214:217], v[28:31]
	v_mfma_f32_16x16x32_bf16 v[24:27], v[204:207], v[214:217], v[24:27]
	v_mfma_f32_16x16x32_bf16 v[20:23], v[196:199], v[222:225], v[20:23]
	v_mfma_f32_16x16x32_bf16 v[16:19], v[204:207], v[222:225], v[16:19]
	v_mfma_f32_16x16x32_bf16 v[12:15], v[196:199], v[230:233], v[12:15]
	v_mfma_f32_16x16x32_bf16 v[8:11], v[204:207], v[230:233], v[8:11]
	v_mfma_f32_16x16x32_bf16 v[4:7], v[196:199], v[238:241], v[4:7]
	v_mfma_f32_16x16x32_bf16 v[0:3], v[204:207], v[238:241], v[0:3]
	s_barrier
	s_add_i32 s80, s80, 2
	s_add_u32 s44, s44, 0x100
	s_addc_u32 s45, s45, 0
	s_add_u32 s70, s70, 0x100
	s_addc_u32 s71, s71, 0
	s_cmp_gt_u32 s80, 5
	s_cbranch_scc0 .LBB0_549
	s_and_b64 vcc, exec, s[40:41]
	s_cbranch_vccz .LBB0_552
	s_barrier

;     DI bool next(int i, Unit& u) const { if (!s.next(i >> 1, u)) return false; u.sel = i & 1; return true; }
; template <class Epi, class Sched, bool ALIGN_EPI, bool CONVA>
; DI void gemm_phase(LAS unsigned char* lds, const Gemm g, const Sched& S, const Epi& E) {
;     ...
;         const bool has_next = S.next(ui + 1, nxt);
;         const char* nA = has_next ? (const char*)(nxt.sel ? g.A2 : g.A) + (size_t)nxt.pm * tstepA + abias : cA;
;         const char* nB = has_next ? (const char*)(nxt.sel ? g.Bt2 : g.Bt) + (size_t)nxt.pn * tstepB : cB;
.LBB0_583:
	s_ashr_i32 s25, s24, 31
	s_lshl_b64 s[26:27], s[24:25], 19
	s_add_u32 s26, s33, s26
	s_addc_u32 s27, s42, s27
	s_and_b64 s[28:29], s[2:3], exec
	s_cselect_b32 s25, s27, s31
	s_cselect_b32 s57, s26, s30
	s_ashr_i32 s21, s20, 31
	s_lshl_b64 s[28:29], s[20:21], 19
	s_add_u32 s28, s22, s28
	s_addc_u32 s29, s23, s29
	s_and_b64 s[40:41], s[2:3], exec
	s_cselect_b32 s21, s29, s35
	s_cselect_b32 s58, s28, s34
	s_add_u32 s30, s30, 0x40080
	s_addc_u32 s31, s31, 0
	s_add_u32 s59, s34, 0x100
	s_addc_u32 s60, s35, 0
	s_mov_b32 s61, -2
	s_waitcnt lgkmcnt(0)
	ds_read_b128 v[128:131], v216
	ds_read_b128 v[132:135], v216 offset:1024
	ds_read_b128 v[136:139], v216 offset:2048
	ds_read_b128 v[140:143], v216 offset:3072
	ds_read_b128 v[144:147], v217
	ds_read_b128 v[148:151], v217 offset:1024
	ds_read_b128 v[152:155], v217 offset:2048
	ds_read_b128 v[156:159], v217 offset:3072
	s_add_u32 s34, s30, 0xfffc0080
	s_addc_u32 s35, s31, -1
	s_cmp_eq_u32 s61, 12
	s_cselect_b32 s41, s25, s35
	s_cselect_b32 s40, s57, s34
	s_cselect_b32 s35, s21, s60
	s_cselect_b32 s34, s58, s59
	v_lshl_add_u64 v[224:225], s[30:31], 0, v[186:187]
	s_add_i32 m0, s7, 0xc000
	ds_read_b128 v[160:163], v218
	ds_read_b128 v[164:167], v218 offset:1024
	ds_read_b128 v[168:171], v218 offset:2048
	ds_read_b128 v[172:175], v218 offset:3072
	ds_read_b128 v[194:197], v218 offset:4096
	ds_read_b128 v[198:201], v218 offset:5120
	ds_read_b128 v[202:205], v218 offset:6144
	ds_read_b128 v[220:223], v218 offset:7168
	global_load_lds_dwordx4 v[224:225], off
	v_lshl_add_u64 v[224:225], s[30:31], 0, v[188:189]
	s_add_i32 m0, s7, 0xe000
	s_nop 0
	global_load_lds_dwordx4 v[224:225], off
	s_waitcnt vmcnt(8)
	s_waitcnt lgkmcnt(0)
	s_barrier
	s_waitcnt lgkmcnt(0)
	v_mfma_f32_16x16x32_bf16 v[124:127], v[128:131], v[160:163], 0
	v_mfma_f32_16x16x32_bf16 v[120:123], v[136:139], v[160:163], 0
	v_mfma_f32_16x16x32_bf16 v[108:111], v[128:131], v[168:171], 0
	v_mfma_f32_16x16x32_bf16 v[104:107], v[136:139], v[168:171], 0
	v_mfma_f32_16x16x32_bf16 v[92:95], v[128:131], v[194:197], 0
	v_mfma_f32_16x16x32_bf16 v[88:91], v[136:139], v[194:197], 0
	v_mfma_f32_16x16x32_bf16 v[76:79], v[128:131], v[202:205], 0
	v_mfma_f32_16x16x32_bf16 v[72:75], v[136:139], v[202:205], 0
	v_mfma_f32_16x16x32_bf16 v[124:127], v[132:135], v[164:167], v[124:127]
	v_mfma_f32_16x16x32_bf16 v[120:123], v[140:143], v[164:167], v[120:123]
	v_mfma_f32_16x16x32_bf16 v[108:111], v[132:135], v[172:175], v[108:111]
	v_mfma_f32_16x16x32_bf16 v[104:107], v[140:143], v[172:175], v[104:107]
	v_mfma_f32_16x16x32_bf16 v[92:95], v[132:135], v[198:201], v[92:95]
	v_mfma_f32_16x16x32_bf16 v[88:91], v[140:143], v[198:201], v[88:91]
	v_mfma_f32_16x16x32_bf16 v[76:79], v[132:135], v[220:223], v[76:79]
	v_mfma_f32_16x16x32_bf16 v[72:75], v[140:143], v[220:223], v[72:75]
	v_mfma_f32_16x16x32_bf16 v[116:119], v[144:147], v[160:163], 0
	v_mfma_f32_16x16x32_bf16 v[112:115], v[152:155], v[160:163], 0
	v_mfma_f32_16x16x32_bf16 v[100:103], v[144:147], v[168:171], 0
	v_mfma_f32_16x16x32_bf16 v[96:99], v[152:155], v[168:171], 0
	v_mfma_f32_16x16x32_bf16 v[84:87], v[144:147], v[194:197], 0
	v_mfma_f32_16x16x32_bf16 v[80:83], v[152:155], v[194:197], 0
	v_mfma_f32_16x16x32_bf16 v[68:71], v[144:147], v[202:205], 0
	v_mfma_f32_16x16x32_bf16 v[64:67], v[152:155], v[202:205], 0
	v_mfma_f32_16x16x32_bf16 v[116:119], v[148:151], v[164:167], v[116:119]
	v_mfma_f32_16x16x32_bf16 v[112:115], v[156:159], v[164:167], v[112:115]
	v_mfma_f32_16x16x32_bf16 v[100:103], v[148:151], v[172:175], v[100:103]
	v_mfma_f32_16x16x32_bf16 v[96:99], v[156:159], v[172:175], v[96:99]
	v_mfma_f32_16x16x32_bf16 v[84:87], v[148:151], v[198:201], v[84:87]
	v_mfma_f32_16x16x32_bf16 v[80:83], v[156:159], v[198:201], v[80:83]
	v_mfma_f32_16x16x32_bf16 v[68:71], v[148:151], v[220:223], v[68:71]
	v_mfma_f32_16x16x32_bf16 v[64:67], v[156:159], v[220:223], v[64:67]
	s_barrier
	s_add_i32 s62, s54, s43
	v_lshl_add_u64 v[224:225], s[34:35], 0, v[180:181]
	s_mov_b32 m0, s62
	ds_read_b128 v[160:163], v218 offset:16384
	ds_read_b128 v[164:167], v218 offset:17408
	ds_read_b128 v[168:171], v218 offset:18432
	ds_read_b128 v[172:175], v218 offset:19456
	ds_read_b128 v[194:197], v218 offset:20480
	ds_read_b128 v[198:201], v218 offset:21504
	ds_read_b128 v[202:205], v218 offset:22528
	ds_read_b128 v[220:223], v218 offset:23552
	global_load_lds_dwordx4 v[224:225], off
	s_add_i32 m0, s62, 0x2000
	s_add_u32 s62, s34, 0x40000
	v_lshl_add_u64 v[226:227], s[34:35], 0, v[184:185]
	s_addc_u32 s63, s35, 0
	s_add_i32 s64, s55, s43
	global_load_lds_dwordx4 v[226:227], off
	v_lshl_add_u64 v[228:229], s[62:63], 0, v[180:181]
	s_mov_b32 m0, s64
	v_lshl_add_u64 v[230:231], s[40:41], 0, v[182:183]
	global_load_lds_dwordx4 v[228:229], off
	v_lshl_add_u64 v[228:229], s[62:63], 0, v[184:185]
	s_add_i32 m0, s64, 0x2000
	s_nop 0
	global_load_lds_dwordx4 v[228:229], off
	v_lshl_add_u64 v[228:229], s[40:41], 0, v[178:179]
	s_mov_b32 m0, s7
	s_nop 0
	global_load_lds_dwordx4 v[228:229], off
	s_mov_b32 m0, s44
	s_nop 0
	global_load_lds_dwordx4 v[230:231], off
	s_waitcnt vmcnt(8)
	s_waitcnt lgkmcnt(0)
	s_barrier
	s_waitcnt lgkmcnt(0)
	v_mfma_f32_16x16x32_bf16 v[60:63], v[128:131], v[160:163], 0
	v_mfma_f32_16x16x32_bf16 v[56:59], v[136:139], v[160:163], 0
	v_mfma_f32_16x16x32_bf16 v[44:47], v[128:131], v[168:171], 0
	v_mfma_f32_16x16x32_bf16 v[40:43], v[136:139], v[168:171], 0
	v_mfma_f32_16x16x32_bf16 v[28:31], v[128:131], v[194:197], 0
	v_mfma_f32_16x16x32_bf16 v[24:27], v[136:139], v[194:197], 0
	v_mfma_f32_16x16x32_bf16 v[12:15], v[128:131], v[202:205], 0
	v_mfma_f32_16x16x32_bf16 v[8:11], v[136:139], v[202:205], 0
	v_mfma_f32_16x16x32_bf16 v[60:63], v[132:135], v[164:167], v[60:63]
	v_mfma_f32_16x16x32_bf16 v[56:59], v[140:143], v[164:167], v[56:59]
	v_mfma_f32_16x16x32_bf16 v[44:47], v[132:135], v[172:175], v[44:47]
	v_mfma_f32_16x16x32_bf16 v[40:43], v[140:143], v[172:175], v[40:43]
	v_mfma_f32_16x16x32_bf16 v[28:31], v[132:135], v[198:201], v[28:31]
	v_mfma_f32_16x16x32_bf16 v[24:27], v[140:143], v[198:201], v[24:27]
	v_mfma_f32_16x16x32_bf16 v[12:15], v[132:135], v[220:223], v[12:15]
	v_mfma_f32_16x16x32_bf16 v[8:11], v[140:143], v[220:223], v[8:11]
	v_mfma_f32_16x16x32_bf16 v[52:55], v[144:147], v[160:163], 0
	v_mfma_f32_16x16x32_bf16 v[48:51], v[152:155], v[160:163], 0
	v_mfma_f32_16x16x32_bf16 v[36:39], v[144:147], v[168:171], 0
	v_mfma_f32_16x16x32_bf16 v[32:35], v[152:155], v[168:171], 0
	v_mfma_f32_16x16x32_bf16 v[20:23], v[144:147], v[194:197], 0
	v_mfma_f32_16x16x32_bf16 v[16:19], v[152:155], v[194:197], 0
	v_mfma_f32_16x16x32_bf16 v[4:7], v[144:147], v[202:205], 0
	v_mfma_f32_16x16x32_bf16 v[0:3], v[152:155], v[202:205], 0
	v_mfma_f32_16x16x32_bf16 v[52:55], v[148:151], v[164:167], v[52:55]
	v_mfma_f32_16x16x32_bf16 v[48:51], v[156:159], v[164:167], v[48:51]
	v_mfma_f32_16x16x32_bf16 v[36:39], v[148:151], v[172:175], v[36:39]
	v_mfma_f32_16x16x32_bf16 v[32:35], v[156:159], v[172:175], v[32:35]
	v_mfma_f32_16x16x32_bf16 v[20:23], v[148:151], v[198:201], v[20:23]
	v_mfma_f32_16x16x32_bf16 v[16:19], v[156:159], v[198:201], v[16:19]
	v_mfma_f32_16x16x32_bf16 v[4:7], v[148:151], v[220:223], v[4:7]
	v_mfma_f32_16x16x32_bf16 v[0:3], v[156:159], v[220:223], v[0:3]
	s_barrier
	s_add_i32 s62, 0, 0x18000
	s_add_i32 s63, 0, 0x1c000
	v_add_u32_e32 v140, s62, v207
	v_add_u32_e32 v156, s63, v207
	ds_read_b128 v[128:131], v140
	ds_read_b128 v[132:135], v140 offset:1024
	ds_read_b128 v[136:139], v140 offset:2048
	ds_read_b128 v[140:143], v140 offset:3072
	ds_read_b128 v[144:147], v156
	ds_read_b128 v[148:151], v156 offset:1024
	ds_read_b128 v[152:155], v156 offset:2048
	ds_read_b128 v[156:159], v156 offset:3072
	s_add_u32 s40, s40, 0x40000
	s_addc_u32 s41, s41, 0
	s_mov_b32 m0, s45
	v_lshl_add_u64 v[232:233], s[40:41], 0, v[178:179]
	ds_read_b128 v[160:163], v218 offset:32768
	ds_read_b128 v[164:167], v218 offset:33792
	ds_read_b128 v[168:171], v218 offset:34816
	ds_read_b128 v[172:175], v218 offset:35840
	ds_read_b128 v[194:197], v218 offset:36864
	ds_read_b128 v[198:201], v218 offset:37888
	ds_read_b128 v[202:205], v218 offset:38912
	ds_read_b128 v[220:223], v218 offset:39936
	global_load_lds_dwordx4 v[232:233], off
	v_lshl_add_u64 v[232:233], s[40:41], 0, v[182:183]
	s_mov_b32 m0, s46
	s_nop 0
	global_load_lds_dwordx4 v[232:233], off
	s_waitcnt vmcnt(8)
	s_waitcnt lgkmcnt(0)
	s_barrier
	s_waitcnt lgkmcnt(0)
	v_mfma_f32_16x16x32_bf16 v[124:127], v[128:131], v[160:163], v[124:127]
	v_mfma_f32_16x16x32_bf16 v[120:123], v[136:139], v[160:163], v[120:123]
	v_mfma_f32_16x16x32_bf16 v[108:111], v[128:131], v[168:171], v[108:111]
	v_mfma_f32_16x16x32_bf16 v[104:107], v[136:139], v[168:171], v[104:107]
	v_mfma_f32_16x16x32_bf16 v[92:95], v[128:131], v[194:197], v[92:95]
	v_mfma_f32_16x16x32_bf16 v[88:91], v[136:139], v[194:197], v[88:91]
	v_mfma_f32_16x16x32_bf16 v[76:79], v[128:131], v[202:205], v[76:79]
	v_mfma_f32_16x16x32_bf16 v[72:75], v[136:139], v[202:205], v[72:75]
	v_mfma_f32_16x16x32_bf16 v[124:127], v[132:135], v[164:167], v[124:127]
	v_mfma_f32_16x16x32_bf16 v[120:123], v[140:143], v[164:167], v[120:123]
	v_mfma_f32_16x16x32_bf16 v[108:111], v[132:135], v[172:175], v[108:111]
	v_mfma_f32_16x16x32_bf16 v[104:107], v[140:143], v[172:175], v[104:107]
	v_mfma_f32_16x16x32_bf16 v[92:95], v[132:135], v[198:201], v[92:95]
	v_mfma_f32_16x16x32_bf16 v[88:91], v[140:143], v[198:201], v[88:91]
	v_mfma_f32_16x16x32_bf16 v[76:79], v[132:135], v[220:223], v[76:79]
	v_mfma_f32_16x16x32_bf16 v[72:75], v[140:143], v[220:223], v[72:75]
	v_mfma_f32_16x16x32_bf16 v[116:119], v[144:147], v[160:163], v[116:119]
	v_mfma_f32_16x16x32_bf16 v[112:115], v[152:155], v[160:163], v[112:115]
	v_mfma_f32_16x16x32_bf16 v[100:103], v[144:147], v[168:171], v[100:103]
	v_mfma_f32_16x16x32_bf16 v[96:99], v[152:155], v[168:171], v[96:99]
	v_mfma_f32_16x16x32_bf16 v[84:87], v[144:147], v[194:197], v[84:87]
	v_mfma_f32_16x16x32_bf16 v[80:83], v[152:155], v[194:197], v[80:83]
	v_mfma_f32_16x16x32_bf16 v[68:71], v[144:147], v[202:205], v[68:71]
	v_mfma_f32_16x16x32_bf16 v[64:67], v[152:155], v[202:205], v[64:67]
	v_mfma_f32_16x16x32_bf16 v[116:119], v[148:151], v[164:167], v[116:119]
	v_mfma_f32_16x16x32_bf16 v[112:115], v[156:159], v[164:167], v[112:115]
	v_mfma_f32_16x16x32_bf16 v[100:103], v[148:151], v[172:175], v[100:103]
	v_mfma_f32_16x16x32_bf16 v[96:99], v[156:159], v[172:175], v[96:99]
	v_mfma_f32_16x16x32_bf16 v[84:87], v[148:151], v[198:201], v[84:87]
	v_mfma_f32_16x16x32_bf16 v[80:83], v[156:159], v[198:201], v[80:83]
	v_mfma_f32_16x16x32_bf16 v[68:71], v[148:151], v[220:223], v[68:71]
	v_mfma_f32_16x16x32_bf16 v[64:67], v[156:159], v[220:223], v[64:67]
	s_barrier
; template <class Epi, class Sched, bool ALIGN_EPI, bool CONVA>
; DI void gemm_phase(LAS unsigned char* lds, const Gemm g, const Sched& S, const Epi& E) {
;     ...
;         for (int t = 0; t < nt; t += 2) {
	s_add_i32 s40, s62, s43
	v_lshl_add_u64 v[224:225], v[224:225], 0, s[16:17]
	s_mov_b32 m0, s40
	ds_read_b128 v[160:163], v218 offset:49152
	ds_read_b128 v[164:167], v218 offset:50176
	ds_read_b128 v[168:171], v218 offset:51200
	ds_read_b128 v[172:175], v218 offset:52224
	ds_read_b128 v[194:197], v218 offset:53248
	ds_read_b128 v[198:201], v218 offset:54272
	ds_read_b128 v[202:205], v218 offset:55296
	ds_read_b128 v[220:223], v218 offset:56320
	global_load_lds_dwordx4 v[224:225], off
	s_add_i32 m0, s40, 0x2000
	s_add_u32 s34, s34, 0x40080
	v_lshl_add_u64 v[224:225], v[226:227], 0, s[16:17]
	s_addc_u32 s35, s35, 0
	s_add_i32 s40, s63, s43
	global_load_lds_dwordx4 v[224:225], off
	v_lshl_add_u64 v[224:225], s[34:35], 0, v[180:181]
	s_mov_b32 m0, s40
	s_nop 0
	global_load_lds_dwordx4 v[224:225], off
	v_lshl_add_u64 v[224:225], s[34:35], 0, v[184:185]
	s_add_i32 m0, s40, 0x2000
	s_nop 0
	global_load_lds_dwordx4 v[224:225], off
	v_lshl_add_u64 v[224:225], v[228:229], 0, s[16:17]
	s_mov_b32 m0, s49
	s_nop 0
	global_load_lds_dwordx4 v[224:225], off
	v_lshl_add_u64 v[224:225], v[230:231], 0, s[16:17]
	s_mov_b32 m0, s50
	s_nop 0
	global_load_lds_dwordx4 v[224:225], off
	s_waitcnt vmcnt(8)
	s_waitcnt lgkmcnt(0)
	s_barrier
	s_waitcnt lgkmcnt(0)
	v_mfma_f32_16x16x32_bf16 v[60:63], v[128:131], v[160:163], v[60:63]
	v_mfma_f32_16x16x32_bf16 v[56:59], v[136:139], v[160:163], v[56:59]
	v_mfma_f32_16x16x32_bf16 v[44:47], v[128:131], v[168:171], v[44:47]
	v_mfma_f32_16x16x32_bf16 v[40:43], v[136:139], v[168:171], v[40:43]
	v_mfma_f32_16x16x32_bf16 v[28:31], v[128:131], v[194:197], v[28:31]
	v_mfma_f32_16x16x32_bf16 v[24:27], v[136:139], v[194:197], v[24:27]
	v_mfma_f32_16x16x32_bf16 v[12:15], v[128:131], v[202:205], v[12:15]
	v_mfma_f32_16x16x32_bf16 v[8:11], v[136:139], v[202:205], v[8:11]
	v_mfma_f32_16x16x32_bf16 v[60:63], v[132:135], v[164:167], v[60:63]
	v_mfma_f32_16x16x32_bf16 v[56:59], v[140:143], v[164:167], v[56:59]
	v_mfma_f32_16x16x32_bf16 v[44:47], v[132:135], v[172:175], v[44:47]
	v_mfma_f32_16x16x32_bf16 v[40:43], v[140:143], v[172:175], v[40:43]
	v_mfma_f32_16x16x32_bf16 v[28:31], v[132:135], v[198:201], v[28:31]
	v_mfma_f32_16x16x32_bf16 v[24:27], v[140:143], v[198:201], v[24:27]
	v_mfma_f32_16x16x32_bf16 v[12:15], v[132:135], v[220:223], v[12:15]
	v_mfma_f32_16x16x32_bf16 v[8:11], v[140:143], v[220:223], v[8:11]
	v_mfma_f32_16x16x32_bf16 v[52:55], v[144:147], v[160:163], v[52:55]
	v_mfma_f32_16x16x32_bf16 v[48:51], v[152:155], v[160:163], v[48:51]
	v_mfma_f32_16x16x32_bf16 v[36:39], v[144:147], v[168:171], v[36:39]
	v_mfma_f32_16x16x32_bf16 v[32:35], v[152:155], v[168:171], v[32:35]
	v_mfma_f32_16x16x32_bf16 v[20:23], v[144:147], v[194:197], v[20:23]
	v_mfma_f32_16x16x32_bf16 v[16:19], v[152:155], v[194:197], v[16:19]
	v_mfma_f32_16x16x32_bf16 v[4:7], v[144:147], v[202:205], v[4:7]
	v_mfma_f32_16x16x32_bf16 v[0:3], v[152:155], v[202:205], v[0:3]
	v_mfma_f32_16x16x32_bf16 v[52:55], v[148:151], v[164:167], v[52:55]
	v_mfma_f32_16x16x32_bf16 v[48:51], v[156:159], v[164:167], v[48:51]
	v_mfma_f32_16x16x32_bf16 v[36:39], v[148:151], v[172:175], v[36:39]
	v_mfma_f32_16x16x32_bf16 v[32:35], v[156:159], v[172:175], v[32:35]
	v_mfma_f32_16x16x32_bf16 v[20:23], v[148:151], v[198:201], v[20:23]
	v_mfma_f32_16x16x32_bf16 v[16:19], v[156:159], v[198:201], v[16:19]
	v_mfma_f32_16x16x32_bf16 v[4:7], v[148:151], v[220:223], v[4:7]
	v_mfma_f32_16x16x32_bf16 v[0:3], v[156:159], v[220:223], v[0:3]
	s_barrier
	s_add_i32 s61, s61, 2
	s_add_u32 s30, s30, 0x100
	s_addc_u32 s31, s31, 0
	s_add_u32 s59, s59, 0x100
	s_addc_u32 s60, s60, 0
	s_cmp_gt_u32 s61, 13
.LBB0_584:
	ds_read_b128 v[128:131], v216
	ds_read_b128 v[132:135], v216 offset:1024
	ds_read_b128 v[136:139], v216 offset:2048
	ds_read_b128 v[140:143], v216 offset:3072
	ds_read_b128 v[144:147], v217
	ds_read_b128 v[148:151], v217 offset:1024
	ds_read_b128 v[152:155], v217 offset:2048
	ds_read_b128 v[156:159], v217 offset:3072
	s_add_u32 s34, s30, 0xfffc0080
	s_addc_u32 s35, s31, -1
	s_cmp_eq_u32 s61, 12
	s_cselect_b32 s41, s25, s35
	s_cselect_b32 s40, s57, s34
	s_cselect_b32 s35, s21, s60
	s_cselect_b32 s34, s58, s59
	v_lshl_add_u64 v[224:225], s[30:31], 0, v[186:187]
	s_add_i32 m0, s7, 0xc000
	ds_read_b128 v[160:163], v218
	ds_read_b128 v[164:167], v218 offset:1024
	ds_read_b128 v[168:171], v218 offset:2048
	ds_read_b128 v[172:175], v218 offset:3072
	ds_read_b128 v[194:197], v218 offset:4096
	ds_read_b128 v[198:201], v218 offset:5120
	ds_read_b128 v[202:205], v218 offset:6144
	ds_read_b128 v[220:223], v218 offset:7168
	global_load_lds_dwordx4 v[224:225], off
	v_lshl_add_u64 v[224:225], s[30:31], 0, v[188:189]
	s_add_i32 m0, s7, 0xe000
	s_nop 0
	global_load_lds_dwordx4 v[224:225], off
	s_waitcnt vmcnt(8)
	s_waitcnt lgkmcnt(0)
	s_barrier
	s_waitcnt lgkmcnt(0)
	v_mfma_f32_16x16x32_bf16 v[124:127], v[128:131], v[160:163], v[124:127]
	v_mfma_f32_16x16x32_bf16 v[120:123], v[136:139], v[160:163], v[120:123]
	v_mfma_f32_16x16x32_bf16 v[108:111], v[128:131], v[168:171], v[108:111]
	v_mfma_f32_16x16x32_bf16 v[104:107], v[136:139], v[168:171], v[104:107]
	v_mfma_f32_16x16x32_bf16 v[92:95], v[128:131], v[194:197], v[92:95]
	v_mfma_f32_16x16x32_bf16 v[88:91], v[136:139], v[194:197], v[88:91]
	v_mfma_f32_16x16x32_bf16 v[76:79], v[128:131], v[202:205], v[76:79]
	v_mfma_f32_16x16x32_bf16 v[72:75], v[136:139], v[202:205], v[72:75]
	v_mfma_f32_16x16x32_bf16 v[124:127], v[132:135], v[164:167], v[124:127]
	v_mfma_f32_16x16x32_bf16 v[120:123], v[140:143], v[164:167], v[120:123]
	v_mfma_f32_16x16x32_bf16 v[108:111], v[132:135], v[172:175], v[108:111]
	v_mfma_f32_16x16x32_bf16 v[104:107], v[140:143], v[172:175], v[104:107]
	v_mfma_f32_16x16x32_bf16 v[92:95], v[132:135], v[198:201], v[92:95]
	v_mfma_f32_16x16x32_bf16 v[88:91], v[140:143], v[198:201], v[88:91]
	v_mfma_f32_16x16x32_bf16 v[76:79], v[132:135], v[220:223], v[76:79]
	v_mfma_f32_16x16x32_bf16 v[72:75], v[140:143], v[220:223], v[72:75]
	v_mfma_f32_16x16x32_bf16 v[116:119], v[144:147], v[160:163], v[116:119]
	v_mfma_f32_16x16x32_bf16 v[112:115], v[152:155], v[160:163], v[112:115]
	v_mfma_f32_16x16x32_bf16 v[100:103], v[144:147], v[168:171], v[100:103]
	v_mfma_f32_16x16x32_bf16 v[96:99], v[152:155], v[168:171], v[96:99]
	v_mfma_f32_16x16x32_bf16 v[84:87], v[144:147], v[194:197], v[84:87]
	v_mfma_f32_16x16x32_bf16 v[80:83], v[152:155], v[194:197], v[80:83]
	v_mfma_f32_16x16x32_bf16 v[68:71], v[144:147], v[202:205], v[68:71]
	v_mfma_f32_16x16x32_bf16 v[64:67], v[152:155], v[202:205], v[64:67]
	v_mfma_f32_16x16x32_bf16 v[116:119], v[148:151], v[164:167], v[116:119]
	v_mfma_f32_16x16x32_bf16 v[112:115], v[156:159], v[164:167], v[112:115]
	v_mfma_f32_16x16x32_bf16 v[100:103], v[148:151], v[172:175], v[100:103]
	v_mfma_f32_16x16x32_bf16 v[96:99], v[156:159], v[172:175], v[96:99]
	v_mfma_f32_16x16x32_bf16 v[84:87], v[148:151], v[198:201], v[84:87]
	v_mfma_f32_16x16x32_bf16 v[80:83], v[156:159], v[198:201], v[80:83]
	v_mfma_f32_16x16x32_bf16 v[68:71], v[148:151], v[220:223], v[68:71]
	v_mfma_f32_16x16x32_bf16 v[64:67], v[156:159], v[220:223], v[64:67]
	s_barrier
	s_add_i32 s62, s54, s43
	v_lshl_add_u64 v[224:225], s[34:35], 0, v[180:181]
	s_mov_b32 m0, s62
	ds_read_b128 v[160:163], v218 offset:16384
	ds_read_b128 v[164:167], v218 offset:17408
	ds_read_b128 v[168:171], v218 offset:18432
	ds_read_b128 v[172:175], v218 offset:19456
	ds_read_b128 v[194:197], v218 offset:20480
	ds_read_b128 v[198:201], v218 offset:21504
	ds_read_b128 v[202:205], v218 offset:22528
	ds_read_b128 v[220:223], v218 offset:23552
	global_load_lds_dwordx4 v[224:225], off
	s_add_i32 m0, s62, 0x2000
	s_add_u32 s62, s34, 0x40000
	v_lshl_add_u64 v[226:227], s[34:35], 0, v[184:185]
	s_addc_u32 s63, s35, 0
	s_add_i32 s64, s55, s43
	global_load_lds_dwordx4 v[226:227], off
	v_lshl_add_u64 v[228:229], s[62:63], 0, v[180:181]
	s_mov_b32 m0, s64
	v_lshl_add_u64 v[230:231], s[40:41], 0, v[182:183]
	global_load_lds_dwordx4 v[228:229], off
	v_lshl_add_u64 v[228:229], s[62:63], 0, v[184:185]
	s_add_i32 m0, s64, 0x2000
	s_nop 0
	global_load_lds_dwordx4 v[228:229], off
	v_lshl_add_u64 v[228:229], s[40:41], 0, v[178:179]
	s_mov_b32 m0, s7
	s_nop 0
	global_load_lds_dwordx4 v[228:229], off
	s_mov_b32 m0, s44
	s_nop 0
	global_load_lds_dwordx4 v[230:231], off
	s_waitcnt vmcnt(8)
	s_waitcnt lgkmcnt(0)
	s_barrier
	s_waitcnt lgkmcnt(0)
	v_mfma_f32_16x16x32_bf16 v[60:63], v[128:131], v[160:163], v[60:63]
	v_mfma_f32_16x16x32_bf16 v[56:59], v[136:139], v[160:163], v[56:59]
	v_mfma_f32_16x16x32_bf16 v[44:47], v[128:131], v[168:171], v[44:47]
	v_mfma_f32_16x16x32_bf16 v[40:43], v[136:139], v[168:171], v[40:43]
	v_mfma_f32_16x16x32_bf16 v[28:31], v[128:131], v[194:197], v[28:31]
	v_mfma_f32_16x16x32_bf16 v[24:27], v[136:139], v[194:197], v[24:27]
	v_mfma_f32_16x16x32_bf16 v[12:15], v[128:131], v[202:205], v[12:15]
	v_mfma_f32_16x16x32_bf16 v[8:11], v[136:139], v[202:205], v[8:11]
	v_mfma_f32_16x16x32_bf16 v[60:63], v[132:135], v[164:167], v[60:63]
	v_mfma_f32_16x16x32_bf16 v[56:59], v[140:143], v[164:167], v[56:59]
	v_mfma_f32_16x16x32_bf16 v[44:47], v[132:135], v[172:175], v[44:47]
	v_mfma_f32_16x16x32_bf16 v[40:43], v[140:143], v[172:175], v[40:43]
	v_mfma_f32_16x16x32_bf16 v[28:31], v[132:135], v[198:201], v[28:31]
	v_mfma_f32_16x16x32_bf16 v[24:27], v[140:143], v[198:201], v[24:27]
	v_mfma_f32_16x16x32_bf16 v[12:15], v[132:135], v[220:223], v[12:15]
	v_mfma_f32_16x16x32_bf16 v[8:11], v[140:143], v[220:223], v[8:11]
	v_mfma_f32_16x16x32_bf16 v[52:55], v[144:147], v[160:163], v[52:55]
	v_mfma_f32_16x16x32_bf16 v[48:51], v[152:155], v[160:163], v[48:51]
	v_mfma_f32_16x16x32_bf16 v[36:39], v[144:147], v[168:171], v[36:39]
	v_mfma_f32_16x16x32_bf16 v[32:35], v[152:155], v[168:171], v[32:35]
	v_mfma_f32_16x16x32_bf16 v[20:23], v[144:147], v[194:197], v[20:23]
	v_mfma_f32_16x16x32_bf16 v[16:19], v[152:155], v[194:197], v[16:19]
	v_mfma_f32_16x16x32_bf16 v[4:7], v[144:147], v[202:205], v[4:7]
	v_mfma_f32_16x16x32_bf16 v[0:3], v[152:155], v[202:205], v[0:3]
	v_mfma_f32_16x16x32_bf16 v[52:55], v[148:151], v[164:167], v[52:55]
	v_mfma_f32_16x16x32_bf16 v[48:51], v[156:159], v[164:167], v[48:51]
	v_mfma_f32_16x16x32_bf16 v[36:39], v[148:151], v[172:175], v[36:39]
	v_mfma_f32_16x16x32_bf16 v[32:35], v[156:159], v[172:175], v[32:35]
	v_mfma_f32_16x16x32_bf16 v[20:23], v[148:151], v[198:201], v[20:23]
	v_mfma_f32_16x16x32_bf16 v[16:19], v[156:159], v[198:201], v[16:19]
	v_mfma_f32_16x16x32_bf16 v[4:7], v[148:151], v[220:223], v[4:7]
	v_mfma_f32_16x16x32_bf16 v[0:3], v[156:159], v[220:223], v[0:3]
	s_barrier
	s_add_i32 s62, 0, 0x18000
	s_add_i32 s63, 0, 0x1c000
	v_add_u32_e32 v140, s62, v207
	v_add_u32_e32 v156, s63, v207
	ds_read_b128 v[128:131], v140
	ds_read_b128 v[132:135], v140 offset:1024
	ds_read_b128 v[136:139], v140 offset:2048
	ds_read_b128 v[140:143], v140 offset:3072
	ds_read_b128 v[144:147], v156
	ds_read_b128 v[148:151], v156 offset:1024
	ds_read_b128 v[152:155], v156 offset:2048
	ds_read_b128 v[156:159], v156 offset:3072
	s_add_u32 s40, s40, 0x40000
	s_addc_u32 s41, s41, 0
	s_mov_b32 m0, s45
	v_lshl_add_u64 v[232:233], s[40:41], 0, v[178:179]
	ds_read_b128 v[160:163], v218 offset:32768
	ds_read_b128 v[164:167], v218 offset:33792
	ds_read_b128 v[168:171], v218 offset:34816
	ds_read_b128 v[172:175], v218 offset:35840
	ds_read_b128 v[194:197], v218 offset:36864
	ds_read_b128 v[198:201], v218 offset:37888
	ds_read_b128 v[202:205], v218 offset:38912
	ds_read_b128 v[220:223], v218 offset:39936
	global_load_lds_dwordx4 v[232:233], off
	v_lshl_add_u64 v[232:233], s[40:41], 0, v[182:183]
	s_mov_b32 m0, s46
	s_nop 0
	global_load_lds_dwordx4 v[232:233], off
	s_waitcnt vmcnt(8)
	s_waitcnt lgkmcnt(0)
	s_barrier
	s_waitcnt lgkmcnt(0)
	v_mfma_f32_16x16x32_bf16 v[124:127], v[128:131], v[160:163], v[124:127]
	v_mfma_f32_16x16x32_bf16 v[120:123], v[136:139], v[160:163], v[120:123]
	v_mfma_f32_16x16x32_bf16 v[108:111], v[128:131], v[168:171], v[108:111]
	v_mfma_f32_16x16x32_bf16 v[104:107], v[136:139], v[168:171], v[104:107]
	v_mfma_f32_16x16x32_bf16 v[92:95], v[128:131], v[194:197], v[92:95]
	v_mfma_f32_16x16x32_bf16 v[88:91], v[136:139], v[194:197], v[88:91]
	v_mfma_f32_16x16x32_bf16 v[76:79], v[128:131], v[202:205], v[76:79]
	v_mfma_f32_16x16x32_bf16 v[72:75], v[136:139], v[202:205], v[72:75]
	v_mfma_f32_16x16x32_bf16 v[124:127], v[132:135], v[164:167], v[124:127]
	v_mfma_f32_16x16x32_bf16 v[120:123], v[140:143], v[164:167], v[120:123]
	v_mfma_f32_16x16x32_bf16 v[108:111], v[132:135], v[172:175], v[108:111]
	v_mfma_f32_16x16x32_bf16 v[104:107], v[140:143], v[172:175], v[104:107]
	v_mfma_f32_16x16x32_bf16 v[92:95], v[132:135], v[198:201], v[92:95]
	v_mfma_f32_16x16x32_bf16 v[88:91], v[140:143], v[198:201], v[88:91]
	v_mfma_f32_16x16x32_bf16 v[76:79], v[132:135], v[220:223], v[76:79]
	v_mfma_f32_16x16x32_bf16 v[72:75], v[140:143], v[220:223], v[72:75]
	v_mfma_f32_16x16x32_bf16 v[116:119], v[144:147], v[160:163], v[116:119]
	v_mfma_f32_16x16x32_bf16 v[112:115], v[152:155], v[160:163], v[112:115]
	v_mfma_f32_16x16x32_bf16 v[100:103], v[144:147], v[168:171], v[100:103]
	v_mfma_f32_16x16x32_bf16 v[96:99], v[152:155], v[168:171], v[96:99]
	v_mfma_f32_16x16x32_bf16 v[84:87], v[144:147], v[194:197], v[84:87]
	v_mfma_f32_16x16x32_bf16 v[80:83], v[152:155], v[194:197], v[80:83]
	v_mfma_f32_16x16x32_bf16 v[68:71], v[144:147], v[202:205], v[68:71]
	v_mfma_f32_16x16x32_bf16 v[64:67], v[152:155], v[202:205], v[64:67]
	v_mfma_f32_16x16x32_bf16 v[116:119], v[148:151], v[164:167], v[116:119]
	v_mfma_f32_16x16x32_bf16 v[112:115], v[156:159], v[164:167], v[112:115]
	v_mfma_f32_16x16x32_bf16 v[100:103], v[148:151], v[172:175], v[100:103]
	v_mfma_f32_16x16x32_bf16 v[96:99], v[156:159], v[172:175], v[96:99]
	v_mfma_f32_16x16x32_bf16 v[84:87], v[148:151], v[198:201], v[84:87]
	v_mfma_f32_16x16x32_bf16 v[80:83], v[156:159], v[198:201], v[80:83]
	v_mfma_f32_16x16x32_bf16 v[68:71], v[148:151], v[220:223], v[68:71]
	v_mfma_f32_16x16x32_bf16 v[64:67], v[156:159], v[220:223], v[64:67]
	s_barrier
; #define PG8_WAIT_V(n) asm volatile("s_waitcnt vmcnt(" #n ")" ::: "memory")
; #define PG8_BAR __builtin_amdgcn_s_barrier()
; template <class Epi, class Sched, bool ALIGN_EPI, bool CONVA>
; DI void gemm_phase(LAS unsigned char* lds, const Gemm g, const Sched& S, const Epi& E) {
;     ...
;         for (int t = 0; t < nt; t += 2) {
;             const bool last = (t == nt - 2);
;             const char* a1 = cA + (size_t)(t + 1) * kstep;
;             const char* a2 = last ? nA : cA + (size_t)(t + 2) * kstep; const char* b2 = last ? nB : cB + (size_t)(t + 2) * kstep;
;             const char* a3 = a2 + kstep; const char* b3 = b2 + kstep;
;             PG8_KBODY(PG8_WAIT_V(8));
;         }
;     ...
;         if constexpr (ALIGN_EPI) { if (wr == 0) PG8_BAR; }
	s_add_i32 s40, s62, s43
	v_lshl_add_u64 v[224:225], v[224:225], 0, s[16:17]
	s_mov_b32 m0, s40
	ds_read_b128 v[160:163], v218 offset:49152
	ds_read_b128 v[164:167], v218 offset:50176
	ds_read_b128 v[168:171], v218 offset:51200
	ds_read_b128 v[172:175], v218 offset:52224
	ds_read_b128 v[194:197], v218 offset:53248
	ds_read_b128 v[198:201], v218 offset:54272
	ds_read_b128 v[202:205], v218 offset:55296
	ds_read_b128 v[220:223], v218 offset:56320
	global_load_lds_dwordx4 v[224:225], off
	s_add_i32 m0, s40, 0x2000
	s_add_u32 s34, s34, 0x40080
	v_lshl_add_u64 v[224:225], v[226:227], 0, s[16:17]
	s_addc_u32 s35, s35, 0
	s_add_i32 s40, s63, s43
	global_load_lds_dwordx4 v[224:225], off
	v_lshl_add_u64 v[224:225], s[34:35], 0, v[180:181]
	s_mov_b32 m0, s40
	s_nop 0
	global_load_lds_dwordx4 v[224:225], off
	v_lshl_add_u64 v[224:225], s[34:35], 0, v[184:185]
	s_add_i32 m0, s40, 0x2000
	s_nop 0
	global_load_lds_dwordx4 v[224:225], off
	v_lshl_add_u64 v[224:225], v[228:229], 0, s[16:17]
	s_mov_b32 m0, s49
	s_nop 0
	global_load_lds_dwordx4 v[224:225], off
	v_lshl_add_u64 v[224:225], v[230:231], 0, s[16:17]
	s_mov_b32 m0, s50
	s_nop 0
	global_load_lds_dwordx4 v[224:225], off
	s_waitcnt vmcnt(8)
	s_waitcnt lgkmcnt(0)
	s_barrier
	s_waitcnt lgkmcnt(0)
	v_mfma_f32_16x16x32_bf16 v[60:63], v[128:131], v[160:163], v[60:63]
	v_mfma_f32_16x16x32_bf16 v[56:59], v[136:139], v[160:163], v[56:59]
	v_mfma_f32_16x16x32_bf16 v[44:47], v[128:131], v[168:171], v[44:47]
	v_mfma_f32_16x16x32_bf16 v[40:43], v[136:139], v[168:171], v[40:43]
	v_mfma_f32_16x16x32_bf16 v[28:31], v[128:131], v[194:197], v[28:31]
	v_mfma_f32_16x16x32_bf16 v[24:27], v[136:139], v[194:197], v[24:27]
	v_mfma_f32_16x16x32_bf16 v[12:15], v[128:131], v[202:205], v[12:15]
	v_mfma_f32_16x16x32_bf16 v[8:11], v[136:139], v[202:205], v[8:11]
	v_mfma_f32_16x16x32_bf16 v[60:63], v[132:135], v[164:167], v[60:63]
	v_mfma_f32_16x16x32_bf16 v[56:59], v[140:143], v[164:167], v[56:59]
	v_mfma_f32_16x16x32_bf16 v[44:47], v[132:135], v[172:175], v[44:47]
	v_mfma_f32_16x16x32_bf16 v[40:43], v[140:143], v[172:175], v[40:43]
	v_mfma_f32_16x16x32_bf16 v[28:31], v[132:135], v[198:201], v[28:31]
	v_mfma_f32_16x16x32_bf16 v[24:27], v[140:143], v[198:201], v[24:27]
	v_mfma_f32_16x16x32_bf16 v[12:15], v[132:135], v[220:223], v[12:15]
	v_mfma_f32_16x16x32_bf16 v[8:11], v[140:143], v[220:223], v[8:11]
	v_mfma_f32_16x16x32_bf16 v[52:55], v[144:147], v[160:163], v[52:55]
	v_mfma_f32_16x16x32_bf16 v[48:51], v[152:155], v[160:163], v[48:51]
	v_mfma_f32_16x16x32_bf16 v[36:39], v[144:147], v[168:171], v[36:39]
	v_mfma_f32_16x16x32_bf16 v[32:35], v[152:155], v[168:171], v[32:35]
	v_mfma_f32_16x16x32_bf16 v[20:23], v[144:147], v[194:197], v[20:23]
	v_mfma_f32_16x16x32_bf16 v[16:19], v[152:155], v[194:197], v[16:19]
	v_mfma_f32_16x16x32_bf16 v[4:7], v[144:147], v[202:205], v[4:7]
	v_mfma_f32_16x16x32_bf16 v[0:3], v[152:155], v[202:205], v[0:3]
	v_mfma_f32_16x16x32_bf16 v[52:55], v[148:151], v[164:167], v[52:55]
	v_mfma_f32_16x16x32_bf16 v[48:51], v[156:159], v[164:167], v[48:51]
	v_mfma_f32_16x16x32_bf16 v[36:39], v[148:151], v[172:175], v[36:39]
	v_mfma_f32_16x16x32_bf16 v[32:35], v[156:159], v[172:175], v[32:35]
	v_mfma_f32_16x16x32_bf16 v[20:23], v[148:151], v[198:201], v[20:23]
	v_mfma_f32_16x16x32_bf16 v[16:19], v[156:159], v[198:201], v[16:19]
	v_mfma_f32_16x16x32_bf16 v[4:7], v[148:151], v[220:223], v[4:7]
	v_mfma_f32_16x16x32_bf16 v[0:3], v[156:159], v[220:223], v[0:3]
	s_barrier
	s_add_i32 s61, s61, 2
	s_add_u32 s30, s30, 0x100
	s_addc_u32 s31, s31, 0
	s_add_u32 s59, s59, 0x100
	s_addc_u32 s60, s60, 0
	s_cmp_gt_u32 s61, 13
	s_cbranch_scc0 .LBB0_584
	s_and_b64 vcc, exec, s[18:19]
	s_cbranch_vccz .LBB0_587
	s_barrier

;     DI bool next(int i, Unit& u) const { if (!s.next(i >> 1, u)) return false; u.sel = i & 1; return true; }
; template <class Epi, class Sched, bool ALIGN_EPI, bool CONVA>
; DI void gemm_phase(LAS unsigned char* lds, const Gemm g, const Sched& S, const Epi& E) {
;     ...
;         const bool has_next = S.next(ui + 1, nxt);
;         const char* nA = has_next ? (const char*)(nxt.sel ? g.A2 : g.A) + (size_t)nxt.pm * tstepA + abias : cA;
;         const char* nB = has_next ? (const char*)(nxt.sel ? g.Bt2 : g.Bt) + (size_t)nxt.pn * tstepB : cB;
;     DI void operator()(f32x4 (&acc)[2][2][4][2], const Unit& u, int wr, int wc, int fr, int fq) const {
;     ...
;         for (int idx = 0; idx < 8; ++idx) { const int t = t0 + idx; const int tc = t < 0 ? 0 : (t >= MTOK ? MTOK - 1 : t); P8[idx] = *(const f32x4*)(ss + (size_t)tc * 16 + 4 * fq); }
.LBB0_640:
	s_ashr_i32 s95, s94, 31
	s_lshl_b64 s[26:27], s[94:95], 19
	v_readlane_b32 s16, v252, 20
	v_readlane_b32 s17, v252, 21
	s_add_u32 s78, s16, s26
	s_addc_u32 s79, s17, s27
	s_and_b64 s[20:21], s[20:21], exec
	s_cselect_b32 s29, s79, s25
	s_cselect_b32 s30, s78, s24
	s_add_u32 s31, s24, 0x100
	s_addc_u32 s34, s25, 0
	s_mov_b32 s35, -2
	ds_read_b128 v[128:131], v219
	ds_read_b128 v[132:135], v219 offset:1024
	ds_read_b128 v[136:139], v219 offset:2048
	ds_read_b128 v[140:143], v219 offset:3072
	ds_read_b128 v[144:147], v220
	ds_read_b128 v[148:151], v220 offset:1024
	ds_read_b128 v[152:155], v220 offset:2048
	ds_read_b128 v[178:181], v220 offset:3072
	s_add_u32 s20, s22, 0x100
	s_addc_u32 s21, s23, 0
	s_cmp_eq_u32 s35, 12
	s_cselect_b32 s27, s97, s21
	s_cselect_b32 s26, s96, s20
	s_cselect_b32 s25, s29, s34
	s_cselect_b32 s24, s30, s31
	v_lshl_add_u64 v[210:211], s[22:23], 0, v[168:169]
	s_add_i32 m0, s60, 0xc000
	ds_read_b128 v[182:185], v221
	ds_read_b128 v[186:189], v221 offset:1024
	ds_read_b128 v[190:193], v221 offset:2048
	ds_read_b128 v[194:197], v221 offset:3072
	ds_read_b128 v[198:201], v221 offset:4096
	ds_read_b128 v[202:205], v221 offset:5120
	ds_read_b128 v[206:209], v221 offset:6144
	ds_read_b128 v[226:229], v221 offset:7168
	global_load_lds_dwordx4 v[210:211], off
	v_lshl_add_u64 v[210:211], s[22:23], 0, v[170:171]
	s_add_i32 m0, s60, 0xe000
	s_nop 0
	global_load_lds_dwordx4 v[210:211], off
	s_waitcnt vmcnt(8)
	s_waitcnt lgkmcnt(0)
	s_barrier
	s_waitcnt lgkmcnt(0)
	v_mfma_f32_16x16x32_bf16 v[124:127], v[128:131], v[182:185], 0
	v_mfma_f32_16x16x32_bf16 v[116:119], v[136:139], v[182:185], 0
	v_mfma_f32_16x16x32_bf16 v[100:103], v[128:131], v[190:193], 0
	v_mfma_f32_16x16x32_bf16 v[44:47], v[136:139], v[190:193], 0
	v_mfma_f32_16x16x32_bf16 v[92:95], v[128:131], v[198:201], 0
	v_mfma_f32_16x16x32_bf16 v[36:39], v[136:139], v[198:201], 0
	v_mfma_f32_16x16x32_bf16 v[96:99], v[128:131], v[206:209], 0
	v_mfma_f32_16x16x32_bf16 v[40:43], v[136:139], v[206:209], 0
	v_mfma_f32_16x16x32_bf16 v[124:127], v[132:135], v[186:189], v[124:127]
	v_mfma_f32_16x16x32_bf16 v[116:119], v[140:143], v[186:189], v[116:119]
	v_mfma_f32_16x16x32_bf16 v[100:103], v[132:135], v[194:197], v[100:103]
	v_mfma_f32_16x16x32_bf16 v[44:47], v[140:143], v[194:197], v[44:47]
	v_mfma_f32_16x16x32_bf16 v[92:95], v[132:135], v[202:205], v[92:95]
	v_mfma_f32_16x16x32_bf16 v[36:39], v[140:143], v[202:205], v[36:39]
	v_mfma_f32_16x16x32_bf16 v[96:99], v[132:135], v[226:229], v[96:99]
	v_mfma_f32_16x16x32_bf16 v[40:43], v[140:143], v[226:229], v[40:43]
	v_mfma_f32_16x16x32_bf16 v[120:123], v[144:147], v[182:185], 0
	v_mfma_f32_16x16x32_bf16 v[76:79], v[152:155], v[182:185], 0
	v_mfma_f32_16x16x32_bf16 v[88:91], v[144:147], v[190:193], 0
	v_mfma_f32_16x16x32_bf16 v[32:35], v[152:155], v[190:193], 0
	v_mfma_f32_16x16x32_bf16 v[68:71], v[144:147], v[198:201], 0
	v_mfma_f32_16x16x32_bf16 v[20:23], v[152:155], v[198:201], 0
	v_mfma_f32_16x16x32_bf16 v[84:87], v[144:147], v[206:209], 0
	v_mfma_f32_16x16x32_bf16 v[28:31], v[152:155], v[206:209], 0
	v_mfma_f32_16x16x32_bf16 v[120:123], v[148:151], v[186:189], v[120:123]
	v_mfma_f32_16x16x32_bf16 v[76:79], v[178:181], v[186:189], v[76:79]
	v_mfma_f32_16x16x32_bf16 v[88:91], v[148:151], v[194:197], v[88:91]
	v_mfma_f32_16x16x32_bf16 v[32:35], v[178:181], v[194:197], v[32:35]
	v_mfma_f32_16x16x32_bf16 v[68:71], v[148:151], v[202:205], v[68:71]
	v_mfma_f32_16x16x32_bf16 v[20:23], v[178:181], v[202:205], v[20:23]
	v_mfma_f32_16x16x32_bf16 v[84:87], v[148:151], v[226:229], v[84:87]
	v_mfma_f32_16x16x32_bf16 v[28:31], v[178:181], v[226:229], v[28:31]
	s_barrier
	s_add_i32 s22, s13, s81
	v_lshl_add_u64 v[210:211], s[24:25], 0, v[158:159]
	s_mov_b32 m0, s22
	ds_read_b128 v[182:185], v221 offset:16384
	ds_read_b128 v[186:189], v221 offset:17408
	ds_read_b128 v[190:193], v221 offset:18432
	ds_read_b128 v[194:197], v221 offset:19456
	ds_read_b128 v[198:201], v221 offset:20480
	ds_read_b128 v[202:205], v221 offset:21504
	ds_read_b128 v[206:209], v221 offset:22528
	ds_read_b128 v[226:229], v221 offset:23552
	global_load_lds_dwordx4 v[210:211], off
	s_add_i32 m0, s22, 0x2000
	s_add_u32 s22, s24, 0x40000
	v_lshl_add_u64 v[230:231], s[24:25], 0, v[162:163]
	s_addc_u32 s23, s25, 0
	s_add_i32 s36, s62, s81
	global_load_lds_dwordx4 v[230:231], off
	v_lshl_add_u64 v[232:233], s[22:23], 0, v[158:159]
	s_mov_b32 m0, s36
	v_lshl_add_u64 v[234:235], s[26:27], 0, v[160:161]
	global_load_lds_dwordx4 v[232:233], off
	v_lshl_add_u64 v[232:233], s[22:23], 0, v[162:163]
	s_add_i32 m0, s36, 0x2000
	s_nop 0
	global_load_lds_dwordx4 v[232:233], off
	v_lshl_add_u64 v[232:233], s[26:27], 0, v[156:157]
	s_mov_b32 m0, s60
	s_nop 0
	global_load_lds_dwordx4 v[232:233], off
	s_mov_b32 m0, s61
	s_nop 0
	global_load_lds_dwordx4 v[234:235], off
	v_lshlrev_b32_e32 v248, 4, v222
	v_lshrrev_b32_e32 v249, 5, v222
	v_lshlrev_b32_e32 v249, 4, v249
	v_xor_b32_e32 v248, v248, v249
	v_and_b32_e32 v249, 48, v222
	v_mov_b32_e32 v250, s28
	v_mul_u32_u24_e32 v250, 0x3f80, v250
	v_lshl_add_u32 v250, s60, 1, v250
	v_sub_u32_e32 v250, v250, v249
	v_add_u32_e32 v250, 0xffffffc0, v250
	v_xor_b32_e32 v249, 32, v248
	v_add_u32_e32 v248, v250, v248
	v_add_u32_e32 v250, v250, v249
	v_ashrrev_i32_e32 v249, 31, v248
	v_ashrrev_i32_e32 v251, 31, v250
	v_lshl_add_u64 v[248:249], v[166:167], 0, v[248:249]
	v_lshl_add_u64 v[250:251], v[166:167], 0, v[250:251]
	s_lshl_b32 m0, s60, 1
	s_add_i32 m0, m0, 0x20800
	s_nop 0
	global_load_lds_dwordx4 v[248:249], off
	global_load_lds_dwordx4 v[250:251], off offset:1024
	s_waitcnt vmcnt(8)
	s_waitcnt lgkmcnt(0)
	s_barrier
	s_waitcnt lgkmcnt(0)
	v_mfma_f32_16x16x32_bf16 v[64:67], v[128:131], v[182:185], 0
	v_mfma_f32_16x16x32_bf16 v[16:19], v[136:139], v[182:185], 0
	v_mfma_f32_16x16x32_bf16 v[80:83], v[128:131], v[190:193], 0
	v_mfma_f32_16x16x32_bf16 v[24:27], v[136:139], v[190:193], 0
	v_mfma_f32_16x16x32_bf16 v[60:63], v[128:131], v[198:201], 0
	v_mfma_f32_16x16x32_bf16 v[12:15], v[136:139], v[198:201], 0
	v_mfma_f32_16x16x32_bf16 v[112:115], v[128:131], v[206:209], 0
	v_mfma_f32_16x16x32_bf16 v[108:111], v[136:139], v[206:209], 0
	v_mfma_f32_16x16x32_bf16 v[64:67], v[132:135], v[186:189], v[64:67]
	v_mfma_f32_16x16x32_bf16 v[16:19], v[140:143], v[186:189], v[16:19]
	v_mfma_f32_16x16x32_bf16 v[80:83], v[132:135], v[194:197], v[80:83]
	v_mfma_f32_16x16x32_bf16 v[24:27], v[140:143], v[194:197], v[24:27]
	v_mfma_f32_16x16x32_bf16 v[60:63], v[132:135], v[202:205], v[60:63]
	v_mfma_f32_16x16x32_bf16 v[12:15], v[140:143], v[202:205], v[12:15]
	v_mfma_f32_16x16x32_bf16 v[112:115], v[132:135], v[226:229], v[112:115]
	v_mfma_f32_16x16x32_bf16 v[108:111], v[140:143], v[226:229], v[108:111]
	v_mfma_f32_16x16x32_bf16 v[52:55], v[144:147], v[182:185], 0
	v_mfma_f32_16x16x32_bf16 v[4:7], v[152:155], v[182:185], 0
	v_mfma_f32_16x16x32_bf16 v[56:59], v[144:147], v[190:193], 0
	v_mfma_f32_16x16x32_bf16 v[8:11], v[152:155], v[190:193], 0
	v_mfma_f32_16x16x32_bf16 v[48:51], v[144:147], v[198:201], 0
	v_mfma_f32_16x16x32_bf16 v[0:3], v[152:155], v[198:201], 0
	v_mfma_f32_16x16x32_bf16 v[104:107], v[144:147], v[206:209], 0
	v_mfma_f32_16x16x32_bf16 v[72:75], v[152:155], v[206:209], 0
	v_mfma_f32_16x16x32_bf16 v[52:55], v[148:151], v[186:189], v[52:55]
	v_mfma_f32_16x16x32_bf16 v[4:7], v[178:181], v[186:189], v[4:7]
	v_mfma_f32_16x16x32_bf16 v[56:59], v[148:151], v[194:197], v[56:59]
	v_mfma_f32_16x16x32_bf16 v[8:11], v[178:181], v[194:197], v[8:11]
	v_mfma_f32_16x16x32_bf16 v[48:51], v[148:151], v[202:205], v[48:51]
	v_mfma_f32_16x16x32_bf16 v[0:3], v[178:181], v[202:205], v[0:3]
	v_mfma_f32_16x16x32_bf16 v[104:107], v[148:151], v[226:229], v[104:107]
	v_mfma_f32_16x16x32_bf16 v[72:75], v[178:181], v[226:229], v[72:75]
	s_barrier
	s_add_i32 s36, 0, 0x18000
	s_add_i32 s37, 0, 0x1c000
	v_add_u32_e32 v140, s36, v214
	v_add_u32_e32 v164, s37, v214
	ds_read_b128 v[128:131], v140
	ds_read_b128 v[132:135], v140 offset:1024
	ds_read_b128 v[136:139], v140 offset:2048
	ds_read_b128 v[140:143], v140 offset:3072
	ds_read_b128 v[144:147], v164
	ds_read_b128 v[148:151], v164 offset:1024
	ds_read_b128 v[152:155], v164 offset:2048
	ds_read_b128 v[178:181], v164 offset:3072
	s_add_u32 s22, s26, 0x2000
	s_addc_u32 s23, s27, 0
	s_mov_b32 m0, s33
	v_lshl_add_u64 v[236:237], s[22:23], 0, v[156:157]
	ds_read_b128 v[182:185], v221 offset:32768
	ds_read_b128 v[186:189], v221 offset:33792
	ds_read_b128 v[190:193], v221 offset:34816
	ds_read_b128 v[194:197], v221 offset:35840
	ds_read_b128 v[198:201], v221 offset:36864
	ds_read_b128 v[202:205], v221 offset:37888
	ds_read_b128 v[206:209], v221 offset:38912
	ds_read_b128 v[226:229], v221 offset:39936
	global_load_lds_dwordx4 v[236:237], off
	v_lshl_add_u64 v[236:237], s[22:23], 0, v[160:161]
	s_mov_b32 m0, s77
	s_nop 0
	global_load_lds_dwordx4 v[236:237], off
	s_waitcnt vmcnt(8)
	s_waitcnt lgkmcnt(0)
	s_barrier
	s_waitcnt lgkmcnt(0)
	v_mfma_f32_16x16x32_bf16 v[124:127], v[128:131], v[182:185], v[124:127]
	v_mfma_f32_16x16x32_bf16 v[116:119], v[136:139], v[182:185], v[116:119]
	v_mfma_f32_16x16x32_bf16 v[100:103], v[128:131], v[190:193], v[100:103]
	v_mfma_f32_16x16x32_bf16 v[44:47], v[136:139], v[190:193], v[44:47]
	v_mfma_f32_16x16x32_bf16 v[92:95], v[128:131], v[198:201], v[92:95]
	v_mfma_f32_16x16x32_bf16 v[36:39], v[136:139], v[198:201], v[36:39]
	v_mfma_f32_16x16x32_bf16 v[96:99], v[128:131], v[206:209], v[96:99]
	v_mfma_f32_16x16x32_bf16 v[40:43], v[136:139], v[206:209], v[40:43]
	v_mfma_f32_16x16x32_bf16 v[124:127], v[132:135], v[186:189], v[124:127]
	v_mfma_f32_16x16x32_bf16 v[116:119], v[140:143], v[186:189], v[116:119]
	v_mfma_f32_16x16x32_bf16 v[100:103], v[132:135], v[194:197], v[100:103]
	v_mfma_f32_16x16x32_bf16 v[44:47], v[140:143], v[194:197], v[44:47]
	v_mfma_f32_16x16x32_bf16 v[92:95], v[132:135], v[202:205], v[92:95]
	v_mfma_f32_16x16x32_bf16 v[36:39], v[140:143], v[202:205], v[36:39]
	v_mfma_f32_16x16x32_bf16 v[96:99], v[132:135], v[226:229], v[96:99]
	v_mfma_f32_16x16x32_bf16 v[40:43], v[140:143], v[226:229], v[40:43]
	v_mfma_f32_16x16x32_bf16 v[120:123], v[144:147], v[182:185], v[120:123]
	v_mfma_f32_16x16x32_bf16 v[76:79], v[152:155], v[182:185], v[76:79]
	v_mfma_f32_16x16x32_bf16 v[88:91], v[144:147], v[190:193], v[88:91]
	v_mfma_f32_16x16x32_bf16 v[32:35], v[152:155], v[190:193], v[32:35]
	v_mfma_f32_16x16x32_bf16 v[68:71], v[144:147], v[198:201], v[68:71]
	v_mfma_f32_16x16x32_bf16 v[20:23], v[152:155], v[198:201], v[20:23]
	v_mfma_f32_16x16x32_bf16 v[84:87], v[144:147], v[206:209], v[84:87]
	v_mfma_f32_16x16x32_bf16 v[28:31], v[152:155], v[206:209], v[28:31]
	v_mfma_f32_16x16x32_bf16 v[120:123], v[148:151], v[186:189], v[120:123]
	v_mfma_f32_16x16x32_bf16 v[76:79], v[178:181], v[186:189], v[76:79]
	v_mfma_f32_16x16x32_bf16 v[88:91], v[148:151], v[194:197], v[88:91]
	v_mfma_f32_16x16x32_bf16 v[32:35], v[178:181], v[194:197], v[32:35]
	v_mfma_f32_16x16x32_bf16 v[68:71], v[148:151], v[202:205], v[68:71]
	v_mfma_f32_16x16x32_bf16 v[20:23], v[178:181], v[202:205], v[20:23]
	v_mfma_f32_16x16x32_bf16 v[84:87], v[148:151], v[226:229], v[84:87]
	v_mfma_f32_16x16x32_bf16 v[28:31], v[178:181], v[226:229], v[28:31]
	s_barrier
; template <class Epi, class Sched, bool ALIGN_EPI, bool CONVA>
; DI void gemm_phase(LAS unsigned char* lds, const Gemm g, const Sched& S, const Epi& E) {
;     ...
;         for (int t = 0; t < nt; t += 2) {
	s_add_i32 s22, s36, s81
	v_lshl_add_u64 v[210:211], v[210:211], 0, s[84:85]
	s_mov_b32 m0, s22
	ds_read_b128 v[182:185], v221 offset:49152
	ds_read_b128 v[186:189], v221 offset:50176
	ds_read_b128 v[190:193], v221 offset:51200
	ds_read_b128 v[194:197], v221 offset:52224
	ds_read_b128 v[198:201], v221 offset:53248
	ds_read_b128 v[202:205], v221 offset:54272
	ds_read_b128 v[206:209], v221 offset:55296
	ds_read_b128 v[226:229], v221 offset:56320
	global_load_lds_dwordx4 v[210:211], off
	s_add_i32 m0, s22, 0x2000
	s_add_u32 s22, s24, 0x40080
	v_lshl_add_u64 v[210:211], v[230:231], 0, s[84:85]
	s_addc_u32 s23, s25, 0
	s_add_i32 s24, s37, s81
	global_load_lds_dwordx4 v[210:211], off
	v_lshl_add_u64 v[210:211], s[22:23], 0, v[158:159]
	s_mov_b32 m0, s24
	s_nop 0
	global_load_lds_dwordx4 v[210:211], off
	v_lshl_add_u64 v[210:211], s[22:23], 0, v[162:163]
	s_add_i32 m0, s24, 0x2000
	s_nop 0
	global_load_lds_dwordx4 v[210:211], off
	v_lshl_add_u64 v[210:211], v[232:233], 0, s[84:85]
	s_mov_b32 m0, s67
	s_nop 0
	global_load_lds_dwordx4 v[210:211], off
	v_lshl_add_u64 v[210:211], v[234:235], 0, s[84:85]
	s_mov_b32 m0, s10
	s_nop 0
	global_load_lds_dwordx4 v[210:211], off
	s_waitcnt vmcnt(8)
	s_waitcnt lgkmcnt(0)
	s_barrier
	s_waitcnt lgkmcnt(0)
	v_mfma_f32_16x16x32_bf16 v[64:67], v[128:131], v[182:185], v[64:67]
	v_mfma_f32_16x16x32_bf16 v[16:19], v[136:139], v[182:185], v[16:19]
	v_mfma_f32_16x16x32_bf16 v[80:83], v[128:131], v[190:193], v[80:83]
	v_mfma_f32_16x16x32_bf16 v[24:27], v[136:139], v[190:193], v[24:27]
	v_mfma_f32_16x16x32_bf16 v[60:63], v[128:131], v[198:201], v[60:63]
	v_mfma_f32_16x16x32_bf16 v[12:15], v[136:139], v[198:201], v[12:15]
	v_mfma_f32_16x16x32_bf16 v[112:115], v[128:131], v[206:209], v[112:115]
	v_mfma_f32_16x16x32_bf16 v[108:111], v[136:139], v[206:209], v[108:111]
	v_mfma_f32_16x16x32_bf16 v[64:67], v[132:135], v[186:189], v[64:67]
	v_mfma_f32_16x16x32_bf16 v[16:19], v[140:143], v[186:189], v[16:19]
	v_mfma_f32_16x16x32_bf16 v[80:83], v[132:135], v[194:197], v[80:83]
	v_mfma_f32_16x16x32_bf16 v[24:27], v[140:143], v[194:197], v[24:27]
	v_mfma_f32_16x16x32_bf16 v[60:63], v[132:135], v[202:205], v[60:63]
	v_mfma_f32_16x16x32_bf16 v[12:15], v[140:143], v[202:205], v[12:15]
	v_mfma_f32_16x16x32_bf16 v[112:115], v[132:135], v[226:229], v[112:115]
	v_mfma_f32_16x16x32_bf16 v[108:111], v[140:143], v[226:229], v[108:111]
	v_mfma_f32_16x16x32_bf16 v[52:55], v[144:147], v[182:185], v[52:55]
	v_mfma_f32_16x16x32_bf16 v[4:7], v[152:155], v[182:185], v[4:7]
	v_mfma_f32_16x16x32_bf16 v[56:59], v[144:147], v[190:193], v[56:59]
	v_mfma_f32_16x16x32_bf16 v[8:11], v[152:155], v[190:193], v[8:11]
	v_mfma_f32_16x16x32_bf16 v[48:51], v[144:147], v[198:201], v[48:51]
	v_mfma_f32_16x16x32_bf16 v[0:3], v[152:155], v[198:201], v[0:3]
	v_mfma_f32_16x16x32_bf16 v[104:107], v[144:147], v[206:209], v[104:107]
	v_mfma_f32_16x16x32_bf16 v[72:75], v[152:155], v[206:209], v[72:75]
	v_mfma_f32_16x16x32_bf16 v[52:55], v[148:151], v[186:189], v[52:55]
	v_mfma_f32_16x16x32_bf16 v[4:7], v[178:181], v[186:189], v[4:7]
	v_mfma_f32_16x16x32_bf16 v[56:59], v[148:151], v[194:197], v[56:59]
	v_mfma_f32_16x16x32_bf16 v[8:11], v[178:181], v[194:197], v[8:11]
	v_mfma_f32_16x16x32_bf16 v[48:51], v[148:151], v[202:205], v[48:51]
	v_mfma_f32_16x16x32_bf16 v[0:3], v[178:181], v[202:205], v[0:3]
	v_mfma_f32_16x16x32_bf16 v[104:107], v[148:151], v[226:229], v[104:107]
	v_mfma_f32_16x16x32_bf16 v[72:75], v[178:181], v[226:229], v[72:75]
	s_barrier
	s_add_i32 s35, s35, 2
	s_add_u32 s31, s31, 0x100
	s_addc_u32 s34, s34, 0
	s_cmp_gt_u32 s35, 13
	s_mov_b64 s[22:23], s[20:21]
.LBB0_641:
	ds_read_b128 v[128:131], v219
	ds_read_b128 v[132:135], v219 offset:1024
	ds_read_b128 v[136:139], v219 offset:2048
	ds_read_b128 v[140:143], v219 offset:3072
	ds_read_b128 v[144:147], v220
	ds_read_b128 v[148:151], v220 offset:1024
	ds_read_b128 v[152:155], v220 offset:2048
	ds_read_b128 v[178:181], v220 offset:3072
	s_add_u32 s20, s22, 0x100
	s_addc_u32 s21, s23, 0
	s_cmp_eq_u32 s35, 12
	s_cselect_b32 s27, s97, s21
	s_cselect_b32 s26, s96, s20
	s_cselect_b32 s25, s29, s34
	s_cselect_b32 s24, s30, s31
	v_lshl_add_u64 v[210:211], s[22:23], 0, v[168:169]
	s_add_i32 m0, s60, 0xc000
	ds_read_b128 v[182:185], v221
	ds_read_b128 v[186:189], v221 offset:1024
	ds_read_b128 v[190:193], v221 offset:2048
	ds_read_b128 v[194:197], v221 offset:3072
	ds_read_b128 v[198:201], v221 offset:4096
	ds_read_b128 v[202:205], v221 offset:5120
	ds_read_b128 v[206:209], v221 offset:6144
	ds_read_b128 v[226:229], v221 offset:7168
	global_load_lds_dwordx4 v[210:211], off
	v_lshl_add_u64 v[210:211], s[22:23], 0, v[170:171]
	s_add_i32 m0, s60, 0xe000
	s_nop 0
	global_load_lds_dwordx4 v[210:211], off
	s_waitcnt vmcnt(8)
	s_waitcnt lgkmcnt(0)
	s_barrier
	s_waitcnt lgkmcnt(0)
	v_mfma_f32_16x16x32_bf16 v[124:127], v[128:131], v[182:185], v[124:127]
	v_mfma_f32_16x16x32_bf16 v[116:119], v[136:139], v[182:185], v[116:119]
	v_mfma_f32_16x16x32_bf16 v[100:103], v[128:131], v[190:193], v[100:103]
	v_mfma_f32_16x16x32_bf16 v[44:47], v[136:139], v[190:193], v[44:47]
	v_mfma_f32_16x16x32_bf16 v[92:95], v[128:131], v[198:201], v[92:95]
	v_mfma_f32_16x16x32_bf16 v[36:39], v[136:139], v[198:201], v[36:39]
	v_mfma_f32_16x16x32_bf16 v[96:99], v[128:131], v[206:209], v[96:99]
	v_mfma_f32_16x16x32_bf16 v[40:43], v[136:139], v[206:209], v[40:43]
	v_mfma_f32_16x16x32_bf16 v[124:127], v[132:135], v[186:189], v[124:127]
	v_mfma_f32_16x16x32_bf16 v[116:119], v[140:143], v[186:189], v[116:119]
	v_mfma_f32_16x16x32_bf16 v[100:103], v[132:135], v[194:197], v[100:103]
	v_mfma_f32_16x16x32_bf16 v[44:47], v[140:143], v[194:197], v[44:47]
	v_mfma_f32_16x16x32_bf16 v[92:95], v[132:135], v[202:205], v[92:95]
	v_mfma_f32_16x16x32_bf16 v[36:39], v[140:143], v[202:205], v[36:39]
	v_mfma_f32_16x16x32_bf16 v[96:99], v[132:135], v[226:229], v[96:99]
	v_mfma_f32_16x16x32_bf16 v[40:43], v[140:143], v[226:229], v[40:43]
	v_mfma_f32_16x16x32_bf16 v[120:123], v[144:147], v[182:185], v[120:123]
	v_mfma_f32_16x16x32_bf16 v[76:79], v[152:155], v[182:185], v[76:79]
	v_mfma_f32_16x16x32_bf16 v[88:91], v[144:147], v[190:193], v[88:91]
	v_mfma_f32_16x16x32_bf16 v[32:35], v[152:155], v[190:193], v[32:35]
	v_mfma_f32_16x16x32_bf16 v[68:71], v[144:147], v[198:201], v[68:71]
	v_mfma_f32_16x16x32_bf16 v[20:23], v[152:155], v[198:201], v[20:23]
	v_mfma_f32_16x16x32_bf16 v[84:87], v[144:147], v[206:209], v[84:87]
	v_mfma_f32_16x16x32_bf16 v[28:31], v[152:155], v[206:209], v[28:31]
	v_mfma_f32_16x16x32_bf16 v[120:123], v[148:151], v[186:189], v[120:123]
	v_mfma_f32_16x16x32_bf16 v[76:79], v[178:181], v[186:189], v[76:79]
	v_mfma_f32_16x16x32_bf16 v[88:91], v[148:151], v[194:197], v[88:91]
	v_mfma_f32_16x16x32_bf16 v[32:35], v[178:181], v[194:197], v[32:35]
	v_mfma_f32_16x16x32_bf16 v[68:71], v[148:151], v[202:205], v[68:71]
	v_mfma_f32_16x16x32_bf16 v[20:23], v[178:181], v[202:205], v[20:23]
	v_mfma_f32_16x16x32_bf16 v[84:87], v[148:151], v[226:229], v[84:87]
	v_mfma_f32_16x16x32_bf16 v[28:31], v[178:181], v[226:229], v[28:31]
	s_barrier
	s_add_i32 s22, s13, s81
	v_lshl_add_u64 v[210:211], s[24:25], 0, v[158:159]
	s_mov_b32 m0, s22
	ds_read_b128 v[182:185], v221 offset:16384
	ds_read_b128 v[186:189], v221 offset:17408
	ds_read_b128 v[190:193], v221 offset:18432
	ds_read_b128 v[194:197], v221 offset:19456
	ds_read_b128 v[198:201], v221 offset:20480
	ds_read_b128 v[202:205], v221 offset:21504
	ds_read_b128 v[206:209], v221 offset:22528
	ds_read_b128 v[226:229], v221 offset:23552
	global_load_lds_dwordx4 v[210:211], off
	s_add_i32 m0, s22, 0x2000
	s_add_u32 s22, s24, 0x40000
	v_lshl_add_u64 v[230:231], s[24:25], 0, v[162:163]
	s_addc_u32 s23, s25, 0
	s_add_i32 s36, s62, s81
	global_load_lds_dwordx4 v[230:231], off
	v_lshl_add_u64 v[232:233], s[22:23], 0, v[158:159]
	s_mov_b32 m0, s36
	v_lshl_add_u64 v[234:235], s[26:27], 0, v[160:161]
	global_load_lds_dwordx4 v[232:233], off
	v_lshl_add_u64 v[232:233], s[22:23], 0, v[162:163]
	s_add_i32 m0, s36, 0x2000
	s_nop 0
	global_load_lds_dwordx4 v[232:233], off
	v_lshl_add_u64 v[232:233], s[26:27], 0, v[156:157]
	s_mov_b32 m0, s60
	s_nop 0
	global_load_lds_dwordx4 v[232:233], off
	s_mov_b32 m0, s61
	s_nop 0
	global_load_lds_dwordx4 v[234:235], off
	s_waitcnt vmcnt(8)
	s_waitcnt lgkmcnt(0)
	s_barrier
	s_waitcnt lgkmcnt(0)
	v_mfma_f32_16x16x32_bf16 v[64:67], v[128:131], v[182:185], v[64:67]
	v_mfma_f32_16x16x32_bf16 v[16:19], v[136:139], v[182:185], v[16:19]
	v_mfma_f32_16x16x32_bf16 v[80:83], v[128:131], v[190:193], v[80:83]
	v_mfma_f32_16x16x32_bf16 v[24:27], v[136:139], v[190:193], v[24:27]
	v_mfma_f32_16x16x32_bf16 v[60:63], v[128:131], v[198:201], v[60:63]
	v_mfma_f32_16x16x32_bf16 v[12:15], v[136:139], v[198:201], v[12:15]
	v_mfma_f32_16x16x32_bf16 v[112:115], v[128:131], v[206:209], v[112:115]
	v_mfma_f32_16x16x32_bf16 v[108:111], v[136:139], v[206:209], v[108:111]
	v_mfma_f32_16x16x32_bf16 v[64:67], v[132:135], v[186:189], v[64:67]
	v_mfma_f32_16x16x32_bf16 v[16:19], v[140:143], v[186:189], v[16:19]
	v_mfma_f32_16x16x32_bf16 v[80:83], v[132:135], v[194:197], v[80:83]
	v_mfma_f32_16x16x32_bf16 v[24:27], v[140:143], v[194:197], v[24:27]
	v_mfma_f32_16x16x32_bf16 v[60:63], v[132:135], v[202:205], v[60:63]
	v_mfma_f32_16x16x32_bf16 v[12:15], v[140:143], v[202:205], v[12:15]
	v_mfma_f32_16x16x32_bf16 v[112:115], v[132:135], v[226:229], v[112:115]
	v_mfma_f32_16x16x32_bf16 v[108:111], v[140:143], v[226:229], v[108:111]
	v_mfma_f32_16x16x32_bf16 v[52:55], v[144:147], v[182:185], v[52:55]
	v_mfma_f32_16x16x32_bf16 v[4:7], v[152:155], v[182:185], v[4:7]
	v_mfma_f32_16x16x32_bf16 v[56:59], v[144:147], v[190:193], v[56:59]
	v_mfma_f32_16x16x32_bf16 v[8:11], v[152:155], v[190:193], v[8:11]
	v_mfma_f32_16x16x32_bf16 v[48:51], v[144:147], v[198:201], v[48:51]
	v_mfma_f32_16x16x32_bf16 v[0:3], v[152:155], v[198:201], v[0:3]
	v_mfma_f32_16x16x32_bf16 v[104:107], v[144:147], v[206:209], v[104:107]
	v_mfma_f32_16x16x32_bf16 v[72:75], v[152:155], v[206:209], v[72:75]
	v_mfma_f32_16x16x32_bf16 v[52:55], v[148:151], v[186:189], v[52:55]
	v_mfma_f32_16x16x32_bf16 v[4:7], v[178:181], v[186:189], v[4:7]
	v_mfma_f32_16x16x32_bf16 v[56:59], v[148:151], v[194:197], v[56:59]
	v_mfma_f32_16x16x32_bf16 v[8:11], v[178:181], v[194:197], v[8:11]
	v_mfma_f32_16x16x32_bf16 v[48:51], v[148:151], v[202:205], v[48:51]
	v_mfma_f32_16x16x32_bf16 v[0:3], v[178:181], v[202:205], v[0:3]
	v_mfma_f32_16x16x32_bf16 v[104:107], v[148:151], v[226:229], v[104:107]
	v_mfma_f32_16x16x32_bf16 v[72:75], v[178:181], v[226:229], v[72:75]
	s_barrier
	s_add_i32 s36, 0, 0x18000
	s_add_i32 s37, 0, 0x1c000
	v_add_u32_e32 v140, s36, v214
	v_add_u32_e32 v164, s37, v214
	ds_read_b128 v[128:131], v140
	ds_read_b128 v[132:135], v140 offset:1024
	ds_read_b128 v[136:139], v140 offset:2048
	ds_read_b128 v[140:143], v140 offset:3072
	ds_read_b128 v[144:147], v164
	ds_read_b128 v[148:151], v164 offset:1024
	ds_read_b128 v[152:155], v164 offset:2048
	ds_read_b128 v[178:181], v164 offset:3072
	s_add_u32 s22, s26, 0x2000
	s_addc_u32 s23, s27, 0
	s_mov_b32 m0, s33
	v_lshl_add_u64 v[236:237], s[22:23], 0, v[156:157]
	ds_read_b128 v[182:185], v221 offset:32768
	ds_read_b128 v[186:189], v221 offset:33792
	ds_read_b128 v[190:193], v221 offset:34816
	ds_read_b128 v[194:197], v221 offset:35840
	ds_read_b128 v[198:201], v221 offset:36864
	ds_read_b128 v[202:205], v221 offset:37888
	ds_read_b128 v[206:209], v221 offset:38912
	ds_read_b128 v[226:229], v221 offset:39936
	global_load_lds_dwordx4 v[236:237], off
	v_lshl_add_u64 v[236:237], s[22:23], 0, v[160:161]
	s_mov_b32 m0, s77
	s_nop 0
	global_load_lds_dwordx4 v[236:237], off
	s_waitcnt vmcnt(8)
	s_waitcnt lgkmcnt(0)
	s_barrier
	s_waitcnt lgkmcnt(0)
	v_mfma_f32_16x16x32_bf16 v[124:127], v[128:131], v[182:185], v[124:127]
	v_mfma_f32_16x16x32_bf16 v[116:119], v[136:139], v[182:185], v[116:119]
	v_mfma_f32_16x16x32_bf16 v[100:103], v[128:131], v[190:193], v[100:103]
	v_mfma_f32_16x16x32_bf16 v[44:47], v[136:139], v[190:193], v[44:47]
	v_mfma_f32_16x16x32_bf16 v[92:95], v[128:131], v[198:201], v[92:95]
	v_mfma_f32_16x16x32_bf16 v[36:39], v[136:139], v[198:201], v[36:39]
	v_mfma_f32_16x16x32_bf16 v[96:99], v[128:131], v[206:209], v[96:99]
	v_mfma_f32_16x16x32_bf16 v[40:43], v[136:139], v[206:209], v[40:43]
	v_mfma_f32_16x16x32_bf16 v[124:127], v[132:135], v[186:189], v[124:127]
	v_mfma_f32_16x16x32_bf16 v[116:119], v[140:143], v[186:189], v[116:119]
	v_mfma_f32_16x16x32_bf16 v[100:103], v[132:135], v[194:197], v[100:103]
	v_mfma_f32_16x16x32_bf16 v[44:47], v[140:143], v[194:197], v[44:47]
	v_mfma_f32_16x16x32_bf16 v[92:95], v[132:135], v[202:205], v[92:95]
	v_mfma_f32_16x16x32_bf16 v[36:39], v[140:143], v[202:205], v[36:39]
	v_mfma_f32_16x16x32_bf16 v[96:99], v[132:135], v[226:229], v[96:99]
	v_mfma_f32_16x16x32_bf16 v[40:43], v[140:143], v[226:229], v[40:43]
	v_mfma_f32_16x16x32_bf16 v[120:123], v[144:147], v[182:185], v[120:123]
	v_mfma_f32_16x16x32_bf16 v[76:79], v[152:155], v[182:185], v[76:79]
	v_mfma_f32_16x16x32_bf16 v[88:91], v[144:147], v[190:193], v[88:91]
	v_mfma_f32_16x16x32_bf16 v[32:35], v[152:155], v[190:193], v[32:35]
	v_mfma_f32_16x16x32_bf16 v[68:71], v[144:147], v[198:201], v[68:71]
	v_mfma_f32_16x16x32_bf16 v[20:23], v[152:155], v[198:201], v[20:23]
	v_mfma_f32_16x16x32_bf16 v[84:87], v[144:147], v[206:209], v[84:87]
	v_mfma_f32_16x16x32_bf16 v[28:31], v[152:155], v[206:209], v[28:31]
	v_mfma_f32_16x16x32_bf16 v[120:123], v[148:151], v[186:189], v[120:123]
	v_mfma_f32_16x16x32_bf16 v[76:79], v[178:181], v[186:189], v[76:79]
	v_mfma_f32_16x16x32_bf16 v[88:91], v[148:151], v[194:197], v[88:91]
	v_mfma_f32_16x16x32_bf16 v[32:35], v[178:181], v[194:197], v[32:35]
	v_mfma_f32_16x16x32_bf16 v[68:71], v[148:151], v[202:205], v[68:71]
	v_mfma_f32_16x16x32_bf16 v[20:23], v[178:181], v[202:205], v[20:23]
	v_mfma_f32_16x16x32_bf16 v[84:87], v[148:151], v[226:229], v[84:87]
	v_mfma_f32_16x16x32_bf16 v[28:31], v[178:181], v[226:229], v[28:31]
	s_barrier
; #define PG8_WAIT_V(n) asm volatile("s_waitcnt vmcnt(" #n ")" ::: "memory")
; #define PG8_BAR __builtin_amdgcn_s_barrier()
; template <class Epi, class Sched, bool ALIGN_EPI, bool CONVA>
; DI void gemm_phase(LAS unsigned char* lds, const Gemm g, const Sched& S, const Epi& E) {
;     ...
;         for (int t = 0; t < nt; t += 2) {
;             const bool last = (t == nt - 2);
;             const char* a1 = cA + (size_t)(t + 1) * kstep;
;             const char* a2 = last ? nA : cA + (size_t)(t + 2) * kstep; const char* b2 = last ? nB : cB + (size_t)(t + 2) * kstep;
;             const char* a3 = a2 + kstep; const char* b3 = b2 + kstep;
;             PG8_KBODY(PG8_WAIT_V(8));
;         }
;     ...
;         if constexpr (ALIGN_EPI) { if (wr == 0) PG8_BAR; }
	s_add_i32 s22, s36, s81
	v_lshl_add_u64 v[210:211], v[210:211], 0, s[84:85]
	s_mov_b32 m0, s22
	ds_read_b128 v[182:185], v221 offset:49152
	ds_read_b128 v[186:189], v221 offset:50176
	ds_read_b128 v[190:193], v221 offset:51200
	ds_read_b128 v[194:197], v221 offset:52224
	ds_read_b128 v[198:201], v221 offset:53248
	ds_read_b128 v[202:205], v221 offset:54272
	ds_read_b128 v[206:209], v221 offset:55296
	ds_read_b128 v[226:229], v221 offset:56320
	global_load_lds_dwordx4 v[210:211], off
	s_add_i32 m0, s22, 0x2000
	s_add_u32 s22, s24, 0x40080
	v_lshl_add_u64 v[210:211], v[230:231], 0, s[84:85]
	s_addc_u32 s23, s25, 0
	s_add_i32 s24, s37, s81
	global_load_lds_dwordx4 v[210:211], off
	v_lshl_add_u64 v[210:211], s[22:23], 0, v[158:159]
	s_mov_b32 m0, s24
	s_nop 0
	global_load_lds_dwordx4 v[210:211], off
	v_lshl_add_u64 v[210:211], s[22:23], 0, v[162:163]
	s_add_i32 m0, s24, 0x2000
	s_nop 0
	global_load_lds_dwordx4 v[210:211], off
	v_lshl_add_u64 v[210:211], v[232:233], 0, s[84:85]
	s_mov_b32 m0, s67
	s_nop 0
	global_load_lds_dwordx4 v[210:211], off
	v_lshl_add_u64 v[210:211], v[234:235], 0, s[84:85]
	s_mov_b32 m0, s10
	s_nop 0
	global_load_lds_dwordx4 v[210:211], off
	s_waitcnt vmcnt(8)
	s_waitcnt lgkmcnt(0)
	s_barrier
	s_waitcnt lgkmcnt(0)
	v_mfma_f32_16x16x32_bf16 v[64:67], v[128:131], v[182:185], v[64:67]
	v_mfma_f32_16x16x32_bf16 v[16:19], v[136:139], v[182:185], v[16:19]
	v_mfma_f32_16x16x32_bf16 v[80:83], v[128:131], v[190:193], v[80:83]
	v_mfma_f32_16x16x32_bf16 v[24:27], v[136:139], v[190:193], v[24:27]
	v_mfma_f32_16x16x32_bf16 v[60:63], v[128:131], v[198:201], v[60:63]
	v_mfma_f32_16x16x32_bf16 v[12:15], v[136:139], v[198:201], v[12:15]
	v_mfma_f32_16x16x32_bf16 v[112:115], v[128:131], v[206:209], v[112:115]
	v_mfma_f32_16x16x32_bf16 v[108:111], v[136:139], v[206:209], v[108:111]
	v_mfma_f32_16x16x32_bf16 v[64:67], v[132:135], v[186:189], v[64:67]
	v_mfma_f32_16x16x32_bf16 v[16:19], v[140:143], v[186:189], v[16:19]
	v_mfma_f32_16x16x32_bf16 v[80:83], v[132:135], v[194:197], v[80:83]
	v_mfma_f32_16x16x32_bf16 v[24:27], v[140:143], v[194:197], v[24:27]
	v_mfma_f32_16x16x32_bf16 v[60:63], v[132:135], v[202:205], v[60:63]
	v_mfma_f32_16x16x32_bf16 v[12:15], v[140:143], v[202:205], v[12:15]
	v_mfma_f32_16x16x32_bf16 v[112:115], v[132:135], v[226:229], v[112:115]
	v_mfma_f32_16x16x32_bf16 v[108:111], v[140:143], v[226:229], v[108:111]
	v_mfma_f32_16x16x32_bf16 v[52:55], v[144:147], v[182:185], v[52:55]
	v_mfma_f32_16x16x32_bf16 v[4:7], v[152:155], v[182:185], v[4:7]
	v_mfma_f32_16x16x32_bf16 v[56:59], v[144:147], v[190:193], v[56:59]
	v_mfma_f32_16x16x32_bf16 v[8:11], v[152:155], v[190:193], v[8:11]
	v_mfma_f32_16x16x32_bf16 v[48:51], v[144:147], v[198:201], v[48:51]
	v_mfma_f32_16x16x32_bf16 v[0:3], v[152:155], v[198:201], v[0:3]
	v_mfma_f32_16x16x32_bf16 v[104:107], v[144:147], v[206:209], v[104:107]
	v_mfma_f32_16x16x32_bf16 v[72:75], v[152:155], v[206:209], v[72:75]
	v_mfma_f32_16x16x32_bf16 v[52:55], v[148:151], v[186:189], v[52:55]
	v_mfma_f32_16x16x32_bf16 v[4:7], v[178:181], v[186:189], v[4:7]
	v_mfma_f32_16x16x32_bf16 v[56:59], v[148:151], v[194:197], v[56:59]
	v_mfma_f32_16x16x32_bf16 v[8:11], v[178:181], v[194:197], v[8:11]
	v_mfma_f32_16x16x32_bf16 v[48:51], v[148:151], v[202:205], v[48:51]
	v_mfma_f32_16x16x32_bf16 v[0:3], v[178:181], v[202:205], v[0:3]
	v_mfma_f32_16x16x32_bf16 v[104:107], v[148:151], v[226:229], v[104:107]
	v_mfma_f32_16x16x32_bf16 v[72:75], v[178:181], v[226:229], v[72:75]
	s_barrier
	s_add_i32 s35, s35, 2
	s_add_u32 s31, s31, 0x100
	s_addc_u32 s34, s34, 0
	s_cmp_gt_u32 s35, 13
	s_mov_b64 s[22:23], s[20:21]
	s_cbranch_scc0 .LBB0_641
	v_readlane_b32 s16, v252, 2
	v_readlane_b32 s17, v252, 3
	s_and_b64 vcc, exec, s[16:17]
	s_cbranch_vccz .LBB0_644
	s_barrier

;     DI bool next(int i, Unit& u) const { if (!s.next(i >> 1, u)) return false; u.sel = i & 1; return true; }
; template <class Epi, class Sched, bool ALIGN_EPI, bool CONVA>
; DI void gemm_phase(LAS unsigned char* lds, const Gemm g, const Sched& S, const Epi& E) {
;     ...
;         const bool has_next = S.next(ui + 1, nxt);
;         const char* nA = has_next ? (const char*)(nxt.sel ? g.A2 : g.A) + (size_t)nxt.pm * tstepA + abias : cA;
;         const char* nB = has_next ? (const char*)(nxt.sel ? g.Bt2 : g.Bt) + (size_t)nxt.pn * tstepB : cB;
.LBB0_720:
	s_add_u32 s6, s26, 0xb0080
	s_addc_u32 s7, s27, 0
	s_add_u32 s8, s24, 0x100
	s_addc_u32 s50, s25, 0
	s_mov_b32 s51, -2
	ds_read_b128 v[128:131], v208
	ds_read_b128 v[132:135], v208 offset:1024
	ds_read_b128 v[136:139], v208 offset:2048
	ds_read_b128 v[140:143], v208 offset:3072
	ds_read_b128 v[144:147], v209
	ds_read_b128 v[148:151], v209 offset:1024
	ds_read_b128 v[170:173], v209 offset:2048
	ds_read_b128 v[174:177], v209 offset:3072
	s_add_u32 s24, s6, 0xfff50080
	s_addc_u32 s25, s7, -1
	s_cmp_eq_u32 s51, 40
	s_cselect_b32 s27, s21, s25
	s_cselect_b32 s26, s20, s24
	s_cselect_b32 s25, s23, s50
	s_cselect_b32 s24, s22, s8
	v_lshl_add_u64 v[226:227], s[6:7], 0, v[162:163]
	s_add_i32 m0, s31, 0xc000
	ds_read_b128 v[178:181], v210
	ds_read_b128 v[182:185], v210 offset:1024
	ds_read_b128 v[186:189], v210 offset:2048
	ds_read_b128 v[190:193], v210 offset:3072
	ds_read_b128 v[194:197], v210 offset:4096
	ds_read_b128 v[214:217], v210 offset:5120
	ds_read_b128 v[218:221], v210 offset:6144
	ds_read_b128 v[222:225], v210 offset:7168
	global_load_lds_dwordx4 v[226:227], off
	v_lshl_add_u64 v[226:227], s[6:7], 0, v[164:165]
	s_add_i32 m0, s31, 0xe000
	s_nop 0
	global_load_lds_dwordx4 v[226:227], off
	s_waitcnt vmcnt(8)
	s_waitcnt lgkmcnt(0)
	s_barrier
	s_waitcnt lgkmcnt(0)
	v_mfma_f32_16x16x32_bf16 v[124:127], v[128:131], v[178:181], 0
	v_mfma_f32_16x16x32_bf16 v[120:123], v[136:139], v[178:181], 0
	v_mfma_f32_16x16x32_bf16 v[108:111], v[128:131], v[186:189], 0
	v_mfma_f32_16x16x32_bf16 v[104:107], v[136:139], v[186:189], 0
	v_mfma_f32_16x16x32_bf16 v[92:95], v[128:131], v[194:197], 0
	v_mfma_f32_16x16x32_bf16 v[88:91], v[136:139], v[194:197], 0
	v_mfma_f32_16x16x32_bf16 v[76:79], v[128:131], v[218:221], 0
	v_mfma_f32_16x16x32_bf16 v[72:75], v[136:139], v[218:221], 0
	v_mfma_f32_16x16x32_bf16 v[124:127], v[132:135], v[182:185], v[124:127]
	v_mfma_f32_16x16x32_bf16 v[120:123], v[140:143], v[182:185], v[120:123]
	v_mfma_f32_16x16x32_bf16 v[108:111], v[132:135], v[190:193], v[108:111]
	v_mfma_f32_16x16x32_bf16 v[104:107], v[140:143], v[190:193], v[104:107]
	v_mfma_f32_16x16x32_bf16 v[92:95], v[132:135], v[214:217], v[92:95]
	v_mfma_f32_16x16x32_bf16 v[88:91], v[140:143], v[214:217], v[88:91]
	v_mfma_f32_16x16x32_bf16 v[76:79], v[132:135], v[222:225], v[76:79]
	v_mfma_f32_16x16x32_bf16 v[72:75], v[140:143], v[222:225], v[72:75]
	v_mfma_f32_16x16x32_bf16 v[116:119], v[144:147], v[178:181], 0
	v_mfma_f32_16x16x32_bf16 v[112:115], v[170:173], v[178:181], 0
	v_mfma_f32_16x16x32_bf16 v[100:103], v[144:147], v[186:189], 0
	v_mfma_f32_16x16x32_bf16 v[96:99], v[170:173], v[186:189], 0
	v_mfma_f32_16x16x32_bf16 v[84:87], v[144:147], v[194:197], 0
	v_mfma_f32_16x16x32_bf16 v[80:83], v[170:173], v[194:197], 0
	v_mfma_f32_16x16x32_bf16 v[68:71], v[144:147], v[218:221], 0
	v_mfma_f32_16x16x32_bf16 v[64:67], v[170:173], v[218:221], 0
	v_mfma_f32_16x16x32_bf16 v[116:119], v[148:151], v[182:185], v[116:119]
	v_mfma_f32_16x16x32_bf16 v[112:115], v[174:177], v[182:185], v[112:115]
	v_mfma_f32_16x16x32_bf16 v[100:103], v[148:151], v[190:193], v[100:103]
	v_mfma_f32_16x16x32_bf16 v[96:99], v[174:177], v[190:193], v[96:99]
	v_mfma_f32_16x16x32_bf16 v[84:87], v[148:151], v[214:217], v[84:87]
	v_mfma_f32_16x16x32_bf16 v[80:83], v[174:177], v[214:217], v[80:83]
	v_mfma_f32_16x16x32_bf16 v[68:71], v[148:151], v[222:225], v[68:71]
	v_mfma_f32_16x16x32_bf16 v[64:67], v[174:177], v[222:225], v[64:67]
	s_barrier
	s_add_i32 s52, s42, s30
	v_lshl_add_u64 v[226:227], s[24:25], 0, v[154:155]
	s_mov_b32 m0, s52
	ds_read_b128 v[178:181], v210 offset:16384
	ds_read_b128 v[182:185], v210 offset:17408
	ds_read_b128 v[186:189], v210 offset:18432
	ds_read_b128 v[190:193], v210 offset:19456
	ds_read_b128 v[194:197], v210 offset:20480
	ds_read_b128 v[214:217], v210 offset:21504
	ds_read_b128 v[218:221], v210 offset:22528
	ds_read_b128 v[222:225], v210 offset:23552
	global_load_lds_dwordx4 v[226:227], off
	s_add_i32 m0, s52, 0x2000
	s_add_u32 s52, s24, 0xb0000
	v_lshl_add_u64 v[228:229], s[24:25], 0, v[158:159]
	s_addc_u32 s53, s25, 0
	s_add_i32 s54, s43, s30
	global_load_lds_dwordx4 v[228:229], off
	v_lshl_add_u64 v[230:231], s[52:53], 0, v[154:155]
	s_mov_b32 m0, s54
	v_lshl_add_u64 v[232:233], s[26:27], 0, v[156:157]
	global_load_lds_dwordx4 v[230:231], off
	v_lshl_add_u64 v[230:231], s[52:53], 0, v[158:159]
	s_add_i32 m0, s54, 0x2000
	s_nop 0
	global_load_lds_dwordx4 v[230:231], off
	v_lshl_add_u64 v[230:231], s[26:27], 0, v[152:153]
	s_mov_b32 m0, s31
	s_nop 0
	global_load_lds_dwordx4 v[230:231], off
	s_mov_b32 m0, s33
	s_nop 0
	global_load_lds_dwordx4 v[232:233], off
	s_waitcnt vmcnt(8)
	s_waitcnt lgkmcnt(0)
	s_barrier
	s_waitcnt lgkmcnt(0)
	v_mfma_f32_16x16x32_bf16 v[60:63], v[128:131], v[178:181], 0
	v_mfma_f32_16x16x32_bf16 v[56:59], v[136:139], v[178:181], 0
	v_mfma_f32_16x16x32_bf16 v[44:47], v[128:131], v[186:189], 0
	v_mfma_f32_16x16x32_bf16 v[40:43], v[136:139], v[186:189], 0
	v_mfma_f32_16x16x32_bf16 v[28:31], v[128:131], v[194:197], 0
	v_mfma_f32_16x16x32_bf16 v[24:27], v[136:139], v[194:197], 0
	v_mfma_f32_16x16x32_bf16 v[12:15], v[128:131], v[218:221], 0
	v_mfma_f32_16x16x32_bf16 v[8:11], v[136:139], v[218:221], 0
	v_mfma_f32_16x16x32_bf16 v[60:63], v[132:135], v[182:185], v[60:63]
	v_mfma_f32_16x16x32_bf16 v[56:59], v[140:143], v[182:185], v[56:59]
	v_mfma_f32_16x16x32_bf16 v[44:47], v[132:135], v[190:193], v[44:47]
	v_mfma_f32_16x16x32_bf16 v[40:43], v[140:143], v[190:193], v[40:43]
	v_mfma_f32_16x16x32_bf16 v[28:31], v[132:135], v[214:217], v[28:31]
	v_mfma_f32_16x16x32_bf16 v[24:27], v[140:143], v[214:217], v[24:27]
	v_mfma_f32_16x16x32_bf16 v[12:15], v[132:135], v[222:225], v[12:15]
	v_mfma_f32_16x16x32_bf16 v[8:11], v[140:143], v[222:225], v[8:11]
	v_mfma_f32_16x16x32_bf16 v[52:55], v[144:147], v[178:181], 0
	v_mfma_f32_16x16x32_bf16 v[48:51], v[170:173], v[178:181], 0
	v_mfma_f32_16x16x32_bf16 v[36:39], v[144:147], v[186:189], 0
	v_mfma_f32_16x16x32_bf16 v[32:35], v[170:173], v[186:189], 0
	v_mfma_f32_16x16x32_bf16 v[20:23], v[144:147], v[194:197], 0
	v_mfma_f32_16x16x32_bf16 v[16:19], v[170:173], v[194:197], 0
	v_mfma_f32_16x16x32_bf16 v[4:7], v[144:147], v[218:221], 0
	v_mfma_f32_16x16x32_bf16 v[0:3], v[170:173], v[218:221], 0
	v_mfma_f32_16x16x32_bf16 v[52:55], v[148:151], v[182:185], v[52:55]
	v_mfma_f32_16x16x32_bf16 v[48:51], v[174:177], v[182:185], v[48:51]
	v_mfma_f32_16x16x32_bf16 v[36:39], v[148:151], v[190:193], v[36:39]
	v_mfma_f32_16x16x32_bf16 v[32:35], v[174:177], v[190:193], v[32:35]
	v_mfma_f32_16x16x32_bf16 v[20:23], v[148:151], v[214:217], v[20:23]
	v_mfma_f32_16x16x32_bf16 v[16:19], v[174:177], v[214:217], v[16:19]
	v_mfma_f32_16x16x32_bf16 v[4:7], v[148:151], v[222:225], v[4:7]
	v_mfma_f32_16x16x32_bf16 v[0:3], v[174:177], v[222:225], v[0:3]
	s_barrier
	s_add_i32 s52, 0, 0x18000
	s_add_i32 s53, 0, 0x1c000
	v_add_u32_e32 v140, s52, v199
	v_add_u32_e32 v174, s53, v199
	ds_read_b128 v[128:131], v140
	ds_read_b128 v[132:135], v140 offset:1024
	ds_read_b128 v[136:139], v140 offset:2048
	ds_read_b128 v[140:143], v140 offset:3072
	ds_read_b128 v[144:147], v174
	ds_read_b128 v[148:151], v174 offset:1024
	ds_read_b128 v[170:173], v174 offset:2048
	ds_read_b128 v[174:177], v174 offset:3072
	s_add_u32 s26, s26, 0xb0000
	s_addc_u32 s27, s27, 0
	s_mov_b32 m0, s34
	v_lshl_add_u64 v[234:235], s[26:27], 0, v[152:153]
	ds_read_b128 v[178:181], v210 offset:32768
	ds_read_b128 v[182:185], v210 offset:33792
	ds_read_b128 v[186:189], v210 offset:34816
	ds_read_b128 v[190:193], v210 offset:35840
	ds_read_b128 v[194:197], v210 offset:36864
	ds_read_b128 v[214:217], v210 offset:37888
	ds_read_b128 v[218:221], v210 offset:38912
	ds_read_b128 v[222:225], v210 offset:39936
	global_load_lds_dwordx4 v[234:235], off
	v_lshl_add_u64 v[234:235], s[26:27], 0, v[156:157]
	s_mov_b32 m0, s35
	s_nop 0
	global_load_lds_dwordx4 v[234:235], off
	s_waitcnt vmcnt(8)
	s_waitcnt lgkmcnt(0)
	s_barrier
	s_waitcnt lgkmcnt(0)
	v_mfma_f32_16x16x32_bf16 v[124:127], v[128:131], v[178:181], v[124:127]
	v_mfma_f32_16x16x32_bf16 v[120:123], v[136:139], v[178:181], v[120:123]
	v_mfma_f32_16x16x32_bf16 v[108:111], v[128:131], v[186:189], v[108:111]
	v_mfma_f32_16x16x32_bf16 v[104:107], v[136:139], v[186:189], v[104:107]
	v_mfma_f32_16x16x32_bf16 v[92:95], v[128:131], v[194:197], v[92:95]
	v_mfma_f32_16x16x32_bf16 v[88:91], v[136:139], v[194:197], v[88:91]
	v_mfma_f32_16x16x32_bf16 v[76:79], v[128:131], v[218:221], v[76:79]
	v_mfma_f32_16x16x32_bf16 v[72:75], v[136:139], v[218:221], v[72:75]
	v_mfma_f32_16x16x32_bf16 v[124:127], v[132:135], v[182:185], v[124:127]
	v_mfma_f32_16x16x32_bf16 v[120:123], v[140:143], v[182:185], v[120:123]
	v_mfma_f32_16x16x32_bf16 v[108:111], v[132:135], v[190:193], v[108:111]
	v_mfma_f32_16x16x32_bf16 v[104:107], v[140:143], v[190:193], v[104:107]
	v_mfma_f32_16x16x32_bf16 v[92:95], v[132:135], v[214:217], v[92:95]
	v_mfma_f32_16x16x32_bf16 v[88:91], v[140:143], v[214:217], v[88:91]
	v_mfma_f32_16x16x32_bf16 v[76:79], v[132:135], v[222:225], v[76:79]
	v_mfma_f32_16x16x32_bf16 v[72:75], v[140:143], v[222:225], v[72:75]
	v_mfma_f32_16x16x32_bf16 v[116:119], v[144:147], v[178:181], v[116:119]
	v_mfma_f32_16x16x32_bf16 v[112:115], v[170:173], v[178:181], v[112:115]
	v_mfma_f32_16x16x32_bf16 v[100:103], v[144:147], v[186:189], v[100:103]
	v_mfma_f32_16x16x32_bf16 v[96:99], v[170:173], v[186:189], v[96:99]
	v_mfma_f32_16x16x32_bf16 v[84:87], v[144:147], v[194:197], v[84:87]
	v_mfma_f32_16x16x32_bf16 v[80:83], v[170:173], v[194:197], v[80:83]
	v_mfma_f32_16x16x32_bf16 v[68:71], v[144:147], v[218:221], v[68:71]
	v_mfma_f32_16x16x32_bf16 v[64:67], v[170:173], v[218:221], v[64:67]
	v_mfma_f32_16x16x32_bf16 v[116:119], v[148:151], v[182:185], v[116:119]
	v_mfma_f32_16x16x32_bf16 v[112:115], v[174:177], v[182:185], v[112:115]
	v_mfma_f32_16x16x32_bf16 v[100:103], v[148:151], v[190:193], v[100:103]
	v_mfma_f32_16x16x32_bf16 v[96:99], v[174:177], v[190:193], v[96:99]
	v_mfma_f32_16x16x32_bf16 v[84:87], v[148:151], v[214:217], v[84:87]
	v_mfma_f32_16x16x32_bf16 v[80:83], v[174:177], v[214:217], v[80:83]
	v_mfma_f32_16x16x32_bf16 v[68:71], v[148:151], v[222:225], v[68:71]
	v_mfma_f32_16x16x32_bf16 v[64:67], v[174:177], v[222:225], v[64:67]
	s_barrier
; template <class Epi, class Sched, bool ALIGN_EPI, bool CONVA>
; DI void gemm_phase(LAS unsigned char* lds, const Gemm g, const Sched& S, const Epi& E) {
;     ...
;         for (int t = 0; t < nt; t += 2) {
	s_add_i32 s26, s52, s30
	v_lshl_add_u64 v[226:227], v[226:227], 0, s[16:17]
	s_mov_b32 m0, s26
	ds_read_b128 v[178:181], v210 offset:49152
	ds_read_b128 v[182:185], v210 offset:50176
	ds_read_b128 v[186:189], v210 offset:51200
	ds_read_b128 v[190:193], v210 offset:52224
	ds_read_b128 v[194:197], v210 offset:53248
	ds_read_b128 v[214:217], v210 offset:54272
	ds_read_b128 v[218:221], v210 offset:55296
	ds_read_b128 v[222:225], v210 offset:56320
	global_load_lds_dwordx4 v[226:227], off
	s_add_i32 m0, s26, 0x2000
	s_add_u32 s24, s24, 0xb0080
	v_lshl_add_u64 v[226:227], v[228:229], 0, s[16:17]
	s_addc_u32 s25, s25, 0
	s_add_i32 s26, s53, s30
	global_load_lds_dwordx4 v[226:227], off
	v_lshl_add_u64 v[226:227], s[24:25], 0, v[154:155]
	s_mov_b32 m0, s26
	s_nop 0
	global_load_lds_dwordx4 v[226:227], off
	v_lshl_add_u64 v[226:227], s[24:25], 0, v[158:159]
	s_add_i32 m0, s26, 0x2000
	s_nop 0
	global_load_lds_dwordx4 v[226:227], off
	v_lshl_add_u64 v[226:227], v[230:231], 0, s[16:17]
	s_mov_b32 m0, s37
	s_nop 0
	global_load_lds_dwordx4 v[226:227], off
	v_lshl_add_u64 v[226:227], v[232:233], 0, s[16:17]
	s_mov_b32 m0, s38
	s_nop 0
	global_load_lds_dwordx4 v[226:227], off
	s_waitcnt vmcnt(8)
	s_waitcnt lgkmcnt(0)
	s_barrier
	s_waitcnt lgkmcnt(0)
	v_mfma_f32_16x16x32_bf16 v[60:63], v[128:131], v[178:181], v[60:63]
	v_mfma_f32_16x16x32_bf16 v[56:59], v[136:139], v[178:181], v[56:59]
	v_mfma_f32_16x16x32_bf16 v[44:47], v[128:131], v[186:189], v[44:47]
	v_mfma_f32_16x16x32_bf16 v[40:43], v[136:139], v[186:189], v[40:43]
	v_mfma_f32_16x16x32_bf16 v[28:31], v[128:131], v[194:197], v[28:31]
	v_mfma_f32_16x16x32_bf16 v[24:27], v[136:139], v[194:197], v[24:27]
	v_mfma_f32_16x16x32_bf16 v[12:15], v[128:131], v[218:221], v[12:15]
	v_mfma_f32_16x16x32_bf16 v[8:11], v[136:139], v[218:221], v[8:11]
	v_mfma_f32_16x16x32_bf16 v[60:63], v[132:135], v[182:185], v[60:63]
	v_mfma_f32_16x16x32_bf16 v[56:59], v[140:143], v[182:185], v[56:59]
	v_mfma_f32_16x16x32_bf16 v[44:47], v[132:135], v[190:193], v[44:47]
	v_mfma_f32_16x16x32_bf16 v[40:43], v[140:143], v[190:193], v[40:43]
	v_mfma_f32_16x16x32_bf16 v[28:31], v[132:135], v[214:217], v[28:31]
	v_mfma_f32_16x16x32_bf16 v[24:27], v[140:143], v[214:217], v[24:27]
	v_mfma_f32_16x16x32_bf16 v[12:15], v[132:135], v[222:225], v[12:15]
	v_mfma_f32_16x16x32_bf16 v[8:11], v[140:143], v[222:225], v[8:11]
	v_mfma_f32_16x16x32_bf16 v[52:55], v[144:147], v[178:181], v[52:55]
	v_mfma_f32_16x16x32_bf16 v[48:51], v[170:173], v[178:181], v[48:51]
	v_mfma_f32_16x16x32_bf16 v[36:39], v[144:147], v[186:189], v[36:39]
	v_mfma_f32_16x16x32_bf16 v[32:35], v[170:173], v[186:189], v[32:35]
	v_mfma_f32_16x16x32_bf16 v[20:23], v[144:147], v[194:197], v[20:23]
	v_mfma_f32_16x16x32_bf16 v[16:19], v[170:173], v[194:197], v[16:19]
	v_mfma_f32_16x16x32_bf16 v[4:7], v[144:147], v[218:221], v[4:7]
	v_mfma_f32_16x16x32_bf16 v[0:3], v[170:173], v[218:221], v[0:3]
	v_mfma_f32_16x16x32_bf16 v[52:55], v[148:151], v[182:185], v[52:55]
	v_mfma_f32_16x16x32_bf16 v[48:51], v[174:177], v[182:185], v[48:51]
	v_mfma_f32_16x16x32_bf16 v[36:39], v[148:151], v[190:193], v[36:39]
	v_mfma_f32_16x16x32_bf16 v[32:35], v[174:177], v[190:193], v[32:35]
	v_mfma_f32_16x16x32_bf16 v[20:23], v[148:151], v[214:217], v[20:23]
	v_mfma_f32_16x16x32_bf16 v[16:19], v[174:177], v[214:217], v[16:19]
	v_mfma_f32_16x16x32_bf16 v[4:7], v[148:151], v[222:225], v[4:7]
	v_mfma_f32_16x16x32_bf16 v[0:3], v[174:177], v[222:225], v[0:3]
	s_barrier
	s_add_i32 s51, s51, 2
	s_add_u32 s6, s6, 0x100
	s_addc_u32 s7, s7, 0
	s_add_u32 s8, s8, 0x100
	s_addc_u32 s50, s50, 0
	s_cmp_gt_u32 s51, 41
.LBB0_721:
	ds_read_b128 v[128:131], v208
	ds_read_b128 v[132:135], v208 offset:1024
	ds_read_b128 v[136:139], v208 offset:2048
	ds_read_b128 v[140:143], v208 offset:3072
	ds_read_b128 v[144:147], v209
	ds_read_b128 v[148:151], v209 offset:1024
	ds_read_b128 v[170:173], v209 offset:2048
	ds_read_b128 v[174:177], v209 offset:3072
	s_add_u32 s24, s6, 0xfff50080
	s_addc_u32 s25, s7, -1
	s_cmp_eq_u32 s51, 40
	s_cselect_b32 s27, s21, s25
	s_cselect_b32 s26, s20, s24
	s_cselect_b32 s25, s23, s50
	s_cselect_b32 s24, s22, s8
	v_lshl_add_u64 v[226:227], s[6:7], 0, v[162:163]
	s_add_i32 m0, s31, 0xc000
	ds_read_b128 v[178:181], v210
	ds_read_b128 v[182:185], v210 offset:1024
	ds_read_b128 v[186:189], v210 offset:2048
	ds_read_b128 v[190:193], v210 offset:3072
	ds_read_b128 v[194:197], v210 offset:4096
	ds_read_b128 v[214:217], v210 offset:5120
	ds_read_b128 v[218:221], v210 offset:6144
	ds_read_b128 v[222:225], v210 offset:7168
	global_load_lds_dwordx4 v[226:227], off
	v_lshl_add_u64 v[226:227], s[6:7], 0, v[164:165]
	s_add_i32 m0, s31, 0xe000
	s_nop 0
	global_load_lds_dwordx4 v[226:227], off
	s_waitcnt vmcnt(8)
	s_waitcnt lgkmcnt(0)
	s_barrier
	s_waitcnt lgkmcnt(0)
	v_mfma_f32_16x16x32_bf16 v[124:127], v[128:131], v[178:181], v[124:127]
	v_mfma_f32_16x16x32_bf16 v[120:123], v[136:139], v[178:181], v[120:123]
	v_mfma_f32_16x16x32_bf16 v[108:111], v[128:131], v[186:189], v[108:111]
	v_mfma_f32_16x16x32_bf16 v[104:107], v[136:139], v[186:189], v[104:107]
	v_mfma_f32_16x16x32_bf16 v[92:95], v[128:131], v[194:197], v[92:95]
	v_mfma_f32_16x16x32_bf16 v[88:91], v[136:139], v[194:197], v[88:91]
	v_mfma_f32_16x16x32_bf16 v[76:79], v[128:131], v[218:221], v[76:79]
	v_mfma_f32_16x16x32_bf16 v[72:75], v[136:139], v[218:221], v[72:75]
	v_mfma_f32_16x16x32_bf16 v[124:127], v[132:135], v[182:185], v[124:127]
	v_mfma_f32_16x16x32_bf16 v[120:123], v[140:143], v[182:185], v[120:123]
	v_mfma_f32_16x16x32_bf16 v[108:111], v[132:135], v[190:193], v[108:111]
	v_mfma_f32_16x16x32_bf16 v[104:107], v[140:143], v[190:193], v[104:107]
	v_mfma_f32_16x16x32_bf16 v[92:95], v[132:135], v[214:217], v[92:95]
	v_mfma_f32_16x16x32_bf16 v[88:91], v[140:143], v[214:217], v[88:91]
	v_mfma_f32_16x16x32_bf16 v[76:79], v[132:135], v[222:225], v[76:79]
	v_mfma_f32_16x16x32_bf16 v[72:75], v[140:143], v[222:225], v[72:75]
	v_mfma_f32_16x16x32_bf16 v[116:119], v[144:147], v[178:181], v[116:119]
	v_mfma_f32_16x16x32_bf16 v[112:115], v[170:173], v[178:181], v[112:115]
	v_mfma_f32_16x16x32_bf16 v[100:103], v[144:147], v[186:189], v[100:103]
	v_mfma_f32_16x16x32_bf16 v[96:99], v[170:173], v[186:189], v[96:99]
	v_mfma_f32_16x16x32_bf16 v[84:87], v[144:147], v[194:197], v[84:87]
	v_mfma_f32_16x16x32_bf16 v[80:83], v[170:173], v[194:197], v[80:83]
	v_mfma_f32_16x16x32_bf16 v[68:71], v[144:147], v[218:221], v[68:71]
	v_mfma_f32_16x16x32_bf16 v[64:67], v[170:173], v[218:221], v[64:67]
	v_mfma_f32_16x16x32_bf16 v[116:119], v[148:151], v[182:185], v[116:119]
	v_mfma_f32_16x16x32_bf16 v[112:115], v[174:177], v[182:185], v[112:115]
	v_mfma_f32_16x16x32_bf16 v[100:103], v[148:151], v[190:193], v[100:103]
	v_mfma_f32_16x16x32_bf16 v[96:99], v[174:177], v[190:193], v[96:99]
	v_mfma_f32_16x16x32_bf16 v[84:87], v[148:151], v[214:217], v[84:87]
	v_mfma_f32_16x16x32_bf16 v[80:83], v[174:177], v[214:217], v[80:83]
	v_mfma_f32_16x16x32_bf16 v[68:71], v[148:151], v[222:225], v[68:71]
	v_mfma_f32_16x16x32_bf16 v[64:67], v[174:177], v[222:225], v[64:67]
	s_barrier
	s_add_i32 s52, s42, s30
	v_lshl_add_u64 v[226:227], s[24:25], 0, v[154:155]
	s_mov_b32 m0, s52
	ds_read_b128 v[178:181], v210 offset:16384
	ds_read_b128 v[182:185], v210 offset:17408
	ds_read_b128 v[186:189], v210 offset:18432
	ds_read_b128 v[190:193], v210 offset:19456
	ds_read_b128 v[194:197], v210 offset:20480
	ds_read_b128 v[214:217], v210 offset:21504
	ds_read_b128 v[218:221], v210 offset:22528
	ds_read_b128 v[222:225], v210 offset:23552
	global_load_lds_dwordx4 v[226:227], off
	s_add_i32 m0, s52, 0x2000
	s_add_u32 s52, s24, 0xb0000
	v_lshl_add_u64 v[228:229], s[24:25], 0, v[158:159]
	s_addc_u32 s53, s25, 0
	s_add_i32 s54, s43, s30
	global_load_lds_dwordx4 v[228:229], off
	v_lshl_add_u64 v[230:231], s[52:53], 0, v[154:155]
	s_mov_b32 m0, s54
	v_lshl_add_u64 v[232:233], s[26:27], 0, v[156:157]
	global_load_lds_dwordx4 v[230:231], off
	v_lshl_add_u64 v[230:231], s[52:53], 0, v[158:159]
	s_add_i32 m0, s54, 0x2000
	s_nop 0
	global_load_lds_dwordx4 v[230:231], off
	v_lshl_add_u64 v[230:231], s[26:27], 0, v[152:153]
	s_mov_b32 m0, s31
	s_nop 0
	global_load_lds_dwordx4 v[230:231], off
	s_mov_b32 m0, s33
	s_nop 0
	global_load_lds_dwordx4 v[232:233], off
	s_waitcnt vmcnt(8)
	s_waitcnt lgkmcnt(0)
	s_barrier
	s_waitcnt lgkmcnt(0)
	v_mfma_f32_16x16x32_bf16 v[60:63], v[128:131], v[178:181], v[60:63]
	v_mfma_f32_16x16x32_bf16 v[56:59], v[136:139], v[178:181], v[56:59]
	v_mfma_f32_16x16x32_bf16 v[44:47], v[128:131], v[186:189], v[44:47]
	v_mfma_f32_16x16x32_bf16 v[40:43], v[136:139], v[186:189], v[40:43]
	v_mfma_f32_16x16x32_bf16 v[28:31], v[128:131], v[194:197], v[28:31]
	v_mfma_f32_16x16x32_bf16 v[24:27], v[136:139], v[194:197], v[24:27]
	v_mfma_f32_16x16x32_bf16 v[12:15], v[128:131], v[218:221], v[12:15]
	v_mfma_f32_16x16x32_bf16 v[8:11], v[136:139], v[218:221], v[8:11]
	v_mfma_f32_16x16x32_bf16 v[60:63], v[132:135], v[182:185], v[60:63]
	v_mfma_f32_16x16x32_bf16 v[56:59], v[140:143], v[182:185], v[56:59]
	v_mfma_f32_16x16x32_bf16 v[44:47], v[132:135], v[190:193], v[44:47]
	v_mfma_f32_16x16x32_bf16 v[40:43], v[140:143], v[190:193], v[40:43]
	v_mfma_f32_16x16x32_bf16 v[28:31], v[132:135], v[214:217], v[28:31]
	v_mfma_f32_16x16x32_bf16 v[24:27], v[140:143], v[214:217], v[24:27]
	v_mfma_f32_16x16x32_bf16 v[12:15], v[132:135], v[222:225], v[12:15]
	v_mfma_f32_16x16x32_bf16 v[8:11], v[140:143], v[222:225], v[8:11]
	v_mfma_f32_16x16x32_bf16 v[52:55], v[144:147], v[178:181], v[52:55]
	v_mfma_f32_16x16x32_bf16 v[48:51], v[170:173], v[178:181], v[48:51]
	v_mfma_f32_16x16x32_bf16 v[36:39], v[144:147], v[186:189], v[36:39]
	v_mfma_f32_16x16x32_bf16 v[32:35], v[170:173], v[186:189], v[32:35]
	v_mfma_f32_16x16x32_bf16 v[20:23], v[144:147], v[194:197], v[20:23]
	v_mfma_f32_16x16x32_bf16 v[16:19], v[170:173], v[194:197], v[16:19]
	v_mfma_f32_16x16x32_bf16 v[4:7], v[144:147], v[218:221], v[4:7]
	v_mfma_f32_16x16x32_bf16 v[0:3], v[170:173], v[218:221], v[0:3]
	v_mfma_f32_16x16x32_bf16 v[52:55], v[148:151], v[182:185], v[52:55]
	v_mfma_f32_16x16x32_bf16 v[48:51], v[174:177], v[182:185], v[48:51]
	v_mfma_f32_16x16x32_bf16 v[36:39], v[148:151], v[190:193], v[36:39]
	v_mfma_f32_16x16x32_bf16 v[32:35], v[174:177], v[190:193], v[32:35]
	v_mfma_f32_16x16x32_bf16 v[20:23], v[148:151], v[214:217], v[20:23]
	v_mfma_f32_16x16x32_bf16 v[16:19], v[174:177], v[214:217], v[16:19]
	v_mfma_f32_16x16x32_bf16 v[4:7], v[148:151], v[222:225], v[4:7]
	v_mfma_f32_16x16x32_bf16 v[0:3], v[174:177], v[222:225], v[0:3]
	s_barrier
	s_add_i32 s52, 0, 0x18000
	s_add_i32 s53, 0, 0x1c000
	v_add_u32_e32 v140, s52, v199
	v_add_u32_e32 v174, s53, v199
	ds_read_b128 v[128:131], v140
	ds_read_b128 v[132:135], v140 offset:1024
	ds_read_b128 v[136:139], v140 offset:2048
	ds_read_b128 v[140:143], v140 offset:3072
	ds_read_b128 v[144:147], v174
	ds_read_b128 v[148:151], v174 offset:1024
	ds_read_b128 v[170:173], v174 offset:2048
	ds_read_b128 v[174:177], v174 offset:3072
	s_add_u32 s26, s26, 0xb0000
	s_addc_u32 s27, s27, 0
	s_mov_b32 m0, s34
	v_lshl_add_u64 v[234:235], s[26:27], 0, v[152:153]
	ds_read_b128 v[178:181], v210 offset:32768
	ds_read_b128 v[182:185], v210 offset:33792
	ds_read_b128 v[186:189], v210 offset:34816
	ds_read_b128 v[190:193], v210 offset:35840
	ds_read_b128 v[194:197], v210 offset:36864
	ds_read_b128 v[214:217], v210 offset:37888
	ds_read_b128 v[218:221], v210 offset:38912
	ds_read_b128 v[222:225], v210 offset:39936
	global_load_lds_dwordx4 v[234:235], off
	v_lshl_add_u64 v[234:235], s[26:27], 0, v[156:157]
	s_mov_b32 m0, s35
	s_nop 0
	global_load_lds_dwordx4 v[234:235], off
	s_waitcnt vmcnt(8)
	s_waitcnt lgkmcnt(0)
	s_barrier
	s_waitcnt lgkmcnt(0)
	v_mfma_f32_16x16x32_bf16 v[124:127], v[128:131], v[178:181], v[124:127]
	v_mfma_f32_16x16x32_bf16 v[120:123], v[136:139], v[178:181], v[120:123]
	v_mfma_f32_16x16x32_bf16 v[108:111], v[128:131], v[186:189], v[108:111]
	v_mfma_f32_16x16x32_bf16 v[104:107], v[136:139], v[186:189], v[104:107]
	v_mfma_f32_16x16x32_bf16 v[92:95], v[128:131], v[194:197], v[92:95]
	v_mfma_f32_16x16x32_bf16 v[88:91], v[136:139], v[194:197], v[88:91]
	v_mfma_f32_16x16x32_bf16 v[76:79], v[128:131], v[218:221], v[76:79]
	v_mfma_f32_16x16x32_bf16 v[72:75], v[136:139], v[218:221], v[72:75]
	v_mfma_f32_16x16x32_bf16 v[124:127], v[132:135], v[182:185], v[124:127]
	v_mfma_f32_16x16x32_bf16 v[120:123], v[140:143], v[182:185], v[120:123]
	v_mfma_f32_16x16x32_bf16 v[108:111], v[132:135], v[190:193], v[108:111]
	v_mfma_f32_16x16x32_bf16 v[104:107], v[140:143], v[190:193], v[104:107]
	v_mfma_f32_16x16x32_bf16 v[92:95], v[132:135], v[214:217], v[92:95]
	v_mfma_f32_16x16x32_bf16 v[88:91], v[140:143], v[214:217], v[88:91]
	v_mfma_f32_16x16x32_bf16 v[76:79], v[132:135], v[222:225], v[76:79]
	v_mfma_f32_16x16x32_bf16 v[72:75], v[140:143], v[222:225], v[72:75]
	v_mfma_f32_16x16x32_bf16 v[116:119], v[144:147], v[178:181], v[116:119]
	v_mfma_f32_16x16x32_bf16 v[112:115], v[170:173], v[178:181], v[112:115]
	v_mfma_f32_16x16x32_bf16 v[100:103], v[144:147], v[186:189], v[100:103]
	v_mfma_f32_16x16x32_bf16 v[96:99], v[170:173], v[186:189], v[96:99]
	v_mfma_f32_16x16x32_bf16 v[84:87], v[144:147], v[194:197], v[84:87]
	v_mfma_f32_16x16x32_bf16 v[80:83], v[170:173], v[194:197], v[80:83]
	v_mfma_f32_16x16x32_bf16 v[68:71], v[144:147], v[218:221], v[68:71]
	v_mfma_f32_16x16x32_bf16 v[64:67], v[170:173], v[218:221], v[64:67]
	v_mfma_f32_16x16x32_bf16 v[116:119], v[148:151], v[182:185], v[116:119]
	v_mfma_f32_16x16x32_bf16 v[112:115], v[174:177], v[182:185], v[112:115]
	v_mfma_f32_16x16x32_bf16 v[100:103], v[148:151], v[190:193], v[100:103]
	v_mfma_f32_16x16x32_bf16 v[96:99], v[174:177], v[190:193], v[96:99]
	v_mfma_f32_16x16x32_bf16 v[84:87], v[148:151], v[214:217], v[84:87]
	v_mfma_f32_16x16x32_bf16 v[80:83], v[174:177], v[214:217], v[80:83]
	v_mfma_f32_16x16x32_bf16 v[68:71], v[148:151], v[222:225], v[68:71]
	v_mfma_f32_16x16x32_bf16 v[64:67], v[174:177], v[222:225], v[64:67]
	s_barrier
; #define PG8_WAIT_V(n) asm volatile("s_waitcnt vmcnt(" #n ")" ::: "memory")
; #define PG8_BAR __builtin_amdgcn_s_barrier()
; template <class Epi, class Sched, bool ALIGN_EPI, bool CONVA>
; DI void gemm_phase(LAS unsigned char* lds, const Gemm g, const Sched& S, const Epi& E) {
;     ...
;         for (int t = 0; t < nt; t += 2) {
;             const bool last = (t == nt - 2);
;             const char* a1 = cA + (size_t)(t + 1) * kstep;
;             const char* a2 = last ? nA : cA + (size_t)(t + 2) * kstep; const char* b2 = last ? nB : cB + (size_t)(t + 2) * kstep;
;             const char* a3 = a2 + kstep; const char* b3 = b2 + kstep;
;             PG8_KBODY(PG8_WAIT_V(8));
;         }
;     ...
;         if constexpr (ALIGN_EPI) { if (wr == 0) PG8_BAR; }
	s_add_i32 s26, s52, s30
	v_lshl_add_u64 v[226:227], v[226:227], 0, s[16:17]
	s_mov_b32 m0, s26
	ds_read_b128 v[178:181], v210 offset:49152
	ds_read_b128 v[182:185], v210 offset:50176
	ds_read_b128 v[186:189], v210 offset:51200
	ds_read_b128 v[190:193], v210 offset:52224
	ds_read_b128 v[194:197], v210 offset:53248
	ds_read_b128 v[214:217], v210 offset:54272
	ds_read_b128 v[218:221], v210 offset:55296
	ds_read_b128 v[222:225], v210 offset:56320
	global_load_lds_dwordx4 v[226:227], off
	s_add_i32 m0, s26, 0x2000
	s_add_u32 s24, s24, 0xb0080
	v_lshl_add_u64 v[226:227], v[228:229], 0, s[16:17]
	s_addc_u32 s25, s25, 0
	s_add_i32 s26, s53, s30
	global_load_lds_dwordx4 v[226:227], off
	v_lshl_add_u64 v[226:227], s[24:25], 0, v[154:155]
	s_mov_b32 m0, s26
	s_nop 0
	global_load_lds_dwordx4 v[226:227], off
	v_lshl_add_u64 v[226:227], s[24:25], 0, v[158:159]
	s_add_i32 m0, s26, 0x2000
	s_nop 0
	global_load_lds_dwordx4 v[226:227], off
	v_lshl_add_u64 v[226:227], v[230:231], 0, s[16:17]
	s_mov_b32 m0, s37
	s_nop 0
	global_load_lds_dwordx4 v[226:227], off
	v_lshl_add_u64 v[226:227], v[232:233], 0, s[16:17]
	s_mov_b32 m0, s38
	s_nop 0
	global_load_lds_dwordx4 v[226:227], off
	s_waitcnt vmcnt(8)
	s_waitcnt lgkmcnt(0)
	s_barrier
	s_waitcnt lgkmcnt(0)
	v_mfma_f32_16x16x32_bf16 v[60:63], v[128:131], v[178:181], v[60:63]
	v_mfma_f32_16x16x32_bf16 v[56:59], v[136:139], v[178:181], v[56:59]
	v_mfma_f32_16x16x32_bf16 v[44:47], v[128:131], v[186:189], v[44:47]
	v_mfma_f32_16x16x32_bf16 v[40:43], v[136:139], v[186:189], v[40:43]
	v_mfma_f32_16x16x32_bf16 v[28:31], v[128:131], v[194:197], v[28:31]
	v_mfma_f32_16x16x32_bf16 v[24:27], v[136:139], v[194:197], v[24:27]
	v_mfma_f32_16x16x32_bf16 v[12:15], v[128:131], v[218:221], v[12:15]
	v_mfma_f32_16x16x32_bf16 v[8:11], v[136:139], v[218:221], v[8:11]
	v_mfma_f32_16x16x32_bf16 v[60:63], v[132:135], v[182:185], v[60:63]
	v_mfma_f32_16x16x32_bf16 v[56:59], v[140:143], v[182:185], v[56:59]
	v_mfma_f32_16x16x32_bf16 v[44:47], v[132:135], v[190:193], v[44:47]
	v_mfma_f32_16x16x32_bf16 v[40:43], v[140:143], v[190:193], v[40:43]
	v_mfma_f32_16x16x32_bf16 v[28:31], v[132:135], v[214:217], v[28:31]
	v_mfma_f32_16x16x32_bf16 v[24:27], v[140:143], v[214:217], v[24:27]
	v_mfma_f32_16x16x32_bf16 v[12:15], v[132:135], v[222:225], v[12:15]
	v_mfma_f32_16x16x32_bf16 v[8:11], v[140:143], v[222:225], v[8:11]
	v_mfma_f32_16x16x32_bf16 v[52:55], v[144:147], v[178:181], v[52:55]
	v_mfma_f32_16x16x32_bf16 v[48:51], v[170:173], v[178:181], v[48:51]
	v_mfma_f32_16x16x32_bf16 v[36:39], v[144:147], v[186:189], v[36:39]
	v_mfma_f32_16x16x32_bf16 v[32:35], v[170:173], v[186:189], v[32:35]
	v_mfma_f32_16x16x32_bf16 v[20:23], v[144:147], v[194:197], v[20:23]
	v_mfma_f32_16x16x32_bf16 v[16:19], v[170:173], v[194:197], v[16:19]
	v_mfma_f32_16x16x32_bf16 v[4:7], v[144:147], v[218:221], v[4:7]
	v_mfma_f32_16x16x32_bf16 v[0:3], v[170:173], v[218:221], v[0:3]
	v_mfma_f32_16x16x32_bf16 v[52:55], v[148:151], v[182:185], v[52:55]
	v_mfma_f32_16x16x32_bf16 v[48:51], v[174:177], v[182:185], v[48:51]
	v_mfma_f32_16x16x32_bf16 v[36:39], v[148:151], v[190:193], v[36:39]
	v_mfma_f32_16x16x32_bf16 v[32:35], v[174:177], v[190:193], v[32:35]
	v_mfma_f32_16x16x32_bf16 v[20:23], v[148:151], v[214:217], v[20:23]
	v_mfma_f32_16x16x32_bf16 v[16:19], v[174:177], v[214:217], v[16:19]
	v_mfma_f32_16x16x32_bf16 v[4:7], v[148:151], v[222:225], v[4:7]
	v_mfma_f32_16x16x32_bf16 v[0:3], v[174:177], v[222:225], v[0:3]
	s_barrier
	s_add_i32 s51, s51, 2
	s_add_u32 s6, s6, 0x100
	s_addc_u32 s7, s7, 0
	s_add_u32 s8, s8, 0x100
	s_addc_u32 s50, s50, 0
	s_cmp_gt_u32 s51, 41
	s_cbranch_scc0 .LBB0_721
	s_and_b64 vcc, exec, s[18:19]
	s_cbranch_vccz .LBB0_724
	s_barrier
